# K-loops: the s_setprio 0 / s_setprio 1 pair in the middle of each 32-MFMA block deleted (one raise per block)
# speedup vs baseline: 1.0075x; 1.0075x over previous
; #define PG8_STAGE(bufoff, gbase, voff) do { _Pragma("unroll") for (int _i = 0; _i < 2; ++_i) \
;         __builtin_amdgcn_global_load_lds((const unsigned*)((const char*)(gbase) + (voff)[_i]), (PG8_LAS unsigned*)(lds + (bufoff) + ldsw + _i * 8192), 16, 0, 0); } while (0)
; #define PG8_STAGEA(bufoff, gbase, voff) do { _Pragma("unroll") for (int _i = 0; _i < 2; ++_i) \
;         __builtin_amdgcn_global_load_lds((const unsigned*)((const char*)(gbase) + (voff)[_i]), (PG8_LAS unsigned*)(lds + (bufoff) + ldsw + _i * 8192), 16, 0, A_AUX); } while (0)
; #define PG8_LDA(dst, b, h) do { _Pragma("unroll") for (int m = 0; m < 4; ++m) _Pragma("unroll") for (int k = 0; k < 2; ++k) dst[m][k] = *(const PG8_LAS bf16x8*)(lds + PG8_SA(b, h) + aoff + m * 2048 + k * 1024); } while (0)
; #define PG8_LDB(dst, b, h) do { _Pragma("unroll") for (int n = 0; n < 2; ++n) _Pragma("unroll") for (int k = 0; k < 2; ++k) dst[n][k] = *(const PG8_LAS bf16x8*)(lds + PG8_SB(b, h) + boff + n * 2048 + k * 1024); } while (0)
; #define PG8_WAIT_V(n) asm volatile("s_waitcnt vmcnt(" #n ")" ::: "memory")
; #define PG8_WAIT_L(n) asm volatile("s_waitcnt lgkmcnt(" #n ")" ::: "memory")
; #define PG8_BAR __builtin_amdgcn_s_barrier()
;     ...
;         const bool has_next = S.next(ui + 1, nxt);
;         const char* nA = has_next ? (const char*)g.A + (size_t)nxt.pm * tstep : cA; const char* nB = has_next ? (const char*)g.Bt + (size_t)nxt.pn * tstep : cB;
;         for (int t = 0; t < nt; t += 2) {
;             const bool last = (t == nt - 2);
;             const char* a1 = cA + (size_t)(t + 1) * kstep;
;             const char* a2 = last ? nA : cA + (size_t)(t + 2) * kstep; const char* b2 = last ? nB : cB + (size_t)(t + 2) * kstep;
;             const char* a3 = a2 + kstep; const char* b3 = b2 + kstep;
;             if (last && has_next) S.a_ready(nxt);
;             if constexpr (SP2) {
;             PG8_LDB(B0, 0, 0); PG8_LDB(B1, 0, 1); PG8_SCHED; PG8_LDA(At, 0, 0); PG8_STAGEA(PG8_SA(1, 1), a1 + hstep, voffA);
;             PG8_WAIT_V(8); PG8_WAIT_L(0); PG8_BAR; PG8_MMA(0, 0, At, B0); PG8_MMA(0, 1, At, B1); PG8_BAR; PG8_SCHED;
;             PG8_LDA(At, 0, 1); PG8_STAGE(PG8_SB(0, 0), b2, voffB); PG8_STAGE(PG8_SB(0, 1), b2 + hstep, voffB); PG8_STAGEA(PG8_SA(0, 0), a2, voffA);
;             PG8_WAIT_V(8); PG8_WAIT_L(0); PG8_BAR; PG8_MMA(1, 0, At, B0); PG8_MMA(1, 1, At, B1); PG8_BAR; PG8_SCHED;
.LBB0_185:
	s_ashr_i32 s53, s52, 31
	s_lshl_b64 s[16:17], s[52:53], 19
	s_add_u32 s54, s97, s16
	s_addc_u32 s55, s29, s17
	s_and_b64 s[16:17], s[38:39], exec
	s_cselect_b32 s16, s55, s1
	s_cselect_b32 s17, s54, s0
	s_ashr_i32 s51, s50, 31
	s_lshl_b64 s[42:43], s[50:51], 19
	v_readlane_b32 s51, v246, 9
	s_add_u32 s56, s51, s42
	v_readlane_b32 s42, v246, 6
	s_addc_u32 s57, s42, s43
	s_and_b64 s[42:43], s[38:39], exec
	s_cselect_b32 s51, s57, s41
	s_cselect_b32 s53, s56, s40
	s_add_u32 s0, s0, 0x40080
	s_addc_u32 s1, s1, 0
	s_add_u32 s58, s40, 0x100
	s_addc_u32 s59, s41, 0
	s_mov_b32 vcc_lo, -2
	s_add_u32 s40, s0, 0xfffc0080
	s_addc_u32 s41, s1, -1
	s_add_i32 s70, 0, 0x10000
	s_cmp_eq_u32 vcc_lo, 12
	s_cselect_b32 s43, s16, s41
	s_cselect_b32 s42, s17, s40
	s_cselect_b32 s41, s51, s59
	s_cselect_b32 s40, s53, s58
	s_add_i32 vcc_hi, 0, 0x14000
	v_add_u32_e32 v94, s70, v201
	v_add_u32_e32 v158, vcc_hi, v201
	ds_read_b128 v[74:77], v94
	ds_read_b128 v[78:81], v94 offset:1024
	ds_read_b128 v[90:93], v94 offset:2048
	ds_read_b128 v[94:97], v94 offset:3072
	ds_read_b128 v[146:149], v158
	ds_read_b128 v[150:153], v158 offset:1024
	ds_read_b128 v[154:157], v158 offset:2048
	ds_read_b128 v[158:161], v158 offset:3072
	v_lshl_add_u64 v[190:191], s[0:1], 0, v[182:183]
	s_add_i32 m0, s61, 0xc000
	ds_read_b128 v[186:189], v203
	ds_read_b128 v[208:211], v203 offset:1024
	ds_read_b128 v[212:215], v203 offset:2048
	ds_read_b128 v[216:219], v203 offset:3072
	ds_read_b128 v[220:223], v203 offset:4096
	ds_read_b128 v[224:227], v203 offset:5120
	ds_read_b128 v[228:231], v203 offset:6144
	ds_read_b128 v[232:235], v203 offset:7168
	global_load_lds_dwordx4 v[190:191], off
	v_lshl_add_u64 v[190:191], s[0:1], 0, v[184:185]
	s_add_i32 m0, s61, 0xe000
	s_nop 0
	global_load_lds_dwordx4 v[190:191], off
	s_waitcnt vmcnt(8)
	s_waitcnt lgkmcnt(0)
	s_barrier
	s_setprio 1
	s_waitcnt lgkmcnt(0)
	v_mfma_f32_16x16x32_bf16 v[142:145], v[74:77], v[186:189], 0
	v_mfma_f32_16x16x32_bf16 v[138:141], v[90:93], v[186:189], 0
	v_mfma_f32_16x16x32_bf16 v[126:129], v[74:77], v[212:215], 0
	v_mfma_f32_16x16x32_bf16 v[122:125], v[90:93], v[212:215], 0
	v_mfma_f32_16x16x32_bf16 v[110:113], v[74:77], v[220:223], 0
	v_mfma_f32_16x16x32_bf16 v[106:109], v[90:93], v[220:223], 0
	v_mfma_f32_16x16x32_bf16 v[86:89], v[74:77], v[228:231], 0
	v_mfma_f32_16x16x32_bf16 v[82:85], v[90:93], v[228:231], 0
	v_mfma_f32_16x16x32_bf16 v[142:145], v[78:81], v[208:211], v[142:145]
	v_mfma_f32_16x16x32_bf16 v[138:141], v[94:97], v[208:211], v[138:141]
	v_mfma_f32_16x16x32_bf16 v[126:129], v[78:81], v[216:219], v[126:129]
	v_mfma_f32_16x16x32_bf16 v[122:125], v[94:97], v[216:219], v[122:125]
	v_mfma_f32_16x16x32_bf16 v[110:113], v[78:81], v[224:227], v[110:113]
	v_mfma_f32_16x16x32_bf16 v[106:109], v[94:97], v[224:227], v[106:109]
	v_mfma_f32_16x16x32_bf16 v[86:89], v[78:81], v[232:235], v[86:89]
	v_mfma_f32_16x16x32_bf16 v[82:85], v[94:97], v[232:235], v[82:85]
	v_mfma_f32_16x16x32_bf16 v[134:137], v[146:149], v[186:189], 0
	v_mfma_f32_16x16x32_bf16 v[130:133], v[154:157], v[186:189], 0
	v_mfma_f32_16x16x32_bf16 v[118:121], v[146:149], v[212:215], 0
	v_mfma_f32_16x16x32_bf16 v[114:117], v[154:157], v[212:215], 0
	v_mfma_f32_16x16x32_bf16 v[102:105], v[146:149], v[220:223], 0
	v_mfma_f32_16x16x32_bf16 v[98:101], v[154:157], v[220:223], 0
	v_mfma_f32_16x16x32_bf16 v[70:73], v[146:149], v[228:231], 0
	v_mfma_f32_16x16x32_bf16 v[66:69], v[154:157], v[228:231], 0
	v_mfma_f32_16x16x32_bf16 v[134:137], v[150:153], v[208:211], v[134:137]
	v_mfma_f32_16x16x32_bf16 v[130:133], v[158:161], v[208:211], v[130:133]
	v_mfma_f32_16x16x32_bf16 v[118:121], v[150:153], v[216:219], v[118:121]
	v_mfma_f32_16x16x32_bf16 v[114:117], v[158:161], v[216:219], v[114:117]
	v_mfma_f32_16x16x32_bf16 v[102:105], v[150:153], v[224:227], v[102:105]
	v_mfma_f32_16x16x32_bf16 v[98:101], v[158:161], v[224:227], v[98:101]
	v_mfma_f32_16x16x32_bf16 v[70:73], v[150:153], v[232:235], v[70:73]
	v_mfma_f32_16x16x32_bf16 v[66:69], v[158:161], v[232:235], v[66:69]
	s_setprio 0
	s_barrier
	s_add_i32 s70, s70, s60
	v_lshl_add_u64 v[190:191], s[40:41], 0, v[0:1]
	s_mov_b32 m0, s70
	ds_read_b128 v[186:189], v203 offset:16384
	ds_read_b128 v[208:211], v203 offset:17408
	ds_read_b128 v[212:215], v203 offset:18432
	ds_read_b128 v[216:219], v203 offset:19456
	ds_read_b128 v[220:223], v203 offset:20480
	ds_read_b128 v[224:227], v203 offset:21504
	ds_read_b128 v[228:231], v203 offset:22528
	ds_read_b128 v[232:235], v203 offset:23552
	global_load_lds_dwordx4 v[190:191], off
	s_add_i32 m0, s70, 0x2000
	s_add_u32 s70, s40, 0x40000
	v_lshl_add_u64 v[236:237], s[40:41], 0, v[174:175]
	s_addc_u32 s71, s41, 0
	s_add_i32 vcc_hi, vcc_hi, s60
	global_load_lds_dwordx4 v[236:237], off
	v_lshl_add_u64 v[238:239], s[70:71], 0, v[0:1]
	s_mov_b32 m0, vcc_hi
	v_lshl_add_u64 v[240:241], s[42:43], 0, v[176:177]
	global_load_lds_dwordx4 v[238:239], off
	v_lshl_add_u64 v[238:239], s[70:71], 0, v[174:175]
	s_add_i32 m0, vcc_hi, 0x2000
	s_nop 0
	global_load_lds_dwordx4 v[238:239], off
	v_lshl_add_u64 v[238:239], s[42:43], 0, v[178:179]
	s_mov_b32 m0, s61
	s_nop 0
	global_load_lds_dwordx4 v[238:239], off
	s_mov_b32 m0, s62
	s_nop 0
	global_load_lds_dwordx4 v[240:241], off
	s_waitcnt vmcnt(8)
	s_waitcnt lgkmcnt(0)
	s_barrier
; #define PG8_STAGEA(bufoff, gbase, voff) do { _Pragma("unroll") for (int _i = 0; _i < 2; ++_i) \
;         __builtin_amdgcn_global_load_lds((const unsigned*)((const char*)(gbase) + (voff)[_i]), (PG8_LAS unsigned*)(lds + (bufoff) + ldsw + _i * 8192), 16, 0, A_AUX); } while (0)
; #define PG8_LDA(dst, b, h) do { _Pragma("unroll") for (int m = 0; m < 4; ++m) _Pragma("unroll") for (int k = 0; k < 2; ++k) dst[m][k] = *(const PG8_LAS bf16x8*)(lds + PG8_SA(b, h) + aoff + m * 2048 + k * 1024); } while (0)
; #define PG8_LDB(dst, b, h) do { _Pragma("unroll") for (int n = 0; n < 2; ++n) _Pragma("unroll") for (int k = 0; k < 2; ++k) dst[n][k] = *(const PG8_LAS bf16x8*)(lds + PG8_SB(b, h) + boff + n * 2048 + k * 1024); } while (0)
; #define PG8_MMA(ai, bj, At, Bt) do { __builtin_amdgcn_s_setprio(1); _Pragma("unroll") for (int m = 0; m < 4; ++m) _Pragma("unroll") for (int n = 0; n < 2; ++n) _Pragma("unroll") for (int k = 0; k < 2; ++k) \
;         acc[ai][bj][m][n] = __builtin_amdgcn_mfma_f32_16x16x32_bf16(Bt[n][k], At[m][k], acc[ai][bj][m][n], 0, 0, 0); __builtin_amdgcn_s_setprio(0); } while (0)
; #define PG8_WAIT_V(n) asm volatile("s_waitcnt vmcnt(" #n ")" ::: "memory")
; #define PG8_WAIT_L(n) asm volatile("s_waitcnt lgkmcnt(" #n ")" ::: "memory")
; #define PG8_BAR __builtin_amdgcn_s_barrier()
; #define PG8_SCHED __builtin_amdgcn_sched_barrier(0)
;     ...
;             PG8_WAIT_V(8); PG8_WAIT_L(0); PG8_BAR; PG8_MMA(1, 0, At, B0); PG8_MMA(1, 1, At, B1); PG8_BAR; PG8_SCHED;
;             PG8_LDB(B0, 1, 0); PG8_LDB(B1, 1, 1); PG8_SCHED; PG8_LDA(At, 1, 0); PG8_STAGEA(PG8_SA(0, 1), a2 + hstep, voffA);
;             PG8_WAIT_V(8); PG8_WAIT_L(0); PG8_BAR; PG8_MMA(0, 0, At, B0); PG8_MMA(0, 1, At, B1); PG8_BAR; PG8_SCHED;
	s_setprio 1
	s_waitcnt lgkmcnt(0)
	v_mfma_f32_16x16x32_bf16 v[62:65], v[74:77], v[186:189], 0
	v_mfma_f32_16x16x32_bf16 v[58:61], v[90:93], v[186:189], 0
	v_mfma_f32_16x16x32_bf16 v[46:49], v[74:77], v[212:215], 0
	v_mfma_f32_16x16x32_bf16 v[42:45], v[90:93], v[212:215], 0
	v_mfma_f32_16x16x32_bf16 v[30:33], v[74:77], v[220:223], 0
	v_mfma_f32_16x16x32_bf16 v[26:29], v[90:93], v[220:223], 0
	v_mfma_f32_16x16x32_bf16 v[14:17], v[74:77], v[228:231], 0
	v_mfma_f32_16x16x32_bf16 v[10:13], v[90:93], v[228:231], 0
	v_mfma_f32_16x16x32_bf16 v[62:65], v[78:81], v[208:211], v[62:65]
	v_mfma_f32_16x16x32_bf16 v[58:61], v[94:97], v[208:211], v[58:61]
	v_mfma_f32_16x16x32_bf16 v[46:49], v[78:81], v[216:219], v[46:49]
	v_mfma_f32_16x16x32_bf16 v[42:45], v[94:97], v[216:219], v[42:45]
	v_mfma_f32_16x16x32_bf16 v[30:33], v[78:81], v[224:227], v[30:33]
	v_mfma_f32_16x16x32_bf16 v[26:29], v[94:97], v[224:227], v[26:29]
	v_mfma_f32_16x16x32_bf16 v[14:17], v[78:81], v[232:235], v[14:17]
	v_mfma_f32_16x16x32_bf16 v[10:13], v[94:97], v[232:235], v[10:13]
	v_mfma_f32_16x16x32_bf16 v[54:57], v[146:149], v[186:189], 0
	v_mfma_f32_16x16x32_bf16 v[50:53], v[154:157], v[186:189], 0
	v_mfma_f32_16x16x32_bf16 v[38:41], v[146:149], v[212:215], 0
	v_mfma_f32_16x16x32_bf16 v[34:37], v[154:157], v[212:215], 0
	v_mfma_f32_16x16x32_bf16 v[22:25], v[146:149], v[220:223], 0
	v_mfma_f32_16x16x32_bf16 v[18:21], v[154:157], v[220:223], 0
	v_mfma_f32_16x16x32_bf16 v[6:9], v[146:149], v[228:231], 0
	v_mfma_f32_16x16x32_bf16 v[2:5], v[154:157], v[228:231], 0
	v_mfma_f32_16x16x32_bf16 v[54:57], v[150:153], v[208:211], v[54:57]
	v_mfma_f32_16x16x32_bf16 v[50:53], v[158:161], v[208:211], v[50:53]
	v_mfma_f32_16x16x32_bf16 v[38:41], v[150:153], v[216:219], v[38:41]
	v_mfma_f32_16x16x32_bf16 v[34:37], v[158:161], v[216:219], v[34:37]
	v_mfma_f32_16x16x32_bf16 v[22:25], v[150:153], v[224:227], v[22:25]
	v_mfma_f32_16x16x32_bf16 v[18:21], v[158:161], v[224:227], v[18:21]
	v_mfma_f32_16x16x32_bf16 v[6:9], v[150:153], v[232:235], v[6:9]
	v_mfma_f32_16x16x32_bf16 v[2:5], v[158:161], v[232:235], v[2:5]
	s_setprio 0
	s_barrier
	s_add_i32 s70, 0, 0x18000
	s_add_i32 s71, 0, 0x1c000
	v_add_u32_e32 v94, s70, v201
	v_add_u32_e32 v158, s71, v201
	ds_read_b128 v[74:77], v94
	ds_read_b128 v[78:81], v94 offset:1024
	ds_read_b128 v[90:93], v94 offset:2048
	ds_read_b128 v[94:97], v94 offset:3072
	ds_read_b128 v[146:149], v158
	ds_read_b128 v[150:153], v158 offset:1024
	ds_read_b128 v[154:157], v158 offset:2048
	ds_read_b128 v[158:161], v158 offset:3072
	s_add_u32 s42, s42, 0x40000
	s_addc_u32 s43, s43, 0
	s_mov_b32 m0, s63
	v_lshl_add_u64 v[242:243], s[42:43], 0, v[178:179]
	ds_read_b128 v[186:189], v203 offset:32768
	ds_read_b128 v[208:211], v203 offset:33792
	ds_read_b128 v[212:215], v203 offset:34816
	ds_read_b128 v[216:219], v203 offset:35840
	ds_read_b128 v[220:223], v203 offset:36864
	ds_read_b128 v[224:227], v203 offset:37888
	ds_read_b128 v[228:231], v203 offset:38912
	ds_read_b128 v[232:235], v203 offset:39936
	global_load_lds_dwordx4 v[242:243], off
	v_lshl_add_u64 v[242:243], s[42:43], 0, v[176:177]
	s_mov_b32 m0, s64
	s_nop 0
	global_load_lds_dwordx4 v[242:243], off
	s_waitcnt vmcnt(8)
	s_waitcnt lgkmcnt(0)
	s_barrier
	s_setprio 1
	s_waitcnt lgkmcnt(0)
	v_mfma_f32_16x16x32_bf16 v[142:145], v[74:77], v[186:189], v[142:145]
	v_mfma_f32_16x16x32_bf16 v[138:141], v[90:93], v[186:189], v[138:141]
	v_mfma_f32_16x16x32_bf16 v[126:129], v[74:77], v[212:215], v[126:129]
	v_mfma_f32_16x16x32_bf16 v[122:125], v[90:93], v[212:215], v[122:125]
	v_mfma_f32_16x16x32_bf16 v[110:113], v[74:77], v[220:223], v[110:113]
	v_mfma_f32_16x16x32_bf16 v[106:109], v[90:93], v[220:223], v[106:109]
	v_mfma_f32_16x16x32_bf16 v[86:89], v[74:77], v[228:231], v[86:89]
	v_mfma_f32_16x16x32_bf16 v[82:85], v[90:93], v[228:231], v[82:85]
	v_mfma_f32_16x16x32_bf16 v[142:145], v[78:81], v[208:211], v[142:145]
	v_mfma_f32_16x16x32_bf16 v[138:141], v[94:97], v[208:211], v[138:141]
	v_mfma_f32_16x16x32_bf16 v[126:129], v[78:81], v[216:219], v[126:129]
	v_mfma_f32_16x16x32_bf16 v[122:125], v[94:97], v[216:219], v[122:125]
	v_mfma_f32_16x16x32_bf16 v[110:113], v[78:81], v[224:227], v[110:113]
	v_mfma_f32_16x16x32_bf16 v[106:109], v[94:97], v[224:227], v[106:109]
	v_mfma_f32_16x16x32_bf16 v[86:89], v[78:81], v[232:235], v[86:89]
	v_mfma_f32_16x16x32_bf16 v[82:85], v[94:97], v[232:235], v[82:85]
	v_mfma_f32_16x16x32_bf16 v[134:137], v[146:149], v[186:189], v[134:137]
	v_mfma_f32_16x16x32_bf16 v[130:133], v[154:157], v[186:189], v[130:133]
	v_mfma_f32_16x16x32_bf16 v[118:121], v[146:149], v[212:215], v[118:121]
	v_mfma_f32_16x16x32_bf16 v[114:117], v[154:157], v[212:215], v[114:117]
	v_mfma_f32_16x16x32_bf16 v[102:105], v[146:149], v[220:223], v[102:105]
	v_mfma_f32_16x16x32_bf16 v[98:101], v[154:157], v[220:223], v[98:101]
	v_mfma_f32_16x16x32_bf16 v[70:73], v[146:149], v[228:231], v[70:73]
	v_mfma_f32_16x16x32_bf16 v[66:69], v[154:157], v[228:231], v[66:69]
	v_mfma_f32_16x16x32_bf16 v[134:137], v[150:153], v[208:211], v[134:137]
	v_mfma_f32_16x16x32_bf16 v[130:133], v[158:161], v[208:211], v[130:133]
	v_mfma_f32_16x16x32_bf16 v[118:121], v[150:153], v[216:219], v[118:121]
	v_mfma_f32_16x16x32_bf16 v[114:117], v[158:161], v[216:219], v[114:117]
	v_mfma_f32_16x16x32_bf16 v[102:105], v[150:153], v[224:227], v[102:105]
	v_mfma_f32_16x16x32_bf16 v[98:101], v[158:161], v[224:227], v[98:101]
	v_mfma_f32_16x16x32_bf16 v[70:73], v[150:153], v[232:235], v[70:73]
	v_mfma_f32_16x16x32_bf16 v[66:69], v[158:161], v[232:235], v[66:69]
	s_setprio 0
	s_barrier
; #define PG8_STAGE(bufoff, gbase, voff) do { _Pragma("unroll") for (int _i = 0; _i < 2; ++_i) \
;         __builtin_amdgcn_global_load_lds((const unsigned*)((const char*)(gbase) + (voff)[_i]), (PG8_LAS unsigned*)(lds + (bufoff) + ldsw + _i * 8192), 16, 0, 0); } while (0)
; #define PG8_STAGEA(bufoff, gbase, voff) do { _Pragma("unroll") for (int _i = 0; _i < 2; ++_i) \
;         __builtin_amdgcn_global_load_lds((const unsigned*)((const char*)(gbase) + (voff)[_i]), (PG8_LAS unsigned*)(lds + (bufoff) + ldsw + _i * 8192), 16, 0, A_AUX); } while (0)
; #define PG8_LDA(dst, b, h) do { _Pragma("unroll") for (int m = 0; m < 4; ++m) _Pragma("unroll") for (int k = 0; k < 2; ++k) dst[m][k] = *(const PG8_LAS bf16x8*)(lds + PG8_SA(b, h) + aoff + m * 2048 + k * 1024); } while (0)
; #define PG8_WAIT_V(n) asm volatile("s_waitcnt vmcnt(" #n ")" ::: "memory")
; #define PG8_BAR __builtin_amdgcn_s_barrier()
;     ...
;         for (int t = 0; t < nt; t += 2) {
;             const bool last = (t == nt - 2);
;             const char* a1 = cA + (size_t)(t + 1) * kstep;
;             const char* a2 = last ? nA : cA + (size_t)(t + 2) * kstep; const char* b2 = last ? nB : cB + (size_t)(t + 2) * kstep;
;             const char* a3 = a2 + kstep; const char* b3 = b2 + kstep;
;             if (last && has_next) S.a_ready(nxt);
;             if constexpr (SP2) {
;             PG8_LDB(B0, 0, 0); PG8_LDB(B1, 0, 1); PG8_SCHED; PG8_LDA(At, 0, 0); PG8_STAGEA(PG8_SA(1, 1), a1 + hstep, voffA);
;             PG8_WAIT_V(8); PG8_WAIT_L(0); PG8_BAR; PG8_MMA(0, 0, At, B0); PG8_MMA(0, 1, At, B1); PG8_BAR; PG8_SCHED;
;             PG8_LDA(At, 0, 1); PG8_STAGE(PG8_SB(0, 0), b2, voffB); PG8_STAGE(PG8_SB(0, 1), b2 + hstep, voffB); PG8_STAGEA(PG8_SA(0, 0), a2, voffA);
;             PG8_WAIT_V(8); PG8_WAIT_L(0); PG8_BAR; PG8_MMA(1, 0, At, B0); PG8_MMA(1, 1, At, B1); PG8_BAR; PG8_SCHED;
;             PG8_LDB(B0, 1, 0); PG8_LDB(B1, 1, 1); PG8_SCHED; PG8_LDA(At, 1, 0); PG8_STAGEA(PG8_SA(0, 1), a2 + hstep, voffA);
;             PG8_WAIT_V(8); PG8_WAIT_L(0); PG8_BAR; PG8_MMA(0, 0, At, B0); PG8_MMA(0, 1, At, B1); PG8_BAR; PG8_SCHED;
;             PG8_LDA(At, 1, 1); PG8_STAGE(PG8_SB(1, 0), b3, voffB); PG8_STAGE(PG8_SB(1, 1), b3 + hstep, voffB); PG8_STAGEA(PG8_SA(1, 0), a3, voffA);
;             PG8_WAIT_V(8); PG8_WAIT_L(0); PG8_BAR; PG8_MMA(1, 0, At, B0); PG8_MMA(1, 1, At, B1); PG8_BAR; PG8_SCHED;
	s_add_i32 s42, s70, s60
	v_lshl_add_u64 v[190:191], v[190:191], 0, s[8:9]
	s_mov_b32 m0, s42
	ds_read_b128 v[186:189], v203 offset:49152
	ds_read_b128 v[208:211], v203 offset:50176
	ds_read_b128 v[212:215], v203 offset:51200
	ds_read_b128 v[216:219], v203 offset:52224
	ds_read_b128 v[220:223], v203 offset:53248
	ds_read_b128 v[224:227], v203 offset:54272
	ds_read_b128 v[228:231], v203 offset:55296
	ds_read_b128 v[232:235], v203 offset:56320
	global_load_lds_dwordx4 v[190:191], off
	s_add_i32 m0, s42, 0x2000
	s_add_u32 s40, s40, 0x40080
	v_lshl_add_u64 v[190:191], v[236:237], 0, s[8:9]
	s_addc_u32 s41, s41, 0
	s_add_i32 s42, s71, s60
	global_load_lds_dwordx4 v[190:191], off
	v_lshl_add_u64 v[190:191], s[40:41], 0, v[0:1]
	s_mov_b32 m0, s42
	s_nop 0
	global_load_lds_dwordx4 v[190:191], off
	v_lshl_add_u64 v[190:191], s[40:41], 0, v[174:175]
	s_add_i32 m0, s42, 0x2000
	s_nop 0
	global_load_lds_dwordx4 v[190:191], off
	v_lshl_add_u64 v[190:191], v[238:239], 0, s[8:9]
	s_mov_b32 m0, s72
	s_nop 0
	global_load_lds_dwordx4 v[190:191], off
	v_lshl_add_u64 v[190:191], v[240:241], 0, s[8:9]
	s_mov_b32 m0, s73
	s_nop 0
	global_load_lds_dwordx4 v[190:191], off
	s_waitcnt vmcnt(8)
	s_waitcnt lgkmcnt(0)
	s_barrier
	s_setprio 1
	s_waitcnt lgkmcnt(0)
	v_mfma_f32_16x16x32_bf16 v[62:65], v[74:77], v[186:189], v[62:65]
	v_mfma_f32_16x16x32_bf16 v[58:61], v[90:93], v[186:189], v[58:61]
	v_mfma_f32_16x16x32_bf16 v[46:49], v[74:77], v[212:215], v[46:49]
	v_mfma_f32_16x16x32_bf16 v[42:45], v[90:93], v[212:215], v[42:45]
	v_mfma_f32_16x16x32_bf16 v[30:33], v[74:77], v[220:223], v[30:33]
	v_mfma_f32_16x16x32_bf16 v[26:29], v[90:93], v[220:223], v[26:29]
	v_mfma_f32_16x16x32_bf16 v[14:17], v[74:77], v[228:231], v[14:17]
	v_mfma_f32_16x16x32_bf16 v[10:13], v[90:93], v[228:231], v[10:13]
	v_mfma_f32_16x16x32_bf16 v[62:65], v[78:81], v[208:211], v[62:65]
	v_mfma_f32_16x16x32_bf16 v[58:61], v[94:97], v[208:211], v[58:61]
	v_mfma_f32_16x16x32_bf16 v[46:49], v[78:81], v[216:219], v[46:49]
	v_mfma_f32_16x16x32_bf16 v[42:45], v[94:97], v[216:219], v[42:45]
	v_mfma_f32_16x16x32_bf16 v[30:33], v[78:81], v[224:227], v[30:33]
	v_mfma_f32_16x16x32_bf16 v[26:29], v[94:97], v[224:227], v[26:29]
	v_mfma_f32_16x16x32_bf16 v[14:17], v[78:81], v[232:235], v[14:17]
	v_mfma_f32_16x16x32_bf16 v[10:13], v[94:97], v[232:235], v[10:13]
	v_mfma_f32_16x16x32_bf16 v[54:57], v[146:149], v[186:189], v[54:57]
	v_mfma_f32_16x16x32_bf16 v[50:53], v[154:157], v[186:189], v[50:53]
	v_mfma_f32_16x16x32_bf16 v[38:41], v[146:149], v[212:215], v[38:41]
	v_mfma_f32_16x16x32_bf16 v[34:37], v[154:157], v[212:215], v[34:37]
	v_mfma_f32_16x16x32_bf16 v[22:25], v[146:149], v[220:223], v[22:25]
	v_mfma_f32_16x16x32_bf16 v[18:21], v[154:157], v[220:223], v[18:21]
	v_mfma_f32_16x16x32_bf16 v[6:9], v[146:149], v[228:231], v[6:9]
	v_mfma_f32_16x16x32_bf16 v[2:5], v[154:157], v[228:231], v[2:5]
	v_mfma_f32_16x16x32_bf16 v[54:57], v[150:153], v[208:211], v[54:57]
	v_mfma_f32_16x16x32_bf16 v[50:53], v[158:161], v[208:211], v[50:53]
	v_mfma_f32_16x16x32_bf16 v[38:41], v[150:153], v[216:219], v[38:41]
	v_mfma_f32_16x16x32_bf16 v[34:37], v[158:161], v[216:219], v[34:37]
	v_mfma_f32_16x16x32_bf16 v[22:25], v[150:153], v[224:227], v[22:25]
	v_mfma_f32_16x16x32_bf16 v[18:21], v[158:161], v[224:227], v[18:21]
	v_mfma_f32_16x16x32_bf16 v[6:9], v[150:153], v[232:235], v[6:9]
	v_mfma_f32_16x16x32_bf16 v[2:5], v[158:161], v[232:235], v[2:5]
	s_setprio 0
	s_barrier
	s_add_i32 vcc_lo, vcc_lo, 2
	s_add_u32 s0, s0, 0x100
	s_addc_u32 s1, s1, 0
	s_add_u32 s58, s58, 0x100
	s_addc_u32 s59, s59, 0
.LBB0_186:
	s_add_u32 s40, s0, 0xfffc0080
	s_addc_u32 s41, s1, -1
	s_add_i32 s70, 0, 0x10000
	s_cmp_eq_u32 vcc_lo, 12
	s_cselect_b32 s43, s16, s41
	s_cselect_b32 s42, s17, s40
	s_cselect_b32 s41, s51, s59
	s_cselect_b32 s40, s53, s58
	s_add_i32 vcc_hi, 0, 0x14000
	v_add_u32_e32 v94, s70, v201
	v_add_u32_e32 v158, vcc_hi, v201
	ds_read_b128 v[74:77], v94
	ds_read_b128 v[78:81], v94 offset:1024
	ds_read_b128 v[90:93], v94 offset:2048
	ds_read_b128 v[94:97], v94 offset:3072
	ds_read_b128 v[146:149], v158
	ds_read_b128 v[150:153], v158 offset:1024
	ds_read_b128 v[154:157], v158 offset:2048
	ds_read_b128 v[158:161], v158 offset:3072
	v_lshl_add_u64 v[190:191], s[0:1], 0, v[182:183]
	s_add_i32 m0, s61, 0xc000
	ds_read_b128 v[186:189], v203
	ds_read_b128 v[208:211], v203 offset:1024
	ds_read_b128 v[212:215], v203 offset:2048
	ds_read_b128 v[216:219], v203 offset:3072
	ds_read_b128 v[220:223], v203 offset:4096
	ds_read_b128 v[224:227], v203 offset:5120
	ds_read_b128 v[228:231], v203 offset:6144
	ds_read_b128 v[232:235], v203 offset:7168
	global_load_lds_dwordx4 v[190:191], off
	v_lshl_add_u64 v[190:191], s[0:1], 0, v[184:185]
	s_add_i32 m0, s61, 0xe000
	s_nop 0
	global_load_lds_dwordx4 v[190:191], off
	s_waitcnt vmcnt(8)
	s_waitcnt lgkmcnt(0)
	s_barrier
; #define PG8_STAGE(bufoff, gbase, voff) do { _Pragma("unroll") for (int _i = 0; _i < 2; ++_i) \
;         __builtin_amdgcn_global_load_lds((const unsigned*)((const char*)(gbase) + (voff)[_i]), (PG8_LAS unsigned*)(lds + (bufoff) + ldsw + _i * 8192), 16, 0, 0); } while (0)
; #define PG8_STAGEA(bufoff, gbase, voff) do { _Pragma("unroll") for (int _i = 0; _i < 2; ++_i) \
;         __builtin_amdgcn_global_load_lds((const unsigned*)((const char*)(gbase) + (voff)[_i]), (PG8_LAS unsigned*)(lds + (bufoff) + ldsw + _i * 8192), 16, 0, A_AUX); } while (0)
; #define PG8_LDA(dst, b, h) do { _Pragma("unroll") for (int m = 0; m < 4; ++m) _Pragma("unroll") for (int k = 0; k < 2; ++k) dst[m][k] = *(const PG8_LAS bf16x8*)(lds + PG8_SA(b, h) + aoff + m * 2048 + k * 1024); } while (0)
; #define PG8_LDB(dst, b, h) do { _Pragma("unroll") for (int n = 0; n < 2; ++n) _Pragma("unroll") for (int k = 0; k < 2; ++k) dst[n][k] = *(const PG8_LAS bf16x8*)(lds + PG8_SB(b, h) + boff + n * 2048 + k * 1024); } while (0)
; #define PG8_MMA(ai, bj, At, Bt) do { __builtin_amdgcn_s_setprio(1); _Pragma("unroll") for (int m = 0; m < 4; ++m) _Pragma("unroll") for (int n = 0; n < 2; ++n) _Pragma("unroll") for (int k = 0; k < 2; ++k) \
;         acc[ai][bj][m][n] = __builtin_amdgcn_mfma_f32_16x16x32_bf16(Bt[n][k], At[m][k], acc[ai][bj][m][n], 0, 0, 0); __builtin_amdgcn_s_setprio(0); } while (0)
; #define PG8_WAIT_V(n) asm volatile("s_waitcnt vmcnt(" #n ")" ::: "memory")
; #define PG8_WAIT_L(n) asm volatile("s_waitcnt lgkmcnt(" #n ")" ::: "memory")
; #define PG8_BAR __builtin_amdgcn_s_barrier()
; #define PG8_SCHED __builtin_amdgcn_sched_barrier(0)
;     ...
;             PG8_LDB(B0, 0, 0); PG8_LDB(B1, 0, 1); PG8_SCHED; PG8_LDA(At, 0, 0); PG8_STAGEA(PG8_SA(1, 1), a1 + hstep, voffA);
;             PG8_WAIT_V(8); PG8_WAIT_L(0); PG8_BAR; PG8_MMA(0, 0, At, B0); PG8_MMA(0, 1, At, B1); PG8_BAR; PG8_SCHED;
;             PG8_LDA(At, 0, 1); PG8_STAGE(PG8_SB(0, 0), b2, voffB); PG8_STAGE(PG8_SB(0, 1), b2 + hstep, voffB); PG8_STAGEA(PG8_SA(0, 0), a2, voffA);
;             PG8_WAIT_V(8); PG8_WAIT_L(0); PG8_BAR; PG8_MMA(1, 0, At, B0); PG8_MMA(1, 1, At, B1); PG8_BAR; PG8_SCHED;
;             PG8_LDB(B0, 1, 0); PG8_LDB(B1, 1, 1); PG8_SCHED; PG8_LDA(At, 1, 0); PG8_STAGEA(PG8_SA(0, 1), a2 + hstep, voffA);
;             PG8_WAIT_V(8); PG8_WAIT_L(0); PG8_BAR; PG8_MMA(0, 0, At, B0); PG8_MMA(0, 1, At, B1); PG8_BAR; PG8_SCHED;
	s_setprio 1
	s_waitcnt lgkmcnt(0)
	v_mfma_f32_16x16x32_bf16 v[142:145], v[74:77], v[186:189], v[142:145]
	v_mfma_f32_16x16x32_bf16 v[138:141], v[90:93], v[186:189], v[138:141]
	v_mfma_f32_16x16x32_bf16 v[126:129], v[74:77], v[212:215], v[126:129]
	v_mfma_f32_16x16x32_bf16 v[122:125], v[90:93], v[212:215], v[122:125]
	v_mfma_f32_16x16x32_bf16 v[110:113], v[74:77], v[220:223], v[110:113]
	v_mfma_f32_16x16x32_bf16 v[106:109], v[90:93], v[220:223], v[106:109]
	v_mfma_f32_16x16x32_bf16 v[86:89], v[74:77], v[228:231], v[86:89]
	v_mfma_f32_16x16x32_bf16 v[82:85], v[90:93], v[228:231], v[82:85]
	v_mfma_f32_16x16x32_bf16 v[142:145], v[78:81], v[208:211], v[142:145]
	v_mfma_f32_16x16x32_bf16 v[138:141], v[94:97], v[208:211], v[138:141]
	v_mfma_f32_16x16x32_bf16 v[126:129], v[78:81], v[216:219], v[126:129]
	v_mfma_f32_16x16x32_bf16 v[122:125], v[94:97], v[216:219], v[122:125]
	v_mfma_f32_16x16x32_bf16 v[110:113], v[78:81], v[224:227], v[110:113]
	v_mfma_f32_16x16x32_bf16 v[106:109], v[94:97], v[224:227], v[106:109]
	v_mfma_f32_16x16x32_bf16 v[86:89], v[78:81], v[232:235], v[86:89]
	v_mfma_f32_16x16x32_bf16 v[82:85], v[94:97], v[232:235], v[82:85]
	v_mfma_f32_16x16x32_bf16 v[134:137], v[146:149], v[186:189], v[134:137]
	v_mfma_f32_16x16x32_bf16 v[130:133], v[154:157], v[186:189], v[130:133]
	v_mfma_f32_16x16x32_bf16 v[118:121], v[146:149], v[212:215], v[118:121]
	v_mfma_f32_16x16x32_bf16 v[114:117], v[154:157], v[212:215], v[114:117]
	v_mfma_f32_16x16x32_bf16 v[102:105], v[146:149], v[220:223], v[102:105]
	v_mfma_f32_16x16x32_bf16 v[98:101], v[154:157], v[220:223], v[98:101]
	v_mfma_f32_16x16x32_bf16 v[70:73], v[146:149], v[228:231], v[70:73]
	v_mfma_f32_16x16x32_bf16 v[66:69], v[154:157], v[228:231], v[66:69]
	v_mfma_f32_16x16x32_bf16 v[134:137], v[150:153], v[208:211], v[134:137]
	v_mfma_f32_16x16x32_bf16 v[130:133], v[158:161], v[208:211], v[130:133]
	v_mfma_f32_16x16x32_bf16 v[118:121], v[150:153], v[216:219], v[118:121]
	v_mfma_f32_16x16x32_bf16 v[114:117], v[158:161], v[216:219], v[114:117]
	v_mfma_f32_16x16x32_bf16 v[102:105], v[150:153], v[224:227], v[102:105]
	v_mfma_f32_16x16x32_bf16 v[98:101], v[158:161], v[224:227], v[98:101]
	v_mfma_f32_16x16x32_bf16 v[70:73], v[150:153], v[232:235], v[70:73]
	v_mfma_f32_16x16x32_bf16 v[66:69], v[158:161], v[232:235], v[66:69]
	s_setprio 0
	s_barrier
	s_add_i32 s70, s70, s60
	v_lshl_add_u64 v[190:191], s[40:41], 0, v[0:1]
	s_mov_b32 m0, s70
	ds_read_b128 v[186:189], v203 offset:16384
	ds_read_b128 v[208:211], v203 offset:17408
	ds_read_b128 v[212:215], v203 offset:18432
	ds_read_b128 v[216:219], v203 offset:19456
	ds_read_b128 v[220:223], v203 offset:20480
	ds_read_b128 v[224:227], v203 offset:21504
	ds_read_b128 v[228:231], v203 offset:22528
	ds_read_b128 v[232:235], v203 offset:23552
	global_load_lds_dwordx4 v[190:191], off
	s_add_i32 m0, s70, 0x2000
	s_add_u32 s70, s40, 0x40000
	v_lshl_add_u64 v[236:237], s[40:41], 0, v[174:175]
	s_addc_u32 s71, s41, 0
	s_add_i32 vcc_hi, vcc_hi, s60
	global_load_lds_dwordx4 v[236:237], off
	v_lshl_add_u64 v[238:239], s[70:71], 0, v[0:1]
	s_mov_b32 m0, vcc_hi
	v_lshl_add_u64 v[240:241], s[42:43], 0, v[176:177]
	global_load_lds_dwordx4 v[238:239], off
	v_lshl_add_u64 v[238:239], s[70:71], 0, v[174:175]
	s_add_i32 m0, vcc_hi, 0x2000
	s_nop 0
	global_load_lds_dwordx4 v[238:239], off
	v_lshl_add_u64 v[238:239], s[42:43], 0, v[178:179]
	s_mov_b32 m0, s61
	s_nop 0
	global_load_lds_dwordx4 v[238:239], off
	s_mov_b32 m0, s62
	s_nop 0
	global_load_lds_dwordx4 v[240:241], off
	s_waitcnt vmcnt(8)
	s_waitcnt lgkmcnt(0)
	s_barrier
	s_setprio 1
	s_waitcnt lgkmcnt(0)
	v_mfma_f32_16x16x32_bf16 v[62:65], v[74:77], v[186:189], v[62:65]
	v_mfma_f32_16x16x32_bf16 v[58:61], v[90:93], v[186:189], v[58:61]
	v_mfma_f32_16x16x32_bf16 v[46:49], v[74:77], v[212:215], v[46:49]
	v_mfma_f32_16x16x32_bf16 v[42:45], v[90:93], v[212:215], v[42:45]
	v_mfma_f32_16x16x32_bf16 v[30:33], v[74:77], v[220:223], v[30:33]
	v_mfma_f32_16x16x32_bf16 v[26:29], v[90:93], v[220:223], v[26:29]
	v_mfma_f32_16x16x32_bf16 v[14:17], v[74:77], v[228:231], v[14:17]
	v_mfma_f32_16x16x32_bf16 v[10:13], v[90:93], v[228:231], v[10:13]
	v_mfma_f32_16x16x32_bf16 v[62:65], v[78:81], v[208:211], v[62:65]
	v_mfma_f32_16x16x32_bf16 v[58:61], v[94:97], v[208:211], v[58:61]
	v_mfma_f32_16x16x32_bf16 v[46:49], v[78:81], v[216:219], v[46:49]
	v_mfma_f32_16x16x32_bf16 v[42:45], v[94:97], v[216:219], v[42:45]
	v_mfma_f32_16x16x32_bf16 v[30:33], v[78:81], v[224:227], v[30:33]
	v_mfma_f32_16x16x32_bf16 v[26:29], v[94:97], v[224:227], v[26:29]
	v_mfma_f32_16x16x32_bf16 v[14:17], v[78:81], v[232:235], v[14:17]
	v_mfma_f32_16x16x32_bf16 v[10:13], v[94:97], v[232:235], v[10:13]
	v_mfma_f32_16x16x32_bf16 v[54:57], v[146:149], v[186:189], v[54:57]
	v_mfma_f32_16x16x32_bf16 v[50:53], v[154:157], v[186:189], v[50:53]
	v_mfma_f32_16x16x32_bf16 v[38:41], v[146:149], v[212:215], v[38:41]
	v_mfma_f32_16x16x32_bf16 v[34:37], v[154:157], v[212:215], v[34:37]
	v_mfma_f32_16x16x32_bf16 v[22:25], v[146:149], v[220:223], v[22:25]
	v_mfma_f32_16x16x32_bf16 v[18:21], v[154:157], v[220:223], v[18:21]
	v_mfma_f32_16x16x32_bf16 v[6:9], v[146:149], v[228:231], v[6:9]
	v_mfma_f32_16x16x32_bf16 v[2:5], v[154:157], v[228:231], v[2:5]
	v_mfma_f32_16x16x32_bf16 v[54:57], v[150:153], v[208:211], v[54:57]
	v_mfma_f32_16x16x32_bf16 v[50:53], v[158:161], v[208:211], v[50:53]
	v_mfma_f32_16x16x32_bf16 v[38:41], v[150:153], v[216:219], v[38:41]
	v_mfma_f32_16x16x32_bf16 v[34:37], v[158:161], v[216:219], v[34:37]
	v_mfma_f32_16x16x32_bf16 v[22:25], v[150:153], v[224:227], v[22:25]
	v_mfma_f32_16x16x32_bf16 v[18:21], v[158:161], v[224:227], v[18:21]
	v_mfma_f32_16x16x32_bf16 v[6:9], v[150:153], v[232:235], v[6:9]
	v_mfma_f32_16x16x32_bf16 v[2:5], v[158:161], v[232:235], v[2:5]
	s_setprio 0
	s_barrier
; #define PG8_STAGEA(bufoff, gbase, voff) do { _Pragma("unroll") for (int _i = 0; _i < 2; ++_i) \
;         __builtin_amdgcn_global_load_lds((const unsigned*)((const char*)(gbase) + (voff)[_i]), (PG8_LAS unsigned*)(lds + (bufoff) + ldsw + _i * 8192), 16, 0, A_AUX); } while (0)
; #define PG8_LDA(dst, b, h) do { _Pragma("unroll") for (int m = 0; m < 4; ++m) _Pragma("unroll") for (int k = 0; k < 2; ++k) dst[m][k] = *(const PG8_LAS bf16x8*)(lds + PG8_SA(b, h) + aoff + m * 2048 + k * 1024); } while (0)
; #define PG8_LDB(dst, b, h) do { _Pragma("unroll") for (int n = 0; n < 2; ++n) _Pragma("unroll") for (int k = 0; k < 2; ++k) dst[n][k] = *(const PG8_LAS bf16x8*)(lds + PG8_SB(b, h) + boff + n * 2048 + k * 1024); } while (0)
; #define PG8_MMA(ai, bj, At, Bt) do { __builtin_amdgcn_s_setprio(1); _Pragma("unroll") for (int m = 0; m < 4; ++m) _Pragma("unroll") for (int n = 0; n < 2; ++n) _Pragma("unroll") for (int k = 0; k < 2; ++k) \
;         acc[ai][bj][m][n] = __builtin_amdgcn_mfma_f32_16x16x32_bf16(Bt[n][k], At[m][k], acc[ai][bj][m][n], 0, 0, 0); __builtin_amdgcn_s_setprio(0); } while (0)
; #define PG8_WAIT_V(n) asm volatile("s_waitcnt vmcnt(" #n ")" ::: "memory")
; #define PG8_WAIT_L(n) asm volatile("s_waitcnt lgkmcnt(" #n ")" ::: "memory")
; #define PG8_BAR __builtin_amdgcn_s_barrier()
; #define PG8_SCHED __builtin_amdgcn_sched_barrier(0)
;     ...
;             PG8_LDB(B0, 1, 0); PG8_LDB(B1, 1, 1); PG8_SCHED; PG8_LDA(At, 1, 0); PG8_STAGEA(PG8_SA(0, 1), a2 + hstep, voffA);
;             PG8_WAIT_V(8); PG8_WAIT_L(0); PG8_BAR; PG8_MMA(0, 0, At, B0); PG8_MMA(0, 1, At, B1); PG8_BAR; PG8_SCHED;
	s_add_i32 s70, 0, 0x18000
	s_add_i32 s71, 0, 0x1c000
	v_add_u32_e32 v94, s70, v201
	v_add_u32_e32 v158, s71, v201
	ds_read_b128 v[74:77], v94
	ds_read_b128 v[78:81], v94 offset:1024
	ds_read_b128 v[90:93], v94 offset:2048
	ds_read_b128 v[94:97], v94 offset:3072
	ds_read_b128 v[146:149], v158
	ds_read_b128 v[150:153], v158 offset:1024
	ds_read_b128 v[154:157], v158 offset:2048
	ds_read_b128 v[158:161], v158 offset:3072
	s_add_u32 s42, s42, 0x40000
	s_addc_u32 s43, s43, 0
	s_mov_b32 m0, s63
	v_lshl_add_u64 v[242:243], s[42:43], 0, v[178:179]
	ds_read_b128 v[186:189], v203 offset:32768
	ds_read_b128 v[208:211], v203 offset:33792
	ds_read_b128 v[212:215], v203 offset:34816
	ds_read_b128 v[216:219], v203 offset:35840
	ds_read_b128 v[220:223], v203 offset:36864
	ds_read_b128 v[224:227], v203 offset:37888
	ds_read_b128 v[228:231], v203 offset:38912
	ds_read_b128 v[232:235], v203 offset:39936
	global_load_lds_dwordx4 v[242:243], off
	v_lshl_add_u64 v[242:243], s[42:43], 0, v[176:177]
	s_mov_b32 m0, s64
	s_nop 0
	global_load_lds_dwordx4 v[242:243], off
	s_waitcnt vmcnt(8)
	s_waitcnt lgkmcnt(0)
	s_barrier
	s_setprio 1
	s_waitcnt lgkmcnt(0)
	v_mfma_f32_16x16x32_bf16 v[142:145], v[74:77], v[186:189], v[142:145]
	v_mfma_f32_16x16x32_bf16 v[138:141], v[90:93], v[186:189], v[138:141]
	v_mfma_f32_16x16x32_bf16 v[126:129], v[74:77], v[212:215], v[126:129]
	v_mfma_f32_16x16x32_bf16 v[122:125], v[90:93], v[212:215], v[122:125]
	v_mfma_f32_16x16x32_bf16 v[110:113], v[74:77], v[220:223], v[110:113]
	v_mfma_f32_16x16x32_bf16 v[106:109], v[90:93], v[220:223], v[106:109]
	v_mfma_f32_16x16x32_bf16 v[86:89], v[74:77], v[228:231], v[86:89]
	v_mfma_f32_16x16x32_bf16 v[82:85], v[90:93], v[228:231], v[82:85]
	v_mfma_f32_16x16x32_bf16 v[142:145], v[78:81], v[208:211], v[142:145]
	v_mfma_f32_16x16x32_bf16 v[138:141], v[94:97], v[208:211], v[138:141]
	v_mfma_f32_16x16x32_bf16 v[126:129], v[78:81], v[216:219], v[126:129]
	v_mfma_f32_16x16x32_bf16 v[122:125], v[94:97], v[216:219], v[122:125]
	v_mfma_f32_16x16x32_bf16 v[110:113], v[78:81], v[224:227], v[110:113]
	v_mfma_f32_16x16x32_bf16 v[106:109], v[94:97], v[224:227], v[106:109]
	v_mfma_f32_16x16x32_bf16 v[86:89], v[78:81], v[232:235], v[86:89]
	v_mfma_f32_16x16x32_bf16 v[82:85], v[94:97], v[232:235], v[82:85]
	v_mfma_f32_16x16x32_bf16 v[134:137], v[146:149], v[186:189], v[134:137]
	v_mfma_f32_16x16x32_bf16 v[130:133], v[154:157], v[186:189], v[130:133]
	v_mfma_f32_16x16x32_bf16 v[118:121], v[146:149], v[212:215], v[118:121]
	v_mfma_f32_16x16x32_bf16 v[114:117], v[154:157], v[212:215], v[114:117]
	v_mfma_f32_16x16x32_bf16 v[102:105], v[146:149], v[220:223], v[102:105]
	v_mfma_f32_16x16x32_bf16 v[98:101], v[154:157], v[220:223], v[98:101]
	v_mfma_f32_16x16x32_bf16 v[70:73], v[146:149], v[228:231], v[70:73]
	v_mfma_f32_16x16x32_bf16 v[66:69], v[154:157], v[228:231], v[66:69]
	v_mfma_f32_16x16x32_bf16 v[134:137], v[150:153], v[208:211], v[134:137]
	v_mfma_f32_16x16x32_bf16 v[130:133], v[158:161], v[208:211], v[130:133]
	v_mfma_f32_16x16x32_bf16 v[118:121], v[150:153], v[216:219], v[118:121]
	v_mfma_f32_16x16x32_bf16 v[114:117], v[158:161], v[216:219], v[114:117]
	v_mfma_f32_16x16x32_bf16 v[102:105], v[150:153], v[224:227], v[102:105]
	v_mfma_f32_16x16x32_bf16 v[98:101], v[158:161], v[224:227], v[98:101]
	v_mfma_f32_16x16x32_bf16 v[70:73], v[150:153], v[232:235], v[70:73]
	v_mfma_f32_16x16x32_bf16 v[66:69], v[158:161], v[232:235], v[66:69]
	s_setprio 0
	s_barrier
; #define PG8_STAGE(bufoff, gbase, voff) do { _Pragma("unroll") for (int _i = 0; _i < 2; ++_i) \
;         __builtin_amdgcn_global_load_lds((const unsigned*)((const char*)(gbase) + (voff)[_i]), (PG8_LAS unsigned*)(lds + (bufoff) + ldsw + _i * 8192), 16, 0, 0); } while (0)
; #define PG8_STAGEA(bufoff, gbase, voff) do { _Pragma("unroll") for (int _i = 0; _i < 2; ++_i) \
;         __builtin_amdgcn_global_load_lds((const unsigned*)((const char*)(gbase) + (voff)[_i]), (PG8_LAS unsigned*)(lds + (bufoff) + ldsw + _i * 8192), 16, 0, A_AUX); } while (0)
; #define PG8_LDA(dst, b, h) do { _Pragma("unroll") for (int m = 0; m < 4; ++m) _Pragma("unroll") for (int k = 0; k < 2; ++k) dst[m][k] = *(const PG8_LAS bf16x8*)(lds + PG8_SA(b, h) + aoff + m * 2048 + k * 1024); } while (0)
; #define PG8_WAIT_V(n) asm volatile("s_waitcnt vmcnt(" #n ")" ::: "memory")
; #define PG8_BAR __builtin_amdgcn_s_barrier()
;     ...
;         for (int t = 0; t < nt; t += 2) {
;             const bool last = (t == nt - 2);
;             const char* a1 = cA + (size_t)(t + 1) * kstep;
;             const char* a2 = last ? nA : cA + (size_t)(t + 2) * kstep; const char* b2 = last ? nB : cB + (size_t)(t + 2) * kstep;
;             const char* a3 = a2 + kstep; const char* b3 = b2 + kstep;
;             if (last && has_next) S.a_ready(nxt);
;             if constexpr (SP2) {
;             PG8_LDB(B0, 0, 0); PG8_LDB(B1, 0, 1); PG8_SCHED; PG8_LDA(At, 0, 0); PG8_STAGEA(PG8_SA(1, 1), a1 + hstep, voffA);
;             PG8_WAIT_V(8); PG8_WAIT_L(0); PG8_BAR; PG8_MMA(0, 0, At, B0); PG8_MMA(0, 1, At, B1); PG8_BAR; PG8_SCHED;
;             PG8_LDA(At, 0, 1); PG8_STAGE(PG8_SB(0, 0), b2, voffB); PG8_STAGE(PG8_SB(0, 1), b2 + hstep, voffB); PG8_STAGEA(PG8_SA(0, 0), a2, voffA);
;             PG8_WAIT_V(8); PG8_WAIT_L(0); PG8_BAR; PG8_MMA(1, 0, At, B0); PG8_MMA(1, 1, At, B1); PG8_BAR; PG8_SCHED;
;             PG8_LDB(B0, 1, 0); PG8_LDB(B1, 1, 1); PG8_SCHED; PG8_LDA(At, 1, 0); PG8_STAGEA(PG8_SA(0, 1), a2 + hstep, voffA);
;             PG8_WAIT_V(8); PG8_WAIT_L(0); PG8_BAR; PG8_MMA(0, 0, At, B0); PG8_MMA(0, 1, At, B1); PG8_BAR; PG8_SCHED;
;             PG8_LDA(At, 1, 1); PG8_STAGE(PG8_SB(1, 0), b3, voffB); PG8_STAGE(PG8_SB(1, 1), b3 + hstep, voffB); PG8_STAGEA(PG8_SA(1, 0), a3, voffA);
;             PG8_WAIT_V(8); PG8_WAIT_L(0); PG8_BAR; PG8_MMA(1, 0, At, B0); PG8_MMA(1, 1, At, B1); PG8_BAR; PG8_SCHED;
	s_add_i32 s42, s70, s60
	v_lshl_add_u64 v[190:191], v[190:191], 0, s[8:9]
	s_mov_b32 m0, s42
	ds_read_b128 v[186:189], v203 offset:49152
	ds_read_b128 v[208:211], v203 offset:50176
	ds_read_b128 v[212:215], v203 offset:51200
	ds_read_b128 v[216:219], v203 offset:52224
	ds_read_b128 v[220:223], v203 offset:53248
	ds_read_b128 v[224:227], v203 offset:54272
	ds_read_b128 v[228:231], v203 offset:55296
	ds_read_b128 v[232:235], v203 offset:56320
	global_load_lds_dwordx4 v[190:191], off
	s_add_i32 m0, s42, 0x2000
	s_add_u32 s40, s40, 0x40080
	v_lshl_add_u64 v[190:191], v[236:237], 0, s[8:9]
	s_addc_u32 s41, s41, 0
	s_add_i32 s42, s71, s60
	global_load_lds_dwordx4 v[190:191], off
	v_lshl_add_u64 v[190:191], s[40:41], 0, v[0:1]
	s_mov_b32 m0, s42
	s_nop 0
	global_load_lds_dwordx4 v[190:191], off
	v_lshl_add_u64 v[190:191], s[40:41], 0, v[174:175]
	s_add_i32 m0, s42, 0x2000
	s_nop 0
	global_load_lds_dwordx4 v[190:191], off
	v_lshl_add_u64 v[190:191], v[238:239], 0, s[8:9]
	s_mov_b32 m0, s72
	s_nop 0
	global_load_lds_dwordx4 v[190:191], off
	v_lshl_add_u64 v[190:191], v[240:241], 0, s[8:9]
	s_mov_b32 m0, s73
	s_nop 0
	global_load_lds_dwordx4 v[190:191], off
	s_waitcnt vmcnt(8)
	s_waitcnt lgkmcnt(0)
	s_barrier
	s_setprio 1
	s_waitcnt lgkmcnt(0)
	v_mfma_f32_16x16x32_bf16 v[62:65], v[74:77], v[186:189], v[62:65]
	v_mfma_f32_16x16x32_bf16 v[58:61], v[90:93], v[186:189], v[58:61]
	v_mfma_f32_16x16x32_bf16 v[46:49], v[74:77], v[212:215], v[46:49]
	v_mfma_f32_16x16x32_bf16 v[42:45], v[90:93], v[212:215], v[42:45]
	v_mfma_f32_16x16x32_bf16 v[30:33], v[74:77], v[220:223], v[30:33]
	v_mfma_f32_16x16x32_bf16 v[26:29], v[90:93], v[220:223], v[26:29]
	v_mfma_f32_16x16x32_bf16 v[14:17], v[74:77], v[228:231], v[14:17]
	v_mfma_f32_16x16x32_bf16 v[10:13], v[90:93], v[228:231], v[10:13]
	v_mfma_f32_16x16x32_bf16 v[62:65], v[78:81], v[208:211], v[62:65]
	v_mfma_f32_16x16x32_bf16 v[58:61], v[94:97], v[208:211], v[58:61]
	v_mfma_f32_16x16x32_bf16 v[46:49], v[78:81], v[216:219], v[46:49]
	v_mfma_f32_16x16x32_bf16 v[42:45], v[94:97], v[216:219], v[42:45]
	v_mfma_f32_16x16x32_bf16 v[30:33], v[78:81], v[224:227], v[30:33]
	v_mfma_f32_16x16x32_bf16 v[26:29], v[94:97], v[224:227], v[26:29]
	v_mfma_f32_16x16x32_bf16 v[14:17], v[78:81], v[232:235], v[14:17]
	v_mfma_f32_16x16x32_bf16 v[10:13], v[94:97], v[232:235], v[10:13]
	v_mfma_f32_16x16x32_bf16 v[54:57], v[146:149], v[186:189], v[54:57]
	v_mfma_f32_16x16x32_bf16 v[50:53], v[154:157], v[186:189], v[50:53]
	v_mfma_f32_16x16x32_bf16 v[38:41], v[146:149], v[212:215], v[38:41]
	v_mfma_f32_16x16x32_bf16 v[34:37], v[154:157], v[212:215], v[34:37]
	v_mfma_f32_16x16x32_bf16 v[22:25], v[146:149], v[220:223], v[22:25]
	v_mfma_f32_16x16x32_bf16 v[18:21], v[154:157], v[220:223], v[18:21]
	v_mfma_f32_16x16x32_bf16 v[6:9], v[146:149], v[228:231], v[6:9]
	v_mfma_f32_16x16x32_bf16 v[2:5], v[154:157], v[228:231], v[2:5]
	v_mfma_f32_16x16x32_bf16 v[54:57], v[150:153], v[208:211], v[54:57]
	v_mfma_f32_16x16x32_bf16 v[50:53], v[158:161], v[208:211], v[50:53]
	v_mfma_f32_16x16x32_bf16 v[38:41], v[150:153], v[216:219], v[38:41]
	v_mfma_f32_16x16x32_bf16 v[34:37], v[158:161], v[216:219], v[34:37]
	v_mfma_f32_16x16x32_bf16 v[22:25], v[150:153], v[224:227], v[22:25]
	v_mfma_f32_16x16x32_bf16 v[18:21], v[158:161], v[224:227], v[18:21]
	v_mfma_f32_16x16x32_bf16 v[6:9], v[150:153], v[232:235], v[6:9]
	v_mfma_f32_16x16x32_bf16 v[2:5], v[158:161], v[232:235], v[2:5]
	s_setprio 0
	s_barrier
	s_add_i32 vcc_lo, vcc_lo, 2
	s_add_u32 s0, s0, 0x100
	s_addc_u32 s1, s1, 0
	s_add_u32 s58, s58, 0x100
	s_addc_u32 s59, s59, 0
	s_cmp_gt_u32 vcc_lo, 13
	s_cbranch_scc0 .LBB0_186
	s_and_b64 vcc, exec, s[46:47]
	s_cbranch_vccz .LBB0_189
	s_barrier

; #define PG8_STAGE(bufoff, gbase, voff) do { _Pragma("unroll") for (int _i = 0; _i < 2; ++_i) \
;         __builtin_amdgcn_global_load_lds((const unsigned*)((const char*)(gbase) + (voff)[_i]), (PG8_LAS unsigned*)(lds + (bufoff) + ldsw + _i * 8192), 16, 0, 0); } while (0)
; #define PG8_STAGEA(bufoff, gbase, voff) do { _Pragma("unroll") for (int _i = 0; _i < 2; ++_i) \
;         __builtin_amdgcn_global_load_lds((const unsigned*)((const char*)(gbase) + (voff)[_i]), (PG8_LAS unsigned*)(lds + (bufoff) + ldsw + _i * 8192), 16, 0, A_AUX); } while (0)
; #define PG8_LDA(dst, b, h) do { _Pragma("unroll") for (int m = 0; m < 4; ++m) _Pragma("unroll") for (int k = 0; k < 2; ++k) dst[m][k] = *(const PG8_LAS bf16x8*)(lds + PG8_SA(b, h) + aoff + m * 2048 + k * 1024); } while (0)
; #define PG8_LDB(dst, b, h) do { _Pragma("unroll") for (int n = 0; n < 2; ++n) _Pragma("unroll") for (int k = 0; k < 2; ++k) dst[n][k] = *(const PG8_LAS bf16x8*)(lds + PG8_SB(b, h) + boff + n * 2048 + k * 1024); } while (0)
; #define PG8_WAIT_V(n) asm volatile("s_waitcnt vmcnt(" #n ")" ::: "memory")
; #define PG8_WAIT_L(n) asm volatile("s_waitcnt lgkmcnt(" #n ")" ::: "memory")
; #define PG8_BAR __builtin_amdgcn_s_barrier()
;     ...
;         const bool has_next = S.next(ui + 1, nxt);
;         const char* nA = has_next ? (const char*)g.A + (size_t)nxt.pm * tstep : cA; const char* nB = has_next ? (const char*)g.Bt + (size_t)nxt.pn * tstep : cB;
;         for (int t = 0; t < nt; t += 2) {
;             const bool last = (t == nt - 2);
;             const char* a1 = cA + (size_t)(t + 1) * kstep;
;             const char* a2 = last ? nA : cA + (size_t)(t + 2) * kstep; const char* b2 = last ? nB : cB + (size_t)(t + 2) * kstep;
;             const char* a3 = a2 + kstep; const char* b3 = b2 + kstep;
;             if (last && has_next) S.a_ready(nxt);
;             if constexpr (SP2) {
;             PG8_LDB(B0, 0, 0); PG8_LDB(B1, 0, 1); PG8_SCHED; PG8_LDA(At, 0, 0); PG8_STAGEA(PG8_SA(1, 1), a1 + hstep, voffA);
;             PG8_WAIT_V(8); PG8_WAIT_L(0); PG8_BAR; PG8_MMA(0, 0, At, B0); PG8_MMA(0, 1, At, B1); PG8_BAR; PG8_SCHED;
;             PG8_LDA(At, 0, 1); PG8_STAGE(PG8_SB(0, 0), b2, voffB); PG8_STAGE(PG8_SB(0, 1), b2 + hstep, voffB); PG8_STAGEA(PG8_SA(0, 0), a2, voffA);
;             PG8_WAIT_V(8); PG8_WAIT_L(0); PG8_BAR; PG8_MMA(1, 0, At, B0); PG8_MMA(1, 1, At, B1); PG8_BAR; PG8_SCHED;
.LBB0_442:
	s_ashr_i32 s43, s42, 31
	s_lshl_b64 s[16:17], s[42:43], 19
	s_add_u32 s44, s24, s16
	s_addc_u32 s45, s25, s17
	s_and_b64 s[16:17], s[38:39], exec
	s_cselect_b32 s16, s45, s49
	s_cselect_b32 s17, s44, s48
	s_ashr_i32 s41, s40, 31
	s_lshl_b64 s[46:47], s[40:41], 19
	s_add_u32 s46, s23, s46
	s_addc_u32 s47, s54, s47
	s_and_b64 s[52:53], s[38:39], exec
	s_cselect_b32 s41, s47, s51
	s_cselect_b32 s43, s46, s50
	s_add_u32 s48, s48, 0x40080
	s_addc_u32 s49, s49, 0
	s_add_u32 s65, s50, 0x100
	s_addc_u32 s72, s51, 0
	s_mov_b32 s73, -2
	s_add_u32 s50, s48, 0xfffc0080
	s_addc_u32 s51, s49, -1
	s_add_i32 s70, 0, 0x10000
	s_cmp_eq_u32 s73, 12
	s_cselect_b32 s53, s16, s51
	s_cselect_b32 s52, s17, s50
	v_add_u32_e32 v140, s70, v143
	s_cselect_b32 s51, s41, s72
	s_cselect_b32 s50, s43, s65
	s_add_i32 s76, 0, 0x14000
	ds_read_b128 v[146:149], v140
	ds_read_b128 v[150:153], v140 offset:1024
	ds_read_b128 v[154:157], v140 offset:2048
	ds_read_b128 v[158:161], v140 offset:3072
	v_add_u32_e32 v140, s76, v143
	ds_read_b128 v[174:177], v140
	ds_read_b128 v[178:181], v140 offset:1024
	ds_read_b128 v[182:185], v140 offset:2048
	ds_read_b128 v[186:189], v140 offset:3072
	v_lshl_add_u64 v[140:141], s[48:49], 0, v[136:137]
	s_add_i32 m0, s56, 0xc000
	ds_read_b128 v[200:203], v145
	ds_read_b128 v[208:211], v145 offset:1024
	ds_read_b128 v[212:215], v145 offset:2048
	ds_read_b128 v[216:219], v145 offset:3072
	ds_read_b128 v[220:223], v145 offset:4096
	ds_read_b128 v[224:227], v145 offset:5120
	ds_read_b128 v[228:231], v145 offset:6144
	ds_read_b128 v[232:235], v145 offset:7168
	global_load_lds_dwordx4 v[140:141], off
	v_lshl_add_u64 v[140:141], s[48:49], 0, v[138:139]
	s_add_i32 m0, s56, 0xe000
	s_nop 0
	global_load_lds_dwordx4 v[140:141], off
	s_waitcnt vmcnt(8)
	s_waitcnt lgkmcnt(0)
	s_barrier
	s_setprio 1
	s_waitcnt lgkmcnt(0)
	v_mfma_f32_16x16x32_bf16 v[126:129], v[146:149], v[200:203], 0
	v_mfma_f32_16x16x32_bf16 v[122:125], v[154:157], v[200:203], 0
	v_mfma_f32_16x16x32_bf16 v[114:117], v[146:149], v[212:215], 0
	v_mfma_f32_16x16x32_bf16 v[106:109], v[154:157], v[212:215], 0
	v_mfma_f32_16x16x32_bf16 v[98:101], v[146:149], v[220:223], 0
	v_mfma_f32_16x16x32_bf16 v[90:93], v[154:157], v[220:223], 0
	v_mfma_f32_16x16x32_bf16 v[82:85], v[146:149], v[228:231], 0
	v_mfma_f32_16x16x32_bf16 v[74:77], v[154:157], v[228:231], 0
	v_mfma_f32_16x16x32_bf16 v[126:129], v[150:153], v[208:211], v[126:129]
	v_mfma_f32_16x16x32_bf16 v[122:125], v[158:161], v[208:211], v[122:125]
	v_mfma_f32_16x16x32_bf16 v[114:117], v[150:153], v[216:219], v[114:117]
	v_mfma_f32_16x16x32_bf16 v[106:109], v[158:161], v[216:219], v[106:109]
	v_mfma_f32_16x16x32_bf16 v[98:101], v[150:153], v[224:227], v[98:101]
	v_mfma_f32_16x16x32_bf16 v[90:93], v[158:161], v[224:227], v[90:93]
	v_mfma_f32_16x16x32_bf16 v[82:85], v[150:153], v[232:235], v[82:85]
	v_mfma_f32_16x16x32_bf16 v[74:77], v[158:161], v[232:235], v[74:77]
	v_mfma_f32_16x16x32_bf16 v[118:121], v[174:177], v[200:203], 0
	v_mfma_f32_16x16x32_bf16 v[110:113], v[182:185], v[200:203], 0
	v_mfma_f32_16x16x32_bf16 v[102:105], v[174:177], v[212:215], 0
	v_mfma_f32_16x16x32_bf16 v[94:97], v[182:185], v[212:215], 0
	v_mfma_f32_16x16x32_bf16 v[86:89], v[174:177], v[220:223], 0
	v_mfma_f32_16x16x32_bf16 v[78:81], v[182:185], v[220:223], 0
	v_mfma_f32_16x16x32_bf16 v[70:73], v[174:177], v[228:231], 0
	v_mfma_f32_16x16x32_bf16 v[66:69], v[182:185], v[228:231], 0
	v_mfma_f32_16x16x32_bf16 v[118:121], v[178:181], v[208:211], v[118:121]
	v_mfma_f32_16x16x32_bf16 v[110:113], v[186:189], v[208:211], v[110:113]
	v_mfma_f32_16x16x32_bf16 v[102:105], v[178:181], v[216:219], v[102:105]
	v_mfma_f32_16x16x32_bf16 v[94:97], v[186:189], v[216:219], v[94:97]
	v_mfma_f32_16x16x32_bf16 v[86:89], v[178:181], v[224:227], v[86:89]
	v_mfma_f32_16x16x32_bf16 v[78:81], v[186:189], v[224:227], v[78:81]
	v_mfma_f32_16x16x32_bf16 v[70:73], v[178:181], v[232:235], v[70:73]
	v_mfma_f32_16x16x32_bf16 v[66:69], v[186:189], v[232:235], v[66:69]
	s_setprio 0
	s_barrier
	s_add_i32 s70, s70, s55
	v_lshl_add_u64 v[140:141], s[50:51], 0, v[0:1]
	s_mov_b32 m0, s70
	ds_read_b128 v[200:203], v145 offset:16384
	ds_read_b128 v[208:211], v145 offset:17408
	ds_read_b128 v[212:215], v145 offset:18432
	ds_read_b128 v[216:219], v145 offset:19456
	ds_read_b128 v[220:223], v145 offset:20480
	ds_read_b128 v[224:227], v145 offset:21504
	ds_read_b128 v[228:231], v145 offset:22528
	ds_read_b128 v[232:235], v145 offset:23552
	global_load_lds_dwordx4 v[140:141], off
	s_add_i32 m0, s70, 0x2000
	s_add_u32 s70, s50, 0x40000
	v_lshl_add_u64 v[190:191], s[50:51], 0, v[130:131]
	s_addc_u32 s71, s51, 0
	s_add_i32 s76, s76, s55
	global_load_lds_dwordx4 v[190:191], off
	v_lshl_add_u64 v[236:237], s[70:71], 0, v[0:1]
	s_mov_b32 m0, s76
	v_lshl_add_u64 v[238:239], s[52:53], 0, v[132:133]
	global_load_lds_dwordx4 v[236:237], off
	v_lshl_add_u64 v[236:237], s[70:71], 0, v[130:131]
	s_add_i32 m0, s76, 0x2000
	s_nop 0
	global_load_lds_dwordx4 v[236:237], off
	v_lshl_add_u64 v[236:237], s[52:53], 0, v[134:135]
	s_mov_b32 m0, s56
	s_nop 0
	global_load_lds_dwordx4 v[236:237], off
	s_mov_b32 m0, s57
	s_nop 0
	global_load_lds_dwordx4 v[238:239], off
	s_waitcnt vmcnt(8)
	s_waitcnt lgkmcnt(0)
	s_barrier
; #define PG8_STAGEA(bufoff, gbase, voff) do { _Pragma("unroll") for (int _i = 0; _i < 2; ++_i) \
;         __builtin_amdgcn_global_load_lds((const unsigned*)((const char*)(gbase) + (voff)[_i]), (PG8_LAS unsigned*)(lds + (bufoff) + ldsw + _i * 8192), 16, 0, A_AUX); } while (0)
; #define PG8_LDA(dst, b, h) do { _Pragma("unroll") for (int m = 0; m < 4; ++m) _Pragma("unroll") for (int k = 0; k < 2; ++k) dst[m][k] = *(const PG8_LAS bf16x8*)(lds + PG8_SA(b, h) + aoff + m * 2048 + k * 1024); } while (0)
; #define PG8_LDB(dst, b, h) do { _Pragma("unroll") for (int n = 0; n < 2; ++n) _Pragma("unroll") for (int k = 0; k < 2; ++k) dst[n][k] = *(const PG8_LAS bf16x8*)(lds + PG8_SB(b, h) + boff + n * 2048 + k * 1024); } while (0)
; #define PG8_MMA(ai, bj, At, Bt) do { __builtin_amdgcn_s_setprio(1); _Pragma("unroll") for (int m = 0; m < 4; ++m) _Pragma("unroll") for (int n = 0; n < 2; ++n) _Pragma("unroll") for (int k = 0; k < 2; ++k) \
;         acc[ai][bj][m][n] = __builtin_amdgcn_mfma_f32_16x16x32_bf16(Bt[n][k], At[m][k], acc[ai][bj][m][n], 0, 0, 0); __builtin_amdgcn_s_setprio(0); } while (0)
; #define PG8_WAIT_V(n) asm volatile("s_waitcnt vmcnt(" #n ")" ::: "memory")
; #define PG8_WAIT_L(n) asm volatile("s_waitcnt lgkmcnt(" #n ")" ::: "memory")
; #define PG8_BAR __builtin_amdgcn_s_barrier()
; #define PG8_SCHED __builtin_amdgcn_sched_barrier(0)
;     ...
;             PG8_WAIT_V(8); PG8_WAIT_L(0); PG8_BAR; PG8_MMA(1, 0, At, B0); PG8_MMA(1, 1, At, B1); PG8_BAR; PG8_SCHED;
;             PG8_LDB(B0, 1, 0); PG8_LDB(B1, 1, 1); PG8_SCHED; PG8_LDA(At, 1, 0); PG8_STAGEA(PG8_SA(0, 1), a2 + hstep, voffA);
;             PG8_WAIT_V(8); PG8_WAIT_L(0); PG8_BAR; PG8_MMA(0, 0, At, B0); PG8_MMA(0, 1, At, B1); PG8_BAR; PG8_SCHED;
	s_setprio 1
	s_waitcnt lgkmcnt(0)
	v_mfma_f32_16x16x32_bf16 v[62:65], v[146:149], v[200:203], 0
	v_mfma_f32_16x16x32_bf16 v[58:61], v[154:157], v[200:203], 0
	v_mfma_f32_16x16x32_bf16 v[50:53], v[146:149], v[212:215], 0
	v_mfma_f32_16x16x32_bf16 v[42:45], v[154:157], v[212:215], 0
	v_mfma_f32_16x16x32_bf16 v[34:37], v[146:149], v[220:223], 0
	v_mfma_f32_16x16x32_bf16 v[26:29], v[154:157], v[220:223], 0
	v_mfma_f32_16x16x32_bf16 v[18:21], v[146:149], v[228:231], 0
	v_mfma_f32_16x16x32_bf16 v[10:13], v[154:157], v[228:231], 0
	v_mfma_f32_16x16x32_bf16 v[62:65], v[150:153], v[208:211], v[62:65]
	v_mfma_f32_16x16x32_bf16 v[58:61], v[158:161], v[208:211], v[58:61]
	v_mfma_f32_16x16x32_bf16 v[50:53], v[150:153], v[216:219], v[50:53]
	v_mfma_f32_16x16x32_bf16 v[42:45], v[158:161], v[216:219], v[42:45]
	v_mfma_f32_16x16x32_bf16 v[34:37], v[150:153], v[224:227], v[34:37]
	v_mfma_f32_16x16x32_bf16 v[26:29], v[158:161], v[224:227], v[26:29]
	v_mfma_f32_16x16x32_bf16 v[18:21], v[150:153], v[232:235], v[18:21]
	v_mfma_f32_16x16x32_bf16 v[10:13], v[158:161], v[232:235], v[10:13]
	v_mfma_f32_16x16x32_bf16 v[54:57], v[174:177], v[200:203], 0
	v_mfma_f32_16x16x32_bf16 v[46:49], v[182:185], v[200:203], 0
	v_mfma_f32_16x16x32_bf16 v[38:41], v[174:177], v[212:215], 0
	v_mfma_f32_16x16x32_bf16 v[30:33], v[182:185], v[212:215], 0
	v_mfma_f32_16x16x32_bf16 v[22:25], v[174:177], v[220:223], 0
	v_mfma_f32_16x16x32_bf16 v[14:17], v[182:185], v[220:223], 0
	v_mfma_f32_16x16x32_bf16 v[6:9], v[174:177], v[228:231], 0
	v_mfma_f32_16x16x32_bf16 v[2:5], v[182:185], v[228:231], 0
	v_mfma_f32_16x16x32_bf16 v[54:57], v[178:181], v[208:211], v[54:57]
	v_mfma_f32_16x16x32_bf16 v[46:49], v[186:189], v[208:211], v[46:49]
	v_mfma_f32_16x16x32_bf16 v[38:41], v[178:181], v[216:219], v[38:41]
	v_mfma_f32_16x16x32_bf16 v[30:33], v[186:189], v[216:219], v[30:33]
	v_mfma_f32_16x16x32_bf16 v[22:25], v[178:181], v[224:227], v[22:25]
	v_mfma_f32_16x16x32_bf16 v[14:17], v[186:189], v[224:227], v[14:17]
	v_mfma_f32_16x16x32_bf16 v[6:9], v[178:181], v[232:235], v[6:9]
	v_mfma_f32_16x16x32_bf16 v[2:5], v[186:189], v[232:235], v[2:5]
	s_setprio 0
	s_barrier
	s_add_i32 s70, 0, 0x18000
	s_add_i32 s71, 0, 0x1c000
	v_add_u32_e32 v158, s70, v143
	v_add_u32_e32 v186, s71, v143
	ds_read_b128 v[146:149], v158
	ds_read_b128 v[150:153], v158 offset:1024
	ds_read_b128 v[154:157], v158 offset:2048
	ds_read_b128 v[158:161], v158 offset:3072
	ds_read_b128 v[174:177], v186
	ds_read_b128 v[178:181], v186 offset:1024
	ds_read_b128 v[182:185], v186 offset:2048
	ds_read_b128 v[186:189], v186 offset:3072
	s_add_u32 s52, s52, 0x40000
	s_addc_u32 s53, s53, 0
	s_mov_b32 m0, s58
	v_lshl_add_u64 v[240:241], s[52:53], 0, v[134:135]
	ds_read_b128 v[200:203], v145 offset:32768
	ds_read_b128 v[208:211], v145 offset:33792
	ds_read_b128 v[212:215], v145 offset:34816
	ds_read_b128 v[216:219], v145 offset:35840
	ds_read_b128 v[220:223], v145 offset:36864
	ds_read_b128 v[224:227], v145 offset:37888
	ds_read_b128 v[228:231], v145 offset:38912
	ds_read_b128 v[232:235], v145 offset:39936
	global_load_lds_dwordx4 v[240:241], off
	v_lshl_add_u64 v[240:241], s[52:53], 0, v[132:133]
	s_mov_b32 m0, s59
	s_nop 0
	global_load_lds_dwordx4 v[240:241], off
	s_waitcnt vmcnt(8)
	s_waitcnt lgkmcnt(0)
	s_barrier
	s_setprio 1
	s_waitcnt lgkmcnt(0)
	v_mfma_f32_16x16x32_bf16 v[126:129], v[146:149], v[200:203], v[126:129]
	v_mfma_f32_16x16x32_bf16 v[122:125], v[154:157], v[200:203], v[122:125]
	v_mfma_f32_16x16x32_bf16 v[114:117], v[146:149], v[212:215], v[114:117]
	v_mfma_f32_16x16x32_bf16 v[106:109], v[154:157], v[212:215], v[106:109]
	v_mfma_f32_16x16x32_bf16 v[98:101], v[146:149], v[220:223], v[98:101]
	v_mfma_f32_16x16x32_bf16 v[90:93], v[154:157], v[220:223], v[90:93]
	v_mfma_f32_16x16x32_bf16 v[82:85], v[146:149], v[228:231], v[82:85]
	v_mfma_f32_16x16x32_bf16 v[74:77], v[154:157], v[228:231], v[74:77]
	v_mfma_f32_16x16x32_bf16 v[126:129], v[150:153], v[208:211], v[126:129]
	v_mfma_f32_16x16x32_bf16 v[122:125], v[158:161], v[208:211], v[122:125]
	v_mfma_f32_16x16x32_bf16 v[114:117], v[150:153], v[216:219], v[114:117]
	v_mfma_f32_16x16x32_bf16 v[106:109], v[158:161], v[216:219], v[106:109]
	v_mfma_f32_16x16x32_bf16 v[98:101], v[150:153], v[224:227], v[98:101]
	v_mfma_f32_16x16x32_bf16 v[90:93], v[158:161], v[224:227], v[90:93]
	v_mfma_f32_16x16x32_bf16 v[82:85], v[150:153], v[232:235], v[82:85]
	v_mfma_f32_16x16x32_bf16 v[74:77], v[158:161], v[232:235], v[74:77]
	v_mfma_f32_16x16x32_bf16 v[118:121], v[174:177], v[200:203], v[118:121]
	v_mfma_f32_16x16x32_bf16 v[110:113], v[182:185], v[200:203], v[110:113]
	v_mfma_f32_16x16x32_bf16 v[102:105], v[174:177], v[212:215], v[102:105]
	v_mfma_f32_16x16x32_bf16 v[94:97], v[182:185], v[212:215], v[94:97]
	v_mfma_f32_16x16x32_bf16 v[86:89], v[174:177], v[220:223], v[86:89]
	v_mfma_f32_16x16x32_bf16 v[78:81], v[182:185], v[220:223], v[78:81]
	v_mfma_f32_16x16x32_bf16 v[70:73], v[174:177], v[228:231], v[70:73]
	v_mfma_f32_16x16x32_bf16 v[66:69], v[182:185], v[228:231], v[66:69]
	v_mfma_f32_16x16x32_bf16 v[118:121], v[178:181], v[208:211], v[118:121]
	v_mfma_f32_16x16x32_bf16 v[110:113], v[186:189], v[208:211], v[110:113]
	v_mfma_f32_16x16x32_bf16 v[102:105], v[178:181], v[216:219], v[102:105]
	v_mfma_f32_16x16x32_bf16 v[94:97], v[186:189], v[216:219], v[94:97]
	v_mfma_f32_16x16x32_bf16 v[86:89], v[178:181], v[224:227], v[86:89]
	v_mfma_f32_16x16x32_bf16 v[78:81], v[186:189], v[224:227], v[78:81]
	v_mfma_f32_16x16x32_bf16 v[70:73], v[178:181], v[232:235], v[70:73]
	v_mfma_f32_16x16x32_bf16 v[66:69], v[186:189], v[232:235], v[66:69]
	s_setprio 0
	s_barrier
; #define PG8_STAGE(bufoff, gbase, voff) do { _Pragma("unroll") for (int _i = 0; _i < 2; ++_i) \
;         __builtin_amdgcn_global_load_lds((const unsigned*)((const char*)(gbase) + (voff)[_i]), (PG8_LAS unsigned*)(lds + (bufoff) + ldsw + _i * 8192), 16, 0, 0); } while (0)
; #define PG8_STAGEA(bufoff, gbase, voff) do { _Pragma("unroll") for (int _i = 0; _i < 2; ++_i) \
;         __builtin_amdgcn_global_load_lds((const unsigned*)((const char*)(gbase) + (voff)[_i]), (PG8_LAS unsigned*)(lds + (bufoff) + ldsw + _i * 8192), 16, 0, A_AUX); } while (0)
; #define PG8_LDA(dst, b, h) do { _Pragma("unroll") for (int m = 0; m < 4; ++m) _Pragma("unroll") for (int k = 0; k < 2; ++k) dst[m][k] = *(const PG8_LAS bf16x8*)(lds + PG8_SA(b, h) + aoff + m * 2048 + k * 1024); } while (0)
; #define PG8_WAIT_V(n) asm volatile("s_waitcnt vmcnt(" #n ")" ::: "memory")
; #define PG8_BAR __builtin_amdgcn_s_barrier()
;     ...
;         for (int t = 0; t < nt; t += 2) {
;             const bool last = (t == nt - 2);
;             const char* a1 = cA + (size_t)(t + 1) * kstep;
;             const char* a2 = last ? nA : cA + (size_t)(t + 2) * kstep; const char* b2 = last ? nB : cB + (size_t)(t + 2) * kstep;
;             const char* a3 = a2 + kstep; const char* b3 = b2 + kstep;
;             if (last && has_next) S.a_ready(nxt);
;             if constexpr (SP2) {
;             PG8_LDB(B0, 0, 0); PG8_LDB(B1, 0, 1); PG8_SCHED; PG8_LDA(At, 0, 0); PG8_STAGEA(PG8_SA(1, 1), a1 + hstep, voffA);
;             PG8_WAIT_V(8); PG8_WAIT_L(0); PG8_BAR; PG8_MMA(0, 0, At, B0); PG8_MMA(0, 1, At, B1); PG8_BAR; PG8_SCHED;
;             PG8_LDA(At, 0, 1); PG8_STAGE(PG8_SB(0, 0), b2, voffB); PG8_STAGE(PG8_SB(0, 1), b2 + hstep, voffB); PG8_STAGEA(PG8_SA(0, 0), a2, voffA);
;             PG8_WAIT_V(8); PG8_WAIT_L(0); PG8_BAR; PG8_MMA(1, 0, At, B0); PG8_MMA(1, 1, At, B1); PG8_BAR; PG8_SCHED;
;             PG8_LDB(B0, 1, 0); PG8_LDB(B1, 1, 1); PG8_SCHED; PG8_LDA(At, 1, 0); PG8_STAGEA(PG8_SA(0, 1), a2 + hstep, voffA);
;             PG8_WAIT_V(8); PG8_WAIT_L(0); PG8_BAR; PG8_MMA(0, 0, At, B0); PG8_MMA(0, 1, At, B1); PG8_BAR; PG8_SCHED;
;             PG8_LDA(At, 1, 1); PG8_STAGE(PG8_SB(1, 0), b3, voffB); PG8_STAGE(PG8_SB(1, 1), b3 + hstep, voffB); PG8_STAGEA(PG8_SA(1, 0), a3, voffA);
;             PG8_WAIT_V(8); PG8_WAIT_L(0); PG8_BAR; PG8_MMA(1, 0, At, B0); PG8_MMA(1, 1, At, B1); PG8_BAR; PG8_SCHED;
	s_add_i32 s52, s70, s55
	v_lshl_add_u64 v[140:141], v[140:141], 0, s[8:9]
	s_mov_b32 m0, s52
	ds_read_b128 v[200:203], v145 offset:49152
	ds_read_b128 v[208:211], v145 offset:50176
	ds_read_b128 v[212:215], v145 offset:51200
	ds_read_b128 v[216:219], v145 offset:52224
	ds_read_b128 v[220:223], v145 offset:53248
	ds_read_b128 v[224:227], v145 offset:54272
	ds_read_b128 v[228:231], v145 offset:55296
	ds_read_b128 v[232:235], v145 offset:56320
	global_load_lds_dwordx4 v[140:141], off
	s_add_i32 m0, s52, 0x2000
	s_add_u32 s50, s50, 0x40080
	v_lshl_add_u64 v[140:141], v[190:191], 0, s[8:9]
	s_addc_u32 s51, s51, 0
	s_add_i32 s52, s71, s55
	global_load_lds_dwordx4 v[140:141], off
	v_lshl_add_u64 v[140:141], s[50:51], 0, v[0:1]
	s_mov_b32 m0, s52
	s_nop 0
	global_load_lds_dwordx4 v[140:141], off
	v_lshl_add_u64 v[140:141], s[50:51], 0, v[130:131]
	s_add_i32 m0, s52, 0x2000
	s_nop 0
	global_load_lds_dwordx4 v[140:141], off
	v_lshl_add_u64 v[140:141], v[236:237], 0, s[8:9]
	s_mov_b32 m0, s60
	s_nop 0
	global_load_lds_dwordx4 v[140:141], off
	v_lshl_add_u64 v[140:141], v[238:239], 0, s[8:9]
	s_mov_b32 m0, s61
	s_nop 0
	global_load_lds_dwordx4 v[140:141], off
	s_waitcnt vmcnt(8)
	s_waitcnt lgkmcnt(0)
	s_barrier
	s_setprio 1
	s_waitcnt lgkmcnt(0)
	v_mfma_f32_16x16x32_bf16 v[62:65], v[146:149], v[200:203], v[62:65]
	v_mfma_f32_16x16x32_bf16 v[58:61], v[154:157], v[200:203], v[58:61]
	v_mfma_f32_16x16x32_bf16 v[50:53], v[146:149], v[212:215], v[50:53]
	v_mfma_f32_16x16x32_bf16 v[42:45], v[154:157], v[212:215], v[42:45]
	v_mfma_f32_16x16x32_bf16 v[34:37], v[146:149], v[220:223], v[34:37]
	v_mfma_f32_16x16x32_bf16 v[26:29], v[154:157], v[220:223], v[26:29]
	v_mfma_f32_16x16x32_bf16 v[18:21], v[146:149], v[228:231], v[18:21]
	v_mfma_f32_16x16x32_bf16 v[10:13], v[154:157], v[228:231], v[10:13]
	v_mfma_f32_16x16x32_bf16 v[62:65], v[150:153], v[208:211], v[62:65]
	v_mfma_f32_16x16x32_bf16 v[58:61], v[158:161], v[208:211], v[58:61]
	v_mfma_f32_16x16x32_bf16 v[50:53], v[150:153], v[216:219], v[50:53]
	v_mfma_f32_16x16x32_bf16 v[42:45], v[158:161], v[216:219], v[42:45]
	v_mfma_f32_16x16x32_bf16 v[34:37], v[150:153], v[224:227], v[34:37]
	v_mfma_f32_16x16x32_bf16 v[26:29], v[158:161], v[224:227], v[26:29]
	v_mfma_f32_16x16x32_bf16 v[18:21], v[150:153], v[232:235], v[18:21]
	v_mfma_f32_16x16x32_bf16 v[10:13], v[158:161], v[232:235], v[10:13]
	v_mfma_f32_16x16x32_bf16 v[54:57], v[174:177], v[200:203], v[54:57]
	v_mfma_f32_16x16x32_bf16 v[46:49], v[182:185], v[200:203], v[46:49]
	v_mfma_f32_16x16x32_bf16 v[38:41], v[174:177], v[212:215], v[38:41]
	v_mfma_f32_16x16x32_bf16 v[30:33], v[182:185], v[212:215], v[30:33]
	v_mfma_f32_16x16x32_bf16 v[22:25], v[174:177], v[220:223], v[22:25]
	v_mfma_f32_16x16x32_bf16 v[14:17], v[182:185], v[220:223], v[14:17]
	v_mfma_f32_16x16x32_bf16 v[6:9], v[174:177], v[228:231], v[6:9]
	v_mfma_f32_16x16x32_bf16 v[2:5], v[182:185], v[228:231], v[2:5]
	v_mfma_f32_16x16x32_bf16 v[54:57], v[178:181], v[208:211], v[54:57]
	v_mfma_f32_16x16x32_bf16 v[46:49], v[186:189], v[208:211], v[46:49]
	v_mfma_f32_16x16x32_bf16 v[38:41], v[178:181], v[216:219], v[38:41]
	v_mfma_f32_16x16x32_bf16 v[30:33], v[186:189], v[216:219], v[30:33]
	v_mfma_f32_16x16x32_bf16 v[22:25], v[178:181], v[224:227], v[22:25]
	v_mfma_f32_16x16x32_bf16 v[14:17], v[186:189], v[224:227], v[14:17]
	v_mfma_f32_16x16x32_bf16 v[6:9], v[178:181], v[232:235], v[6:9]
	v_mfma_f32_16x16x32_bf16 v[2:5], v[186:189], v[232:235], v[2:5]
	s_setprio 0
	s_barrier
	s_add_i32 s73, s73, 2
	s_add_u32 s48, s48, 0x100
	s_addc_u32 s49, s49, 0
	s_add_u32 s65, s65, 0x100
	s_addc_u32 s72, s72, 0
.LBB0_443:
	s_add_u32 s50, s48, 0xfffc0080
	s_addc_u32 s51, s49, -1
	s_add_i32 s70, 0, 0x10000
	s_cmp_eq_u32 s73, 12
	s_cselect_b32 s53, s16, s51
	s_cselect_b32 s52, s17, s50
	v_add_u32_e32 v140, s70, v143
	s_cselect_b32 s51, s41, s72
	s_cselect_b32 s50, s43, s65
	s_add_i32 s76, 0, 0x14000
	ds_read_b128 v[146:149], v140
	ds_read_b128 v[150:153], v140 offset:1024
	ds_read_b128 v[154:157], v140 offset:2048
	ds_read_b128 v[158:161], v140 offset:3072
	v_add_u32_e32 v140, s76, v143
	ds_read_b128 v[174:177], v140
	ds_read_b128 v[178:181], v140 offset:1024
	ds_read_b128 v[182:185], v140 offset:2048
	ds_read_b128 v[186:189], v140 offset:3072
	v_lshl_add_u64 v[140:141], s[48:49], 0, v[136:137]
	s_add_i32 m0, s56, 0xc000
	ds_read_b128 v[200:203], v145
	ds_read_b128 v[208:211], v145 offset:1024
	ds_read_b128 v[212:215], v145 offset:2048
	ds_read_b128 v[216:219], v145 offset:3072
	ds_read_b128 v[220:223], v145 offset:4096
	ds_read_b128 v[224:227], v145 offset:5120
	ds_read_b128 v[228:231], v145 offset:6144
	ds_read_b128 v[232:235], v145 offset:7168
	global_load_lds_dwordx4 v[140:141], off
	v_lshl_add_u64 v[140:141], s[48:49], 0, v[138:139]
	s_add_i32 m0, s56, 0xe000
	s_nop 0
	global_load_lds_dwordx4 v[140:141], off
	s_waitcnt vmcnt(8)
	s_waitcnt lgkmcnt(0)
	s_barrier
; #define PG8_STAGE(bufoff, gbase, voff) do { _Pragma("unroll") for (int _i = 0; _i < 2; ++_i) \
;         __builtin_amdgcn_global_load_lds((const unsigned*)((const char*)(gbase) + (voff)[_i]), (PG8_LAS unsigned*)(lds + (bufoff) + ldsw + _i * 8192), 16, 0, 0); } while (0)
; #define PG8_STAGEA(bufoff, gbase, voff) do { _Pragma("unroll") for (int _i = 0; _i < 2; ++_i) \
;         __builtin_amdgcn_global_load_lds((const unsigned*)((const char*)(gbase) + (voff)[_i]), (PG8_LAS unsigned*)(lds + (bufoff) + ldsw + _i * 8192), 16, 0, A_AUX); } while (0)
; #define PG8_LDA(dst, b, h) do { _Pragma("unroll") for (int m = 0; m < 4; ++m) _Pragma("unroll") for (int k = 0; k < 2; ++k) dst[m][k] = *(const PG8_LAS bf16x8*)(lds + PG8_SA(b, h) + aoff + m * 2048 + k * 1024); } while (0)
; #define PG8_LDB(dst, b, h) do { _Pragma("unroll") for (int n = 0; n < 2; ++n) _Pragma("unroll") for (int k = 0; k < 2; ++k) dst[n][k] = *(const PG8_LAS bf16x8*)(lds + PG8_SB(b, h) + boff + n * 2048 + k * 1024); } while (0)
; #define PG8_MMA(ai, bj, At, Bt) do { __builtin_amdgcn_s_setprio(1); _Pragma("unroll") for (int m = 0; m < 4; ++m) _Pragma("unroll") for (int n = 0; n < 2; ++n) _Pragma("unroll") for (int k = 0; k < 2; ++k) \
;         acc[ai][bj][m][n] = __builtin_amdgcn_mfma_f32_16x16x32_bf16(Bt[n][k], At[m][k], acc[ai][bj][m][n], 0, 0, 0); __builtin_amdgcn_s_setprio(0); } while (0)
; #define PG8_WAIT_V(n) asm volatile("s_waitcnt vmcnt(" #n ")" ::: "memory")
; #define PG8_WAIT_L(n) asm volatile("s_waitcnt lgkmcnt(" #n ")" ::: "memory")
; #define PG8_BAR __builtin_amdgcn_s_barrier()
; #define PG8_SCHED __builtin_amdgcn_sched_barrier(0)
;     ...
;             PG8_LDB(B0, 0, 0); PG8_LDB(B1, 0, 1); PG8_SCHED; PG8_LDA(At, 0, 0); PG8_STAGEA(PG8_SA(1, 1), a1 + hstep, voffA);
;             PG8_WAIT_V(8); PG8_WAIT_L(0); PG8_BAR; PG8_MMA(0, 0, At, B0); PG8_MMA(0, 1, At, B1); PG8_BAR; PG8_SCHED;
;             PG8_LDA(At, 0, 1); PG8_STAGE(PG8_SB(0, 0), b2, voffB); PG8_STAGE(PG8_SB(0, 1), b2 + hstep, voffB); PG8_STAGEA(PG8_SA(0, 0), a2, voffA);
;             PG8_WAIT_V(8); PG8_WAIT_L(0); PG8_BAR; PG8_MMA(1, 0, At, B0); PG8_MMA(1, 1, At, B1); PG8_BAR; PG8_SCHED;
;             PG8_LDB(B0, 1, 0); PG8_LDB(B1, 1, 1); PG8_SCHED; PG8_LDA(At, 1, 0); PG8_STAGEA(PG8_SA(0, 1), a2 + hstep, voffA);
;             PG8_WAIT_V(8); PG8_WAIT_L(0); PG8_BAR; PG8_MMA(0, 0, At, B0); PG8_MMA(0, 1, At, B1); PG8_BAR; PG8_SCHED;
	s_setprio 1
	s_waitcnt lgkmcnt(0)
	v_mfma_f32_16x16x32_bf16 v[126:129], v[146:149], v[200:203], v[126:129]
	v_mfma_f32_16x16x32_bf16 v[122:125], v[154:157], v[200:203], v[122:125]
	v_mfma_f32_16x16x32_bf16 v[114:117], v[146:149], v[212:215], v[114:117]
	v_mfma_f32_16x16x32_bf16 v[106:109], v[154:157], v[212:215], v[106:109]
	v_mfma_f32_16x16x32_bf16 v[98:101], v[146:149], v[220:223], v[98:101]
	v_mfma_f32_16x16x32_bf16 v[90:93], v[154:157], v[220:223], v[90:93]
	v_mfma_f32_16x16x32_bf16 v[82:85], v[146:149], v[228:231], v[82:85]
	v_mfma_f32_16x16x32_bf16 v[74:77], v[154:157], v[228:231], v[74:77]
	v_mfma_f32_16x16x32_bf16 v[126:129], v[150:153], v[208:211], v[126:129]
	v_mfma_f32_16x16x32_bf16 v[122:125], v[158:161], v[208:211], v[122:125]
	v_mfma_f32_16x16x32_bf16 v[114:117], v[150:153], v[216:219], v[114:117]
	v_mfma_f32_16x16x32_bf16 v[106:109], v[158:161], v[216:219], v[106:109]
	v_mfma_f32_16x16x32_bf16 v[98:101], v[150:153], v[224:227], v[98:101]
	v_mfma_f32_16x16x32_bf16 v[90:93], v[158:161], v[224:227], v[90:93]
	v_mfma_f32_16x16x32_bf16 v[82:85], v[150:153], v[232:235], v[82:85]
	v_mfma_f32_16x16x32_bf16 v[74:77], v[158:161], v[232:235], v[74:77]
	v_mfma_f32_16x16x32_bf16 v[118:121], v[174:177], v[200:203], v[118:121]
	v_mfma_f32_16x16x32_bf16 v[110:113], v[182:185], v[200:203], v[110:113]
	v_mfma_f32_16x16x32_bf16 v[102:105], v[174:177], v[212:215], v[102:105]
	v_mfma_f32_16x16x32_bf16 v[94:97], v[182:185], v[212:215], v[94:97]
	v_mfma_f32_16x16x32_bf16 v[86:89], v[174:177], v[220:223], v[86:89]
	v_mfma_f32_16x16x32_bf16 v[78:81], v[182:185], v[220:223], v[78:81]
	v_mfma_f32_16x16x32_bf16 v[70:73], v[174:177], v[228:231], v[70:73]
	v_mfma_f32_16x16x32_bf16 v[66:69], v[182:185], v[228:231], v[66:69]
	v_mfma_f32_16x16x32_bf16 v[118:121], v[178:181], v[208:211], v[118:121]
	v_mfma_f32_16x16x32_bf16 v[110:113], v[186:189], v[208:211], v[110:113]
	v_mfma_f32_16x16x32_bf16 v[102:105], v[178:181], v[216:219], v[102:105]
	v_mfma_f32_16x16x32_bf16 v[94:97], v[186:189], v[216:219], v[94:97]
	v_mfma_f32_16x16x32_bf16 v[86:89], v[178:181], v[224:227], v[86:89]
	v_mfma_f32_16x16x32_bf16 v[78:81], v[186:189], v[224:227], v[78:81]
	v_mfma_f32_16x16x32_bf16 v[70:73], v[178:181], v[232:235], v[70:73]
	v_mfma_f32_16x16x32_bf16 v[66:69], v[186:189], v[232:235], v[66:69]
	s_setprio 0
	s_barrier
	s_add_i32 s70, s70, s55
	v_lshl_add_u64 v[140:141], s[50:51], 0, v[0:1]
	s_mov_b32 m0, s70
	ds_read_b128 v[200:203], v145 offset:16384
	ds_read_b128 v[208:211], v145 offset:17408
	ds_read_b128 v[212:215], v145 offset:18432
	ds_read_b128 v[216:219], v145 offset:19456
	ds_read_b128 v[220:223], v145 offset:20480
	ds_read_b128 v[224:227], v145 offset:21504
	ds_read_b128 v[228:231], v145 offset:22528
	ds_read_b128 v[232:235], v145 offset:23552
	global_load_lds_dwordx4 v[140:141], off
	s_add_i32 m0, s70, 0x2000
	s_add_u32 s70, s50, 0x40000
	v_lshl_add_u64 v[190:191], s[50:51], 0, v[130:131]
	s_addc_u32 s71, s51, 0
	s_add_i32 s76, s76, s55
	global_load_lds_dwordx4 v[190:191], off
	v_lshl_add_u64 v[236:237], s[70:71], 0, v[0:1]
	s_mov_b32 m0, s76
	v_lshl_add_u64 v[238:239], s[52:53], 0, v[132:133]
	global_load_lds_dwordx4 v[236:237], off
	v_lshl_add_u64 v[236:237], s[70:71], 0, v[130:131]
	s_add_i32 m0, s76, 0x2000
	s_nop 0
	global_load_lds_dwordx4 v[236:237], off
	v_lshl_add_u64 v[236:237], s[52:53], 0, v[134:135]
	s_mov_b32 m0, s56
	s_nop 0
	global_load_lds_dwordx4 v[236:237], off
	s_mov_b32 m0, s57
	s_nop 0
	global_load_lds_dwordx4 v[238:239], off
	s_waitcnt vmcnt(8)
	s_waitcnt lgkmcnt(0)
	s_barrier
	s_setprio 1
	s_waitcnt lgkmcnt(0)
	v_mfma_f32_16x16x32_bf16 v[62:65], v[146:149], v[200:203], v[62:65]
	v_mfma_f32_16x16x32_bf16 v[58:61], v[154:157], v[200:203], v[58:61]
	v_mfma_f32_16x16x32_bf16 v[50:53], v[146:149], v[212:215], v[50:53]
	v_mfma_f32_16x16x32_bf16 v[42:45], v[154:157], v[212:215], v[42:45]
	v_mfma_f32_16x16x32_bf16 v[34:37], v[146:149], v[220:223], v[34:37]
	v_mfma_f32_16x16x32_bf16 v[26:29], v[154:157], v[220:223], v[26:29]
	v_mfma_f32_16x16x32_bf16 v[18:21], v[146:149], v[228:231], v[18:21]
	v_mfma_f32_16x16x32_bf16 v[10:13], v[154:157], v[228:231], v[10:13]
	v_mfma_f32_16x16x32_bf16 v[62:65], v[150:153], v[208:211], v[62:65]
	v_mfma_f32_16x16x32_bf16 v[58:61], v[158:161], v[208:211], v[58:61]
	v_mfma_f32_16x16x32_bf16 v[50:53], v[150:153], v[216:219], v[50:53]
	v_mfma_f32_16x16x32_bf16 v[42:45], v[158:161], v[216:219], v[42:45]
	v_mfma_f32_16x16x32_bf16 v[34:37], v[150:153], v[224:227], v[34:37]
	v_mfma_f32_16x16x32_bf16 v[26:29], v[158:161], v[224:227], v[26:29]
	v_mfma_f32_16x16x32_bf16 v[18:21], v[150:153], v[232:235], v[18:21]
	v_mfma_f32_16x16x32_bf16 v[10:13], v[158:161], v[232:235], v[10:13]
	v_mfma_f32_16x16x32_bf16 v[54:57], v[174:177], v[200:203], v[54:57]
	v_mfma_f32_16x16x32_bf16 v[46:49], v[182:185], v[200:203], v[46:49]
	v_mfma_f32_16x16x32_bf16 v[38:41], v[174:177], v[212:215], v[38:41]
	v_mfma_f32_16x16x32_bf16 v[30:33], v[182:185], v[212:215], v[30:33]
	v_mfma_f32_16x16x32_bf16 v[22:25], v[174:177], v[220:223], v[22:25]
	v_mfma_f32_16x16x32_bf16 v[14:17], v[182:185], v[220:223], v[14:17]
	v_mfma_f32_16x16x32_bf16 v[6:9], v[174:177], v[228:231], v[6:9]
	v_mfma_f32_16x16x32_bf16 v[2:5], v[182:185], v[228:231], v[2:5]
	v_mfma_f32_16x16x32_bf16 v[54:57], v[178:181], v[208:211], v[54:57]
	v_mfma_f32_16x16x32_bf16 v[46:49], v[186:189], v[208:211], v[46:49]
	v_mfma_f32_16x16x32_bf16 v[38:41], v[178:181], v[216:219], v[38:41]
	v_mfma_f32_16x16x32_bf16 v[30:33], v[186:189], v[216:219], v[30:33]
	v_mfma_f32_16x16x32_bf16 v[22:25], v[178:181], v[224:227], v[22:25]
	v_mfma_f32_16x16x32_bf16 v[14:17], v[186:189], v[224:227], v[14:17]
	v_mfma_f32_16x16x32_bf16 v[6:9], v[178:181], v[232:235], v[6:9]
	v_mfma_f32_16x16x32_bf16 v[2:5], v[186:189], v[232:235], v[2:5]
	s_setprio 0
	s_barrier
; #define PG8_STAGEA(bufoff, gbase, voff) do { _Pragma("unroll") for (int _i = 0; _i < 2; ++_i) \
;         __builtin_amdgcn_global_load_lds((const unsigned*)((const char*)(gbase) + (voff)[_i]), (PG8_LAS unsigned*)(lds + (bufoff) + ldsw + _i * 8192), 16, 0, A_AUX); } while (0)
; #define PG8_LDA(dst, b, h) do { _Pragma("unroll") for (int m = 0; m < 4; ++m) _Pragma("unroll") for (int k = 0; k < 2; ++k) dst[m][k] = *(const PG8_LAS bf16x8*)(lds + PG8_SA(b, h) + aoff + m * 2048 + k * 1024); } while (0)
; #define PG8_LDB(dst, b, h) do { _Pragma("unroll") for (int n = 0; n < 2; ++n) _Pragma("unroll") for (int k = 0; k < 2; ++k) dst[n][k] = *(const PG8_LAS bf16x8*)(lds + PG8_SB(b, h) + boff + n * 2048 + k * 1024); } while (0)
; #define PG8_MMA(ai, bj, At, Bt) do { __builtin_amdgcn_s_setprio(1); _Pragma("unroll") for (int m = 0; m < 4; ++m) _Pragma("unroll") for (int n = 0; n < 2; ++n) _Pragma("unroll") for (int k = 0; k < 2; ++k) \
;         acc[ai][bj][m][n] = __builtin_amdgcn_mfma_f32_16x16x32_bf16(Bt[n][k], At[m][k], acc[ai][bj][m][n], 0, 0, 0); __builtin_amdgcn_s_setprio(0); } while (0)
; #define PG8_WAIT_V(n) asm volatile("s_waitcnt vmcnt(" #n ")" ::: "memory")
; #define PG8_WAIT_L(n) asm volatile("s_waitcnt lgkmcnt(" #n ")" ::: "memory")
; #define PG8_BAR __builtin_amdgcn_s_barrier()
; #define PG8_SCHED __builtin_amdgcn_sched_barrier(0)
;     ...
;             PG8_LDB(B0, 1, 0); PG8_LDB(B1, 1, 1); PG8_SCHED; PG8_LDA(At, 1, 0); PG8_STAGEA(PG8_SA(0, 1), a2 + hstep, voffA);
;             PG8_WAIT_V(8); PG8_WAIT_L(0); PG8_BAR; PG8_MMA(0, 0, At, B0); PG8_MMA(0, 1, At, B1); PG8_BAR; PG8_SCHED;
	s_add_i32 s70, 0, 0x18000
	s_add_i32 s71, 0, 0x1c000
	v_add_u32_e32 v158, s70, v143
	v_add_u32_e32 v186, s71, v143
	ds_read_b128 v[146:149], v158
	ds_read_b128 v[150:153], v158 offset:1024
	ds_read_b128 v[154:157], v158 offset:2048
	ds_read_b128 v[158:161], v158 offset:3072
	ds_read_b128 v[174:177], v186
	ds_read_b128 v[178:181], v186 offset:1024
	ds_read_b128 v[182:185], v186 offset:2048
	ds_read_b128 v[186:189], v186 offset:3072
	s_add_u32 s52, s52, 0x40000
	s_addc_u32 s53, s53, 0
	s_mov_b32 m0, s58
	v_lshl_add_u64 v[240:241], s[52:53], 0, v[134:135]
	ds_read_b128 v[200:203], v145 offset:32768
	ds_read_b128 v[208:211], v145 offset:33792
	ds_read_b128 v[212:215], v145 offset:34816
	ds_read_b128 v[216:219], v145 offset:35840
	ds_read_b128 v[220:223], v145 offset:36864
	ds_read_b128 v[224:227], v145 offset:37888
	ds_read_b128 v[228:231], v145 offset:38912
	ds_read_b128 v[232:235], v145 offset:39936
	global_load_lds_dwordx4 v[240:241], off
	v_lshl_add_u64 v[240:241], s[52:53], 0, v[132:133]
	s_mov_b32 m0, s59
	s_nop 0
	global_load_lds_dwordx4 v[240:241], off
	s_waitcnt vmcnt(8)
	s_waitcnt lgkmcnt(0)
	s_barrier
	s_setprio 1
	s_waitcnt lgkmcnt(0)
	v_mfma_f32_16x16x32_bf16 v[126:129], v[146:149], v[200:203], v[126:129]
	v_mfma_f32_16x16x32_bf16 v[122:125], v[154:157], v[200:203], v[122:125]
	v_mfma_f32_16x16x32_bf16 v[114:117], v[146:149], v[212:215], v[114:117]
	v_mfma_f32_16x16x32_bf16 v[106:109], v[154:157], v[212:215], v[106:109]
	v_mfma_f32_16x16x32_bf16 v[98:101], v[146:149], v[220:223], v[98:101]
	v_mfma_f32_16x16x32_bf16 v[90:93], v[154:157], v[220:223], v[90:93]
	v_mfma_f32_16x16x32_bf16 v[82:85], v[146:149], v[228:231], v[82:85]
	v_mfma_f32_16x16x32_bf16 v[74:77], v[154:157], v[228:231], v[74:77]
	v_mfma_f32_16x16x32_bf16 v[126:129], v[150:153], v[208:211], v[126:129]
	v_mfma_f32_16x16x32_bf16 v[122:125], v[158:161], v[208:211], v[122:125]
	v_mfma_f32_16x16x32_bf16 v[114:117], v[150:153], v[216:219], v[114:117]
	v_mfma_f32_16x16x32_bf16 v[106:109], v[158:161], v[216:219], v[106:109]
	v_mfma_f32_16x16x32_bf16 v[98:101], v[150:153], v[224:227], v[98:101]
	v_mfma_f32_16x16x32_bf16 v[90:93], v[158:161], v[224:227], v[90:93]
	v_mfma_f32_16x16x32_bf16 v[82:85], v[150:153], v[232:235], v[82:85]
	v_mfma_f32_16x16x32_bf16 v[74:77], v[158:161], v[232:235], v[74:77]
	v_mfma_f32_16x16x32_bf16 v[118:121], v[174:177], v[200:203], v[118:121]
	v_mfma_f32_16x16x32_bf16 v[110:113], v[182:185], v[200:203], v[110:113]
	v_mfma_f32_16x16x32_bf16 v[102:105], v[174:177], v[212:215], v[102:105]
	v_mfma_f32_16x16x32_bf16 v[94:97], v[182:185], v[212:215], v[94:97]
	v_mfma_f32_16x16x32_bf16 v[86:89], v[174:177], v[220:223], v[86:89]
	v_mfma_f32_16x16x32_bf16 v[78:81], v[182:185], v[220:223], v[78:81]
	v_mfma_f32_16x16x32_bf16 v[70:73], v[174:177], v[228:231], v[70:73]
	v_mfma_f32_16x16x32_bf16 v[66:69], v[182:185], v[228:231], v[66:69]
	v_mfma_f32_16x16x32_bf16 v[118:121], v[178:181], v[208:211], v[118:121]
	v_mfma_f32_16x16x32_bf16 v[110:113], v[186:189], v[208:211], v[110:113]
	v_mfma_f32_16x16x32_bf16 v[102:105], v[178:181], v[216:219], v[102:105]
	v_mfma_f32_16x16x32_bf16 v[94:97], v[186:189], v[216:219], v[94:97]
	v_mfma_f32_16x16x32_bf16 v[86:89], v[178:181], v[224:227], v[86:89]
	v_mfma_f32_16x16x32_bf16 v[78:81], v[186:189], v[224:227], v[78:81]
	v_mfma_f32_16x16x32_bf16 v[70:73], v[178:181], v[232:235], v[70:73]
	v_mfma_f32_16x16x32_bf16 v[66:69], v[186:189], v[232:235], v[66:69]
	s_setprio 0
	s_barrier
; #define PG8_STAGE(bufoff, gbase, voff) do { _Pragma("unroll") for (int _i = 0; _i < 2; ++_i) \
;         __builtin_amdgcn_global_load_lds((const unsigned*)((const char*)(gbase) + (voff)[_i]), (PG8_LAS unsigned*)(lds + (bufoff) + ldsw + _i * 8192), 16, 0, 0); } while (0)
; #define PG8_STAGEA(bufoff, gbase, voff) do { _Pragma("unroll") for (int _i = 0; _i < 2; ++_i) \
;         __builtin_amdgcn_global_load_lds((const unsigned*)((const char*)(gbase) + (voff)[_i]), (PG8_LAS unsigned*)(lds + (bufoff) + ldsw + _i * 8192), 16, 0, A_AUX); } while (0)
; #define PG8_LDA(dst, b, h) do { _Pragma("unroll") for (int m = 0; m < 4; ++m) _Pragma("unroll") for (int k = 0; k < 2; ++k) dst[m][k] = *(const PG8_LAS bf16x8*)(lds + PG8_SA(b, h) + aoff + m * 2048 + k * 1024); } while (0)
; #define PG8_WAIT_V(n) asm volatile("s_waitcnt vmcnt(" #n ")" ::: "memory")
; #define PG8_BAR __builtin_amdgcn_s_barrier()
;     ...
;         for (int t = 0; t < nt; t += 2) {
;             const bool last = (t == nt - 2);
;             const char* a1 = cA + (size_t)(t + 1) * kstep;
;             const char* a2 = last ? nA : cA + (size_t)(t + 2) * kstep; const char* b2 = last ? nB : cB + (size_t)(t + 2) * kstep;
;             const char* a3 = a2 + kstep; const char* b3 = b2 + kstep;
;             if (last && has_next) S.a_ready(nxt);
;             if constexpr (SP2) {
;             PG8_LDB(B0, 0, 0); PG8_LDB(B1, 0, 1); PG8_SCHED; PG8_LDA(At, 0, 0); PG8_STAGEA(PG8_SA(1, 1), a1 + hstep, voffA);
;             PG8_WAIT_V(8); PG8_WAIT_L(0); PG8_BAR; PG8_MMA(0, 0, At, B0); PG8_MMA(0, 1, At, B1); PG8_BAR; PG8_SCHED;
;             PG8_LDA(At, 0, 1); PG8_STAGE(PG8_SB(0, 0), b2, voffB); PG8_STAGE(PG8_SB(0, 1), b2 + hstep, voffB); PG8_STAGEA(PG8_SA(0, 0), a2, voffA);
;             PG8_WAIT_V(8); PG8_WAIT_L(0); PG8_BAR; PG8_MMA(1, 0, At, B0); PG8_MMA(1, 1, At, B1); PG8_BAR; PG8_SCHED;
;             PG8_LDB(B0, 1, 0); PG8_LDB(B1, 1, 1); PG8_SCHED; PG8_LDA(At, 1, 0); PG8_STAGEA(PG8_SA(0, 1), a2 + hstep, voffA);
;             PG8_WAIT_V(8); PG8_WAIT_L(0); PG8_BAR; PG8_MMA(0, 0, At, B0); PG8_MMA(0, 1, At, B1); PG8_BAR; PG8_SCHED;
;             PG8_LDA(At, 1, 1); PG8_STAGE(PG8_SB(1, 0), b3, voffB); PG8_STAGE(PG8_SB(1, 1), b3 + hstep, voffB); PG8_STAGEA(PG8_SA(1, 0), a3, voffA);
;             PG8_WAIT_V(8); PG8_WAIT_L(0); PG8_BAR; PG8_MMA(1, 0, At, B0); PG8_MMA(1, 1, At, B1); PG8_BAR; PG8_SCHED;
	s_add_i32 s52, s70, s55
	v_lshl_add_u64 v[140:141], v[140:141], 0, s[8:9]
	s_mov_b32 m0, s52
	ds_read_b128 v[200:203], v145 offset:49152
	ds_read_b128 v[208:211], v145 offset:50176
	ds_read_b128 v[212:215], v145 offset:51200
	ds_read_b128 v[216:219], v145 offset:52224
	ds_read_b128 v[220:223], v145 offset:53248
	ds_read_b128 v[224:227], v145 offset:54272
	ds_read_b128 v[228:231], v145 offset:55296
	ds_read_b128 v[232:235], v145 offset:56320
	global_load_lds_dwordx4 v[140:141], off
	s_add_i32 m0, s52, 0x2000
	s_add_u32 s50, s50, 0x40080
	v_lshl_add_u64 v[140:141], v[190:191], 0, s[8:9]
	s_addc_u32 s51, s51, 0
	s_add_i32 s52, s71, s55
	global_load_lds_dwordx4 v[140:141], off
	v_lshl_add_u64 v[140:141], s[50:51], 0, v[0:1]
	s_mov_b32 m0, s52
	s_nop 0
	global_load_lds_dwordx4 v[140:141], off
	v_lshl_add_u64 v[140:141], s[50:51], 0, v[130:131]
	s_add_i32 m0, s52, 0x2000
	s_nop 0
	global_load_lds_dwordx4 v[140:141], off
	v_lshl_add_u64 v[140:141], v[236:237], 0, s[8:9]
	s_mov_b32 m0, s60
	s_nop 0
	global_load_lds_dwordx4 v[140:141], off
	v_lshl_add_u64 v[140:141], v[238:239], 0, s[8:9]
	s_mov_b32 m0, s61
	s_nop 0
	global_load_lds_dwordx4 v[140:141], off
	s_waitcnt vmcnt(8)
	s_waitcnt lgkmcnt(0)
	s_barrier
	s_setprio 1
	s_waitcnt lgkmcnt(0)
	v_mfma_f32_16x16x32_bf16 v[62:65], v[146:149], v[200:203], v[62:65]
	v_mfma_f32_16x16x32_bf16 v[58:61], v[154:157], v[200:203], v[58:61]
	v_mfma_f32_16x16x32_bf16 v[50:53], v[146:149], v[212:215], v[50:53]
	v_mfma_f32_16x16x32_bf16 v[42:45], v[154:157], v[212:215], v[42:45]
	v_mfma_f32_16x16x32_bf16 v[34:37], v[146:149], v[220:223], v[34:37]
	v_mfma_f32_16x16x32_bf16 v[26:29], v[154:157], v[220:223], v[26:29]
	v_mfma_f32_16x16x32_bf16 v[18:21], v[146:149], v[228:231], v[18:21]
	v_mfma_f32_16x16x32_bf16 v[10:13], v[154:157], v[228:231], v[10:13]
	v_mfma_f32_16x16x32_bf16 v[62:65], v[150:153], v[208:211], v[62:65]
	v_mfma_f32_16x16x32_bf16 v[58:61], v[158:161], v[208:211], v[58:61]
	v_mfma_f32_16x16x32_bf16 v[50:53], v[150:153], v[216:219], v[50:53]
	v_mfma_f32_16x16x32_bf16 v[42:45], v[158:161], v[216:219], v[42:45]
	v_mfma_f32_16x16x32_bf16 v[34:37], v[150:153], v[224:227], v[34:37]
	v_mfma_f32_16x16x32_bf16 v[26:29], v[158:161], v[224:227], v[26:29]
	v_mfma_f32_16x16x32_bf16 v[18:21], v[150:153], v[232:235], v[18:21]
	v_mfma_f32_16x16x32_bf16 v[10:13], v[158:161], v[232:235], v[10:13]
	v_mfma_f32_16x16x32_bf16 v[54:57], v[174:177], v[200:203], v[54:57]
	v_mfma_f32_16x16x32_bf16 v[46:49], v[182:185], v[200:203], v[46:49]
	v_mfma_f32_16x16x32_bf16 v[38:41], v[174:177], v[212:215], v[38:41]
	v_mfma_f32_16x16x32_bf16 v[30:33], v[182:185], v[212:215], v[30:33]
	v_mfma_f32_16x16x32_bf16 v[22:25], v[174:177], v[220:223], v[22:25]
	v_mfma_f32_16x16x32_bf16 v[14:17], v[182:185], v[220:223], v[14:17]
	v_mfma_f32_16x16x32_bf16 v[6:9], v[174:177], v[228:231], v[6:9]
	v_mfma_f32_16x16x32_bf16 v[2:5], v[182:185], v[228:231], v[2:5]
	v_mfma_f32_16x16x32_bf16 v[54:57], v[178:181], v[208:211], v[54:57]
	v_mfma_f32_16x16x32_bf16 v[46:49], v[186:189], v[208:211], v[46:49]
	v_mfma_f32_16x16x32_bf16 v[38:41], v[178:181], v[216:219], v[38:41]
	v_mfma_f32_16x16x32_bf16 v[30:33], v[186:189], v[216:219], v[30:33]
	v_mfma_f32_16x16x32_bf16 v[22:25], v[178:181], v[224:227], v[22:25]
	v_mfma_f32_16x16x32_bf16 v[14:17], v[186:189], v[224:227], v[14:17]
	v_mfma_f32_16x16x32_bf16 v[6:9], v[178:181], v[232:235], v[6:9]
	v_mfma_f32_16x16x32_bf16 v[2:5], v[186:189], v[232:235], v[2:5]
	s_setprio 0
	s_barrier
	s_add_i32 s73, s73, 2
	s_add_u32 s48, s48, 0x100
	s_addc_u32 s49, s49, 0
	s_add_u32 s65, s65, 0x100
	s_addc_u32 s72, s72, 0
	s_cmp_gt_u32 s73, 13
	s_cbranch_scc0 .LBB0_443
	s_and_b64 vcc, exec, s[36:37]
	s_cbranch_vccz .LBB0_446
	s_barrier

; #define PG8_STAGE(bufoff, gbase, voff) do { _Pragma("unroll") for (int _i = 0; _i < 2; ++_i) \
;         __builtin_amdgcn_global_load_lds((const unsigned*)((const char*)(gbase) + (voff)[_i]), (PG8_LAS unsigned*)(lds + (bufoff) + ldsw + _i * 8192), 16, 0, 0); } while (0)
; #define PG8_STAGEA(bufoff, gbase, voff) do { _Pragma("unroll") for (int _i = 0; _i < 2; ++_i) \
;         __builtin_amdgcn_global_load_lds((const unsigned*)((const char*)(gbase) + (voff)[_i]), (PG8_LAS unsigned*)(lds + (bufoff) + ldsw + _i * 8192), 16, 0, A_AUX); } while (0)
; #define PG8_LDA(dst, b, h) do { _Pragma("unroll") for (int m = 0; m < 4; ++m) _Pragma("unroll") for (int k = 0; k < 2; ++k) dst[m][k] = *(const PG8_LAS bf16x8*)(lds + PG8_SA(b, h) + aoff + m * 2048 + k * 1024); } while (0)
; #define PG8_LDB(dst, b, h) do { _Pragma("unroll") for (int n = 0; n < 2; ++n) _Pragma("unroll") for (int k = 0; k < 2; ++k) dst[n][k] = *(const PG8_LAS bf16x8*)(lds + PG8_SB(b, h) + boff + n * 2048 + k * 1024); } while (0)
; #define PG8_WAIT_V(n) asm volatile("s_waitcnt vmcnt(" #n ")" ::: "memory")
; #define PG8_WAIT_L(n) asm volatile("s_waitcnt lgkmcnt(" #n ")" ::: "memory")
; #define PG8_BAR __builtin_amdgcn_s_barrier()
;     ...
;         const bool has_next = S.next(ui + 1, nxt);
;         const char* nA = has_next ? (const char*)g.A + (size_t)nxt.pm * tstep : cA; const char* nB = has_next ? (const char*)g.Bt + (size_t)nxt.pn * tstep : cB;
;         for (int t = 0; t < nt; t += 2) {
;             const bool last = (t == nt - 2);
;             const char* a1 = cA + (size_t)(t + 1) * kstep;
;             const char* a2 = last ? nA : cA + (size_t)(t + 2) * kstep; const char* b2 = last ? nB : cB + (size_t)(t + 2) * kstep;
;             const char* a3 = a2 + kstep; const char* b3 = b2 + kstep;
;             if (last && has_next) S.a_ready(nxt);
;             if constexpr (SP2) {
;             PG8_LDB(B0, 0, 0); PG8_LDB(B1, 0, 1); PG8_SCHED; PG8_LDA(At, 0, 0); PG8_STAGEA(PG8_SA(1, 1), a1 + hstep, voffA);
;             PG8_WAIT_V(8); PG8_WAIT_L(0); PG8_BAR; PG8_MMA(0, 0, At, B0); PG8_MMA(0, 1, At, B1); PG8_BAR; PG8_SCHED;
;             PG8_LDA(At, 0, 1); PG8_STAGE(PG8_SB(0, 0), b2, voffB); PG8_STAGE(PG8_SB(0, 1), b2 + hstep, voffB); PG8_STAGEA(PG8_SA(0, 0), a2, voffA);
;             PG8_WAIT_V(8); PG8_WAIT_L(0); PG8_BAR; PG8_MMA(1, 0, At, B0); PG8_MMA(1, 1, At, B1); PG8_BAR; PG8_SCHED;
.LBB0_579:
	s_ashr_i32 s45, s44, 31
	s_lshl_b64 s[16:17], s[44:45], 19
	s_add_u32 s46, s97, s16
	s_addc_u32 s47, s29, s17
	s_and_b64 s[16:17], s[40:41], exec
	s_cselect_b32 s16, s47, s51
	s_cselect_b32 s17, s46, s50
	s_ashr_i32 s43, s42, 31
	s_lshl_b64 s[48:49], s[42:43], 19
	s_add_u32 s48, s23, s48
	s_addc_u32 s49, s56, s49
	s_and_b64 s[54:55], s[40:41], exec
	s_cselect_b32 s43, s49, s53
	s_cselect_b32 s45, s48, s52
	s_add_u32 s50, s50, 0x40080
	s_addc_u32 s51, s51, 0
	s_add_u32 s73, s52, 0x100
	s_addc_u32 s76, s53, 0
	s_mov_b32 vcc_lo, -2
	s_add_u32 s52, s50, 0xfffc0080
	s_addc_u32 s53, s51, -1
	s_add_i32 s70, 0, 0x10000
	s_cmp_eq_u32 vcc_lo, 12
	s_cselect_b32 s55, s16, s53
	s_cselect_b32 s54, s17, s52
	v_add_u32_e32 v140, s70, v143
	s_cselect_b32 s53, s43, s76
	s_cselect_b32 s52, s45, s73
	s_add_i32 vcc_hi, 0, 0x14000
	ds_read_b128 v[146:149], v140
	ds_read_b128 v[150:153], v140 offset:1024
	ds_read_b128 v[154:157], v140 offset:2048
	ds_read_b128 v[158:161], v140 offset:3072
	v_add_u32_e32 v140, vcc_hi, v143
	ds_read_b128 v[174:177], v140
	ds_read_b128 v[178:181], v140 offset:1024
	ds_read_b128 v[182:185], v140 offset:2048
	ds_read_b128 v[186:189], v140 offset:3072
	v_lshl_add_u64 v[140:141], s[50:51], 0, v[136:137]
	s_add_i32 m0, s58, 0xc000
	ds_read_b128 v[200:203], v145
	ds_read_b128 v[208:211], v145 offset:1024
	ds_read_b128 v[212:215], v145 offset:2048
	ds_read_b128 v[216:219], v145 offset:3072
	ds_read_b128 v[220:223], v145 offset:4096
	ds_read_b128 v[224:227], v145 offset:5120
	ds_read_b128 v[228:231], v145 offset:6144
	ds_read_b128 v[232:235], v145 offset:7168
	global_load_lds_dwordx4 v[140:141], off
	v_lshl_add_u64 v[140:141], s[50:51], 0, v[138:139]
	s_add_i32 m0, s58, 0xe000
	s_nop 0
	global_load_lds_dwordx4 v[140:141], off
	s_waitcnt vmcnt(8)
	s_waitcnt lgkmcnt(0)
	s_barrier
	s_setprio 1
	s_waitcnt lgkmcnt(0)
	v_mfma_f32_16x16x32_bf16 v[126:129], v[146:149], v[200:203], 0
	v_mfma_f32_16x16x32_bf16 v[122:125], v[154:157], v[200:203], 0
	v_mfma_f32_16x16x32_bf16 v[110:113], v[146:149], v[212:215], 0
	v_mfma_f32_16x16x32_bf16 v[106:109], v[154:157], v[212:215], 0
	v_mfma_f32_16x16x32_bf16 v[94:97], v[146:149], v[220:223], 0
	v_mfma_f32_16x16x32_bf16 v[90:93], v[154:157], v[220:223], 0
	v_mfma_f32_16x16x32_bf16 v[78:81], v[146:149], v[228:231], 0
	v_mfma_f32_16x16x32_bf16 v[74:77], v[154:157], v[228:231], 0
	v_mfma_f32_16x16x32_bf16 v[126:129], v[150:153], v[208:211], v[126:129]
	v_mfma_f32_16x16x32_bf16 v[122:125], v[158:161], v[208:211], v[122:125]
	v_mfma_f32_16x16x32_bf16 v[110:113], v[150:153], v[216:219], v[110:113]
	v_mfma_f32_16x16x32_bf16 v[106:109], v[158:161], v[216:219], v[106:109]
	v_mfma_f32_16x16x32_bf16 v[94:97], v[150:153], v[224:227], v[94:97]
	v_mfma_f32_16x16x32_bf16 v[90:93], v[158:161], v[224:227], v[90:93]
	v_mfma_f32_16x16x32_bf16 v[78:81], v[150:153], v[232:235], v[78:81]
	v_mfma_f32_16x16x32_bf16 v[74:77], v[158:161], v[232:235], v[74:77]
	v_mfma_f32_16x16x32_bf16 v[118:121], v[174:177], v[200:203], 0
	v_mfma_f32_16x16x32_bf16 v[114:117], v[182:185], v[200:203], 0
	v_mfma_f32_16x16x32_bf16 v[102:105], v[174:177], v[212:215], 0
	v_mfma_f32_16x16x32_bf16 v[98:101], v[182:185], v[212:215], 0
	v_mfma_f32_16x16x32_bf16 v[86:89], v[174:177], v[220:223], 0
	v_mfma_f32_16x16x32_bf16 v[82:85], v[182:185], v[220:223], 0
	v_mfma_f32_16x16x32_bf16 v[70:73], v[174:177], v[228:231], 0
	v_mfma_f32_16x16x32_bf16 v[66:69], v[182:185], v[228:231], 0
	v_mfma_f32_16x16x32_bf16 v[118:121], v[178:181], v[208:211], v[118:121]
	v_mfma_f32_16x16x32_bf16 v[114:117], v[186:189], v[208:211], v[114:117]
	v_mfma_f32_16x16x32_bf16 v[102:105], v[178:181], v[216:219], v[102:105]
	v_mfma_f32_16x16x32_bf16 v[98:101], v[186:189], v[216:219], v[98:101]
	v_mfma_f32_16x16x32_bf16 v[86:89], v[178:181], v[224:227], v[86:89]
	v_mfma_f32_16x16x32_bf16 v[82:85], v[186:189], v[224:227], v[82:85]
	v_mfma_f32_16x16x32_bf16 v[70:73], v[178:181], v[232:235], v[70:73]
	v_mfma_f32_16x16x32_bf16 v[66:69], v[186:189], v[232:235], v[66:69]
	s_setprio 0
	s_barrier
	s_add_i32 s70, s70, s57
	v_lshl_add_u64 v[140:141], s[52:53], 0, v[0:1]
	s_mov_b32 m0, s70
	ds_read_b128 v[200:203], v145 offset:16384
	ds_read_b128 v[208:211], v145 offset:17408
	ds_read_b128 v[212:215], v145 offset:18432
	ds_read_b128 v[216:219], v145 offset:19456
	ds_read_b128 v[220:223], v145 offset:20480
	ds_read_b128 v[224:227], v145 offset:21504
	ds_read_b128 v[228:231], v145 offset:22528
	ds_read_b128 v[232:235], v145 offset:23552
	global_load_lds_dwordx4 v[140:141], off
	s_add_i32 m0, s70, 0x2000
	s_add_u32 s70, s52, 0x40000
	v_lshl_add_u64 v[190:191], s[52:53], 0, v[130:131]
	s_addc_u32 s71, s53, 0
	s_add_i32 vcc_hi, vcc_hi, s57
	global_load_lds_dwordx4 v[190:191], off
	v_lshl_add_u64 v[236:237], s[70:71], 0, v[0:1]
	s_mov_b32 m0, vcc_hi
	v_lshl_add_u64 v[238:239], s[54:55], 0, v[132:133]
	global_load_lds_dwordx4 v[236:237], off
	v_lshl_add_u64 v[236:237], s[70:71], 0, v[130:131]
	s_add_i32 m0, vcc_hi, 0x2000
	s_nop 0
	global_load_lds_dwordx4 v[236:237], off
	v_lshl_add_u64 v[236:237], s[54:55], 0, v[134:135]
	s_mov_b32 m0, s58
	s_nop 0
	global_load_lds_dwordx4 v[236:237], off
	s_mov_b32 m0, s59
	s_nop 0
	global_load_lds_dwordx4 v[238:239], off
	s_waitcnt vmcnt(8)
	s_waitcnt lgkmcnt(0)
	s_barrier
; #define PG8_STAGEA(bufoff, gbase, voff) do { _Pragma("unroll") for (int _i = 0; _i < 2; ++_i) \
;         __builtin_amdgcn_global_load_lds((const unsigned*)((const char*)(gbase) + (voff)[_i]), (PG8_LAS unsigned*)(lds + (bufoff) + ldsw + _i * 8192), 16, 0, A_AUX); } while (0)
; #define PG8_LDA(dst, b, h) do { _Pragma("unroll") for (int m = 0; m < 4; ++m) _Pragma("unroll") for (int k = 0; k < 2; ++k) dst[m][k] = *(const PG8_LAS bf16x8*)(lds + PG8_SA(b, h) + aoff + m * 2048 + k * 1024); } while (0)
; #define PG8_LDB(dst, b, h) do { _Pragma("unroll") for (int n = 0; n < 2; ++n) _Pragma("unroll") for (int k = 0; k < 2; ++k) dst[n][k] = *(const PG8_LAS bf16x8*)(lds + PG8_SB(b, h) + boff + n * 2048 + k * 1024); } while (0)
; #define PG8_MMA(ai, bj, At, Bt) do { __builtin_amdgcn_s_setprio(1); _Pragma("unroll") for (int m = 0; m < 4; ++m) _Pragma("unroll") for (int n = 0; n < 2; ++n) _Pragma("unroll") for (int k = 0; k < 2; ++k) \
;         acc[ai][bj][m][n] = __builtin_amdgcn_mfma_f32_16x16x32_bf16(Bt[n][k], At[m][k], acc[ai][bj][m][n], 0, 0, 0); __builtin_amdgcn_s_setprio(0); } while (0)
; #define PG8_WAIT_V(n) asm volatile("s_waitcnt vmcnt(" #n ")" ::: "memory")
; #define PG8_WAIT_L(n) asm volatile("s_waitcnt lgkmcnt(" #n ")" ::: "memory")
; #define PG8_BAR __builtin_amdgcn_s_barrier()
; #define PG8_SCHED __builtin_amdgcn_sched_barrier(0)
;     ...
;             PG8_WAIT_V(8); PG8_WAIT_L(0); PG8_BAR; PG8_MMA(1, 0, At, B0); PG8_MMA(1, 1, At, B1); PG8_BAR; PG8_SCHED;
;             PG8_LDB(B0, 1, 0); PG8_LDB(B1, 1, 1); PG8_SCHED; PG8_LDA(At, 1, 0); PG8_STAGEA(PG8_SA(0, 1), a2 + hstep, voffA);
;             PG8_WAIT_V(8); PG8_WAIT_L(0); PG8_BAR; PG8_MMA(0, 0, At, B0); PG8_MMA(0, 1, At, B1); PG8_BAR; PG8_SCHED;
	s_setprio 1
	s_waitcnt lgkmcnt(0)
	v_mfma_f32_16x16x32_bf16 v[62:65], v[146:149], v[200:203], 0
	v_mfma_f32_16x16x32_bf16 v[58:61], v[154:157], v[200:203], 0
	v_mfma_f32_16x16x32_bf16 v[46:49], v[146:149], v[212:215], 0
	v_mfma_f32_16x16x32_bf16 v[42:45], v[154:157], v[212:215], 0
	v_mfma_f32_16x16x32_bf16 v[30:33], v[146:149], v[220:223], 0
	v_mfma_f32_16x16x32_bf16 v[26:29], v[154:157], v[220:223], 0
	v_mfma_f32_16x16x32_bf16 v[14:17], v[146:149], v[228:231], 0
	v_mfma_f32_16x16x32_bf16 v[10:13], v[154:157], v[228:231], 0
	v_mfma_f32_16x16x32_bf16 v[62:65], v[150:153], v[208:211], v[62:65]
	v_mfma_f32_16x16x32_bf16 v[58:61], v[158:161], v[208:211], v[58:61]
	v_mfma_f32_16x16x32_bf16 v[46:49], v[150:153], v[216:219], v[46:49]
	v_mfma_f32_16x16x32_bf16 v[42:45], v[158:161], v[216:219], v[42:45]
	v_mfma_f32_16x16x32_bf16 v[30:33], v[150:153], v[224:227], v[30:33]
	v_mfma_f32_16x16x32_bf16 v[26:29], v[158:161], v[224:227], v[26:29]
	v_mfma_f32_16x16x32_bf16 v[14:17], v[150:153], v[232:235], v[14:17]
	v_mfma_f32_16x16x32_bf16 v[10:13], v[158:161], v[232:235], v[10:13]
	v_mfma_f32_16x16x32_bf16 v[54:57], v[174:177], v[200:203], 0
	v_mfma_f32_16x16x32_bf16 v[50:53], v[182:185], v[200:203], 0
	v_mfma_f32_16x16x32_bf16 v[38:41], v[174:177], v[212:215], 0
	v_mfma_f32_16x16x32_bf16 v[34:37], v[182:185], v[212:215], 0
	v_mfma_f32_16x16x32_bf16 v[22:25], v[174:177], v[220:223], 0
	v_mfma_f32_16x16x32_bf16 v[18:21], v[182:185], v[220:223], 0
	v_mfma_f32_16x16x32_bf16 v[6:9], v[174:177], v[228:231], 0
	v_mfma_f32_16x16x32_bf16 v[2:5], v[182:185], v[228:231], 0
	v_mfma_f32_16x16x32_bf16 v[54:57], v[178:181], v[208:211], v[54:57]
	v_mfma_f32_16x16x32_bf16 v[50:53], v[186:189], v[208:211], v[50:53]
	v_mfma_f32_16x16x32_bf16 v[38:41], v[178:181], v[216:219], v[38:41]
	v_mfma_f32_16x16x32_bf16 v[34:37], v[186:189], v[216:219], v[34:37]
	v_mfma_f32_16x16x32_bf16 v[22:25], v[178:181], v[224:227], v[22:25]
	v_mfma_f32_16x16x32_bf16 v[18:21], v[186:189], v[224:227], v[18:21]
	v_mfma_f32_16x16x32_bf16 v[6:9], v[178:181], v[232:235], v[6:9]
	v_mfma_f32_16x16x32_bf16 v[2:5], v[186:189], v[232:235], v[2:5]
	s_setprio 0
	s_barrier
	s_add_i32 s70, 0, 0x18000
	s_add_i32 s71, 0, 0x1c000
	v_add_u32_e32 v158, s70, v143
	v_add_u32_e32 v186, s71, v143
	ds_read_b128 v[146:149], v158
	ds_read_b128 v[150:153], v158 offset:1024
	ds_read_b128 v[154:157], v158 offset:2048
	ds_read_b128 v[158:161], v158 offset:3072
	ds_read_b128 v[174:177], v186
	ds_read_b128 v[178:181], v186 offset:1024
	ds_read_b128 v[182:185], v186 offset:2048
	ds_read_b128 v[186:189], v186 offset:3072
	s_add_u32 s54, s54, 0x40000
	s_addc_u32 s55, s55, 0
	s_mov_b32 m0, s60
	v_lshl_add_u64 v[240:241], s[54:55], 0, v[134:135]
	ds_read_b128 v[200:203], v145 offset:32768
	ds_read_b128 v[208:211], v145 offset:33792
	ds_read_b128 v[212:215], v145 offset:34816
	ds_read_b128 v[216:219], v145 offset:35840
	ds_read_b128 v[220:223], v145 offset:36864
	ds_read_b128 v[224:227], v145 offset:37888
	ds_read_b128 v[228:231], v145 offset:38912
	ds_read_b128 v[232:235], v145 offset:39936
	global_load_lds_dwordx4 v[240:241], off
	v_lshl_add_u64 v[240:241], s[54:55], 0, v[132:133]
	s_mov_b32 m0, s61
	s_nop 0
	global_load_lds_dwordx4 v[240:241], off
	s_waitcnt vmcnt(8)
	s_waitcnt lgkmcnt(0)
	s_barrier
	s_setprio 1
	s_waitcnt lgkmcnt(0)
	v_mfma_f32_16x16x32_bf16 v[126:129], v[146:149], v[200:203], v[126:129]
	v_mfma_f32_16x16x32_bf16 v[122:125], v[154:157], v[200:203], v[122:125]
	v_mfma_f32_16x16x32_bf16 v[110:113], v[146:149], v[212:215], v[110:113]
	v_mfma_f32_16x16x32_bf16 v[106:109], v[154:157], v[212:215], v[106:109]
	v_mfma_f32_16x16x32_bf16 v[94:97], v[146:149], v[220:223], v[94:97]
	v_mfma_f32_16x16x32_bf16 v[90:93], v[154:157], v[220:223], v[90:93]
	v_mfma_f32_16x16x32_bf16 v[78:81], v[146:149], v[228:231], v[78:81]
	v_mfma_f32_16x16x32_bf16 v[74:77], v[154:157], v[228:231], v[74:77]
	v_mfma_f32_16x16x32_bf16 v[126:129], v[150:153], v[208:211], v[126:129]
	v_mfma_f32_16x16x32_bf16 v[122:125], v[158:161], v[208:211], v[122:125]
	v_mfma_f32_16x16x32_bf16 v[110:113], v[150:153], v[216:219], v[110:113]
	v_mfma_f32_16x16x32_bf16 v[106:109], v[158:161], v[216:219], v[106:109]
	v_mfma_f32_16x16x32_bf16 v[94:97], v[150:153], v[224:227], v[94:97]
	v_mfma_f32_16x16x32_bf16 v[90:93], v[158:161], v[224:227], v[90:93]
	v_mfma_f32_16x16x32_bf16 v[78:81], v[150:153], v[232:235], v[78:81]
	v_mfma_f32_16x16x32_bf16 v[74:77], v[158:161], v[232:235], v[74:77]
	v_mfma_f32_16x16x32_bf16 v[118:121], v[174:177], v[200:203], v[118:121]
	v_mfma_f32_16x16x32_bf16 v[114:117], v[182:185], v[200:203], v[114:117]
	v_mfma_f32_16x16x32_bf16 v[102:105], v[174:177], v[212:215], v[102:105]
	v_mfma_f32_16x16x32_bf16 v[98:101], v[182:185], v[212:215], v[98:101]
	v_mfma_f32_16x16x32_bf16 v[86:89], v[174:177], v[220:223], v[86:89]
	v_mfma_f32_16x16x32_bf16 v[82:85], v[182:185], v[220:223], v[82:85]
	v_mfma_f32_16x16x32_bf16 v[70:73], v[174:177], v[228:231], v[70:73]
	v_mfma_f32_16x16x32_bf16 v[66:69], v[182:185], v[228:231], v[66:69]
	v_mfma_f32_16x16x32_bf16 v[118:121], v[178:181], v[208:211], v[118:121]
	v_mfma_f32_16x16x32_bf16 v[114:117], v[186:189], v[208:211], v[114:117]
	v_mfma_f32_16x16x32_bf16 v[102:105], v[178:181], v[216:219], v[102:105]
	v_mfma_f32_16x16x32_bf16 v[98:101], v[186:189], v[216:219], v[98:101]
	v_mfma_f32_16x16x32_bf16 v[86:89], v[178:181], v[224:227], v[86:89]
	v_mfma_f32_16x16x32_bf16 v[82:85], v[186:189], v[224:227], v[82:85]
	v_mfma_f32_16x16x32_bf16 v[70:73], v[178:181], v[232:235], v[70:73]
	v_mfma_f32_16x16x32_bf16 v[66:69], v[186:189], v[232:235], v[66:69]
	s_setprio 0
	s_barrier
; #define PG8_STAGE(bufoff, gbase, voff) do { _Pragma("unroll") for (int _i = 0; _i < 2; ++_i) \
;         __builtin_amdgcn_global_load_lds((const unsigned*)((const char*)(gbase) + (voff)[_i]), (PG8_LAS unsigned*)(lds + (bufoff) + ldsw + _i * 8192), 16, 0, 0); } while (0)
; #define PG8_STAGEA(bufoff, gbase, voff) do { _Pragma("unroll") for (int _i = 0; _i < 2; ++_i) \
;         __builtin_amdgcn_global_load_lds((const unsigned*)((const char*)(gbase) + (voff)[_i]), (PG8_LAS unsigned*)(lds + (bufoff) + ldsw + _i * 8192), 16, 0, A_AUX); } while (0)
; #define PG8_LDA(dst, b, h) do { _Pragma("unroll") for (int m = 0; m < 4; ++m) _Pragma("unroll") for (int k = 0; k < 2; ++k) dst[m][k] = *(const PG8_LAS bf16x8*)(lds + PG8_SA(b, h) + aoff + m * 2048 + k * 1024); } while (0)
; #define PG8_WAIT_V(n) asm volatile("s_waitcnt vmcnt(" #n ")" ::: "memory")
; #define PG8_BAR __builtin_amdgcn_s_barrier()
;     ...
;         for (int t = 0; t < nt; t += 2) {
;             const bool last = (t == nt - 2);
;             const char* a1 = cA + (size_t)(t + 1) * kstep;
;             const char* a2 = last ? nA : cA + (size_t)(t + 2) * kstep; const char* b2 = last ? nB : cB + (size_t)(t + 2) * kstep;
;             const char* a3 = a2 + kstep; const char* b3 = b2 + kstep;
;             if (last && has_next) S.a_ready(nxt);
;             if constexpr (SP2) {
;             PG8_LDB(B0, 0, 0); PG8_LDB(B1, 0, 1); PG8_SCHED; PG8_LDA(At, 0, 0); PG8_STAGEA(PG8_SA(1, 1), a1 + hstep, voffA);
;             PG8_WAIT_V(8); PG8_WAIT_L(0); PG8_BAR; PG8_MMA(0, 0, At, B0); PG8_MMA(0, 1, At, B1); PG8_BAR; PG8_SCHED;
;             PG8_LDA(At, 0, 1); PG8_STAGE(PG8_SB(0, 0), b2, voffB); PG8_STAGE(PG8_SB(0, 1), b2 + hstep, voffB); PG8_STAGEA(PG8_SA(0, 0), a2, voffA);
;             PG8_WAIT_V(8); PG8_WAIT_L(0); PG8_BAR; PG8_MMA(1, 0, At, B0); PG8_MMA(1, 1, At, B1); PG8_BAR; PG8_SCHED;
;             PG8_LDB(B0, 1, 0); PG8_LDB(B1, 1, 1); PG8_SCHED; PG8_LDA(At, 1, 0); PG8_STAGEA(PG8_SA(0, 1), a2 + hstep, voffA);
;             PG8_WAIT_V(8); PG8_WAIT_L(0); PG8_BAR; PG8_MMA(0, 0, At, B0); PG8_MMA(0, 1, At, B1); PG8_BAR; PG8_SCHED;
;             PG8_LDA(At, 1, 1); PG8_STAGE(PG8_SB(1, 0), b3, voffB); PG8_STAGE(PG8_SB(1, 1), b3 + hstep, voffB); PG8_STAGEA(PG8_SA(1, 0), a3, voffA);
;             PG8_WAIT_V(8); PG8_WAIT_L(0); PG8_BAR; PG8_MMA(1, 0, At, B0); PG8_MMA(1, 1, At, B1); PG8_BAR; PG8_SCHED;
	s_add_i32 s54, s70, s57
	v_lshl_add_u64 v[140:141], v[140:141], 0, s[8:9]
	s_mov_b32 m0, s54
	ds_read_b128 v[200:203], v145 offset:49152
	ds_read_b128 v[208:211], v145 offset:50176
	ds_read_b128 v[212:215], v145 offset:51200
	ds_read_b128 v[216:219], v145 offset:52224
	ds_read_b128 v[220:223], v145 offset:53248
	ds_read_b128 v[224:227], v145 offset:54272
	ds_read_b128 v[228:231], v145 offset:55296
	ds_read_b128 v[232:235], v145 offset:56320
	global_load_lds_dwordx4 v[140:141], off
	s_add_i32 m0, s54, 0x2000
	s_add_u32 s52, s52, 0x40080
	v_lshl_add_u64 v[140:141], v[190:191], 0, s[8:9]
	s_addc_u32 s53, s53, 0
	s_add_i32 s54, s71, s57
	global_load_lds_dwordx4 v[140:141], off
	v_lshl_add_u64 v[140:141], s[52:53], 0, v[0:1]
	s_mov_b32 m0, s54
	s_nop 0
	global_load_lds_dwordx4 v[140:141], off
	v_lshl_add_u64 v[140:141], s[52:53], 0, v[130:131]
	s_add_i32 m0, s54, 0x2000
	s_nop 0
	global_load_lds_dwordx4 v[140:141], off
	v_lshl_add_u64 v[140:141], v[236:237], 0, s[8:9]
	s_mov_b32 m0, s62
	s_nop 0
	global_load_lds_dwordx4 v[140:141], off
	v_lshl_add_u64 v[140:141], v[238:239], 0, s[8:9]
	s_mov_b32 m0, s63
	s_nop 0
	global_load_lds_dwordx4 v[140:141], off
	s_waitcnt vmcnt(8)
	s_waitcnt lgkmcnt(0)
	s_barrier
	s_setprio 1
	s_waitcnt lgkmcnt(0)
	v_mfma_f32_16x16x32_bf16 v[62:65], v[146:149], v[200:203], v[62:65]
	v_mfma_f32_16x16x32_bf16 v[58:61], v[154:157], v[200:203], v[58:61]
	v_mfma_f32_16x16x32_bf16 v[46:49], v[146:149], v[212:215], v[46:49]
	v_mfma_f32_16x16x32_bf16 v[42:45], v[154:157], v[212:215], v[42:45]
	v_mfma_f32_16x16x32_bf16 v[30:33], v[146:149], v[220:223], v[30:33]
	v_mfma_f32_16x16x32_bf16 v[26:29], v[154:157], v[220:223], v[26:29]
	v_mfma_f32_16x16x32_bf16 v[14:17], v[146:149], v[228:231], v[14:17]
	v_mfma_f32_16x16x32_bf16 v[10:13], v[154:157], v[228:231], v[10:13]
	v_mfma_f32_16x16x32_bf16 v[62:65], v[150:153], v[208:211], v[62:65]
	v_mfma_f32_16x16x32_bf16 v[58:61], v[158:161], v[208:211], v[58:61]
	v_mfma_f32_16x16x32_bf16 v[46:49], v[150:153], v[216:219], v[46:49]
	v_mfma_f32_16x16x32_bf16 v[42:45], v[158:161], v[216:219], v[42:45]
	v_mfma_f32_16x16x32_bf16 v[30:33], v[150:153], v[224:227], v[30:33]
	v_mfma_f32_16x16x32_bf16 v[26:29], v[158:161], v[224:227], v[26:29]
	v_mfma_f32_16x16x32_bf16 v[14:17], v[150:153], v[232:235], v[14:17]
	v_mfma_f32_16x16x32_bf16 v[10:13], v[158:161], v[232:235], v[10:13]
	v_mfma_f32_16x16x32_bf16 v[54:57], v[174:177], v[200:203], v[54:57]
	v_mfma_f32_16x16x32_bf16 v[50:53], v[182:185], v[200:203], v[50:53]
	v_mfma_f32_16x16x32_bf16 v[38:41], v[174:177], v[212:215], v[38:41]
	v_mfma_f32_16x16x32_bf16 v[34:37], v[182:185], v[212:215], v[34:37]
	v_mfma_f32_16x16x32_bf16 v[22:25], v[174:177], v[220:223], v[22:25]
	v_mfma_f32_16x16x32_bf16 v[18:21], v[182:185], v[220:223], v[18:21]
	v_mfma_f32_16x16x32_bf16 v[6:9], v[174:177], v[228:231], v[6:9]
	v_mfma_f32_16x16x32_bf16 v[2:5], v[182:185], v[228:231], v[2:5]
	v_mfma_f32_16x16x32_bf16 v[54:57], v[178:181], v[208:211], v[54:57]
	v_mfma_f32_16x16x32_bf16 v[50:53], v[186:189], v[208:211], v[50:53]
	v_mfma_f32_16x16x32_bf16 v[38:41], v[178:181], v[216:219], v[38:41]
	v_mfma_f32_16x16x32_bf16 v[34:37], v[186:189], v[216:219], v[34:37]
	v_mfma_f32_16x16x32_bf16 v[22:25], v[178:181], v[224:227], v[22:25]
	v_mfma_f32_16x16x32_bf16 v[18:21], v[186:189], v[224:227], v[18:21]
	v_mfma_f32_16x16x32_bf16 v[6:9], v[178:181], v[232:235], v[6:9]
	v_mfma_f32_16x16x32_bf16 v[2:5], v[186:189], v[232:235], v[2:5]
	s_setprio 0
	s_barrier
	s_add_i32 vcc_lo, vcc_lo, 2
	s_add_u32 s50, s50, 0x100
	s_addc_u32 s51, s51, 0
	s_add_u32 s73, s73, 0x100
	s_addc_u32 s76, s76, 0
.LBB0_580:
	s_add_u32 s52, s50, 0xfffc0080
	s_addc_u32 s53, s51, -1
	s_add_i32 s70, 0, 0x10000
	s_cmp_eq_u32 vcc_lo, 12
	s_cselect_b32 s55, s16, s53
	s_cselect_b32 s54, s17, s52
	v_add_u32_e32 v140, s70, v143
	s_cselect_b32 s53, s43, s76
	s_cselect_b32 s52, s45, s73
	s_add_i32 vcc_hi, 0, 0x14000
	ds_read_b128 v[146:149], v140
	ds_read_b128 v[150:153], v140 offset:1024
	ds_read_b128 v[154:157], v140 offset:2048
	ds_read_b128 v[158:161], v140 offset:3072
	v_add_u32_e32 v140, vcc_hi, v143
	ds_read_b128 v[174:177], v140
	ds_read_b128 v[178:181], v140 offset:1024
	ds_read_b128 v[182:185], v140 offset:2048
	ds_read_b128 v[186:189], v140 offset:3072
	v_lshl_add_u64 v[140:141], s[50:51], 0, v[136:137]
	s_add_i32 m0, s58, 0xc000
	ds_read_b128 v[200:203], v145
	ds_read_b128 v[208:211], v145 offset:1024
	ds_read_b128 v[212:215], v145 offset:2048
	ds_read_b128 v[216:219], v145 offset:3072
	ds_read_b128 v[220:223], v145 offset:4096
	ds_read_b128 v[224:227], v145 offset:5120
	ds_read_b128 v[228:231], v145 offset:6144
	ds_read_b128 v[232:235], v145 offset:7168
	global_load_lds_dwordx4 v[140:141], off
	v_lshl_add_u64 v[140:141], s[50:51], 0, v[138:139]
	s_add_i32 m0, s58, 0xe000
	s_nop 0
	global_load_lds_dwordx4 v[140:141], off
	s_waitcnt vmcnt(8)
	s_waitcnt lgkmcnt(0)
	s_barrier
; #define PG8_STAGE(bufoff, gbase, voff) do { _Pragma("unroll") for (int _i = 0; _i < 2; ++_i) \
;         __builtin_amdgcn_global_load_lds((const unsigned*)((const char*)(gbase) + (voff)[_i]), (PG8_LAS unsigned*)(lds + (bufoff) + ldsw + _i * 8192), 16, 0, 0); } while (0)
; #define PG8_STAGEA(bufoff, gbase, voff) do { _Pragma("unroll") for (int _i = 0; _i < 2; ++_i) \
;         __builtin_amdgcn_global_load_lds((const unsigned*)((const char*)(gbase) + (voff)[_i]), (PG8_LAS unsigned*)(lds + (bufoff) + ldsw + _i * 8192), 16, 0, A_AUX); } while (0)
; #define PG8_LDA(dst, b, h) do { _Pragma("unroll") for (int m = 0; m < 4; ++m) _Pragma("unroll") for (int k = 0; k < 2; ++k) dst[m][k] = *(const PG8_LAS bf16x8*)(lds + PG8_SA(b, h) + aoff + m * 2048 + k * 1024); } while (0)
; #define PG8_MMA(ai, bj, At, Bt) do { __builtin_amdgcn_s_setprio(1); _Pragma("unroll") for (int m = 0; m < 4; ++m) _Pragma("unroll") for (int n = 0; n < 2; ++n) _Pragma("unroll") for (int k = 0; k < 2; ++k) \
;         acc[ai][bj][m][n] = __builtin_amdgcn_mfma_f32_16x16x32_bf16(Bt[n][k], At[m][k], acc[ai][bj][m][n], 0, 0, 0); __builtin_amdgcn_s_setprio(0); } while (0)
; #define PG8_WAIT_V(n) asm volatile("s_waitcnt vmcnt(" #n ")" ::: "memory")
; #define PG8_WAIT_L(n) asm volatile("s_waitcnt lgkmcnt(" #n ")" ::: "memory")
; #define PG8_BAR __builtin_amdgcn_s_barrier()
; #define PG8_SCHED __builtin_amdgcn_sched_barrier(0)
;     ...
;             PG8_WAIT_V(8); PG8_WAIT_L(0); PG8_BAR; PG8_MMA(0, 0, At, B0); PG8_MMA(0, 1, At, B1); PG8_BAR; PG8_SCHED;
;             PG8_LDA(At, 0, 1); PG8_STAGE(PG8_SB(0, 0), b2, voffB); PG8_STAGE(PG8_SB(0, 1), b2 + hstep, voffB); PG8_STAGEA(PG8_SA(0, 0), a2, voffA);
;             PG8_WAIT_V(8); PG8_WAIT_L(0); PG8_BAR; PG8_MMA(1, 0, At, B0); PG8_MMA(1, 1, At, B1); PG8_BAR; PG8_SCHED;
	s_setprio 1
	s_waitcnt lgkmcnt(0)
	v_mfma_f32_16x16x32_bf16 v[126:129], v[146:149], v[200:203], v[126:129]
	v_mfma_f32_16x16x32_bf16 v[122:125], v[154:157], v[200:203], v[122:125]
	v_mfma_f32_16x16x32_bf16 v[110:113], v[146:149], v[212:215], v[110:113]
	v_mfma_f32_16x16x32_bf16 v[106:109], v[154:157], v[212:215], v[106:109]
	v_mfma_f32_16x16x32_bf16 v[94:97], v[146:149], v[220:223], v[94:97]
	v_mfma_f32_16x16x32_bf16 v[90:93], v[154:157], v[220:223], v[90:93]
	v_mfma_f32_16x16x32_bf16 v[78:81], v[146:149], v[228:231], v[78:81]
	v_mfma_f32_16x16x32_bf16 v[74:77], v[154:157], v[228:231], v[74:77]
	v_mfma_f32_16x16x32_bf16 v[126:129], v[150:153], v[208:211], v[126:129]
	v_mfma_f32_16x16x32_bf16 v[122:125], v[158:161], v[208:211], v[122:125]
	v_mfma_f32_16x16x32_bf16 v[110:113], v[150:153], v[216:219], v[110:113]
	v_mfma_f32_16x16x32_bf16 v[106:109], v[158:161], v[216:219], v[106:109]
	v_mfma_f32_16x16x32_bf16 v[94:97], v[150:153], v[224:227], v[94:97]
	v_mfma_f32_16x16x32_bf16 v[90:93], v[158:161], v[224:227], v[90:93]
	v_mfma_f32_16x16x32_bf16 v[78:81], v[150:153], v[232:235], v[78:81]
	v_mfma_f32_16x16x32_bf16 v[74:77], v[158:161], v[232:235], v[74:77]
	v_mfma_f32_16x16x32_bf16 v[118:121], v[174:177], v[200:203], v[118:121]
	v_mfma_f32_16x16x32_bf16 v[114:117], v[182:185], v[200:203], v[114:117]
	v_mfma_f32_16x16x32_bf16 v[102:105], v[174:177], v[212:215], v[102:105]
	v_mfma_f32_16x16x32_bf16 v[98:101], v[182:185], v[212:215], v[98:101]
	v_mfma_f32_16x16x32_bf16 v[86:89], v[174:177], v[220:223], v[86:89]
	v_mfma_f32_16x16x32_bf16 v[82:85], v[182:185], v[220:223], v[82:85]
	v_mfma_f32_16x16x32_bf16 v[70:73], v[174:177], v[228:231], v[70:73]
	v_mfma_f32_16x16x32_bf16 v[66:69], v[182:185], v[228:231], v[66:69]
	v_mfma_f32_16x16x32_bf16 v[118:121], v[178:181], v[208:211], v[118:121]
	v_mfma_f32_16x16x32_bf16 v[114:117], v[186:189], v[208:211], v[114:117]
	v_mfma_f32_16x16x32_bf16 v[102:105], v[178:181], v[216:219], v[102:105]
	v_mfma_f32_16x16x32_bf16 v[98:101], v[186:189], v[216:219], v[98:101]
	v_mfma_f32_16x16x32_bf16 v[86:89], v[178:181], v[224:227], v[86:89]
	v_mfma_f32_16x16x32_bf16 v[82:85], v[186:189], v[224:227], v[82:85]
	v_mfma_f32_16x16x32_bf16 v[70:73], v[178:181], v[232:235], v[70:73]
	v_mfma_f32_16x16x32_bf16 v[66:69], v[186:189], v[232:235], v[66:69]
	s_setprio 0
	s_barrier
	s_add_i32 s70, s70, s57
	v_lshl_add_u64 v[140:141], s[52:53], 0, v[0:1]
	s_mov_b32 m0, s70
	ds_read_b128 v[200:203], v145 offset:16384
	ds_read_b128 v[208:211], v145 offset:17408
	ds_read_b128 v[212:215], v145 offset:18432
	ds_read_b128 v[216:219], v145 offset:19456
	ds_read_b128 v[220:223], v145 offset:20480
	ds_read_b128 v[224:227], v145 offset:21504
	ds_read_b128 v[228:231], v145 offset:22528
	ds_read_b128 v[232:235], v145 offset:23552
	global_load_lds_dwordx4 v[140:141], off
	s_add_i32 m0, s70, 0x2000
	s_add_u32 s70, s52, 0x40000
	v_lshl_add_u64 v[190:191], s[52:53], 0, v[130:131]
	s_addc_u32 s71, s53, 0
	s_add_i32 vcc_hi, vcc_hi, s57
	global_load_lds_dwordx4 v[190:191], off
	v_lshl_add_u64 v[236:237], s[70:71], 0, v[0:1]
	s_mov_b32 m0, vcc_hi
	v_lshl_add_u64 v[238:239], s[54:55], 0, v[132:133]
	global_load_lds_dwordx4 v[236:237], off
	v_lshl_add_u64 v[236:237], s[70:71], 0, v[130:131]
	s_add_i32 m0, vcc_hi, 0x2000
	s_nop 0
	global_load_lds_dwordx4 v[236:237], off
	v_lshl_add_u64 v[236:237], s[54:55], 0, v[134:135]
	s_mov_b32 m0, s58
	s_nop 0
	global_load_lds_dwordx4 v[236:237], off
	s_mov_b32 m0, s59
	s_nop 0
	global_load_lds_dwordx4 v[238:239], off
	s_waitcnt vmcnt(8)
	s_waitcnt lgkmcnt(0)
	s_barrier
	s_setprio 1
	s_waitcnt lgkmcnt(0)
	v_mfma_f32_16x16x32_bf16 v[62:65], v[146:149], v[200:203], v[62:65]
	v_mfma_f32_16x16x32_bf16 v[58:61], v[154:157], v[200:203], v[58:61]
	v_mfma_f32_16x16x32_bf16 v[46:49], v[146:149], v[212:215], v[46:49]
	v_mfma_f32_16x16x32_bf16 v[42:45], v[154:157], v[212:215], v[42:45]
	v_mfma_f32_16x16x32_bf16 v[30:33], v[146:149], v[220:223], v[30:33]
	v_mfma_f32_16x16x32_bf16 v[26:29], v[154:157], v[220:223], v[26:29]
	v_mfma_f32_16x16x32_bf16 v[14:17], v[146:149], v[228:231], v[14:17]
	v_mfma_f32_16x16x32_bf16 v[10:13], v[154:157], v[228:231], v[10:13]
	v_mfma_f32_16x16x32_bf16 v[62:65], v[150:153], v[208:211], v[62:65]
	v_mfma_f32_16x16x32_bf16 v[58:61], v[158:161], v[208:211], v[58:61]
	v_mfma_f32_16x16x32_bf16 v[46:49], v[150:153], v[216:219], v[46:49]
	v_mfma_f32_16x16x32_bf16 v[42:45], v[158:161], v[216:219], v[42:45]
	v_mfma_f32_16x16x32_bf16 v[30:33], v[150:153], v[224:227], v[30:33]
	v_mfma_f32_16x16x32_bf16 v[26:29], v[158:161], v[224:227], v[26:29]
	v_mfma_f32_16x16x32_bf16 v[14:17], v[150:153], v[232:235], v[14:17]
	v_mfma_f32_16x16x32_bf16 v[10:13], v[158:161], v[232:235], v[10:13]
	v_mfma_f32_16x16x32_bf16 v[54:57], v[174:177], v[200:203], v[54:57]
	v_mfma_f32_16x16x32_bf16 v[50:53], v[182:185], v[200:203], v[50:53]
	v_mfma_f32_16x16x32_bf16 v[38:41], v[174:177], v[212:215], v[38:41]
	v_mfma_f32_16x16x32_bf16 v[34:37], v[182:185], v[212:215], v[34:37]
	v_mfma_f32_16x16x32_bf16 v[22:25], v[174:177], v[220:223], v[22:25]
	v_mfma_f32_16x16x32_bf16 v[18:21], v[182:185], v[220:223], v[18:21]
	v_mfma_f32_16x16x32_bf16 v[6:9], v[174:177], v[228:231], v[6:9]
	v_mfma_f32_16x16x32_bf16 v[2:5], v[182:185], v[228:231], v[2:5]
	v_mfma_f32_16x16x32_bf16 v[54:57], v[178:181], v[208:211], v[54:57]
	v_mfma_f32_16x16x32_bf16 v[50:53], v[186:189], v[208:211], v[50:53]
	v_mfma_f32_16x16x32_bf16 v[38:41], v[178:181], v[216:219], v[38:41]
	v_mfma_f32_16x16x32_bf16 v[34:37], v[186:189], v[216:219], v[34:37]
	v_mfma_f32_16x16x32_bf16 v[22:25], v[178:181], v[224:227], v[22:25]
	v_mfma_f32_16x16x32_bf16 v[18:21], v[186:189], v[224:227], v[18:21]
	v_mfma_f32_16x16x32_bf16 v[6:9], v[178:181], v[232:235], v[6:9]
	v_mfma_f32_16x16x32_bf16 v[2:5], v[186:189], v[232:235], v[2:5]
	s_setprio 0
	s_barrier
; #define PG8_STAGEA(bufoff, gbase, voff) do { _Pragma("unroll") for (int _i = 0; _i < 2; ++_i) \
;         __builtin_amdgcn_global_load_lds((const unsigned*)((const char*)(gbase) + (voff)[_i]), (PG8_LAS unsigned*)(lds + (bufoff) + ldsw + _i * 8192), 16, 0, A_AUX); } while (0)
; #define PG8_LDA(dst, b, h) do { _Pragma("unroll") for (int m = 0; m < 4; ++m) _Pragma("unroll") for (int k = 0; k < 2; ++k) dst[m][k] = *(const PG8_LAS bf16x8*)(lds + PG8_SA(b, h) + aoff + m * 2048 + k * 1024); } while (0)
; #define PG8_LDB(dst, b, h) do { _Pragma("unroll") for (int n = 0; n < 2; ++n) _Pragma("unroll") for (int k = 0; k < 2; ++k) dst[n][k] = *(const PG8_LAS bf16x8*)(lds + PG8_SB(b, h) + boff + n * 2048 + k * 1024); } while (0)
; #define PG8_MMA(ai, bj, At, Bt) do { __builtin_amdgcn_s_setprio(1); _Pragma("unroll") for (int m = 0; m < 4; ++m) _Pragma("unroll") for (int n = 0; n < 2; ++n) _Pragma("unroll") for (int k = 0; k < 2; ++k) \
;         acc[ai][bj][m][n] = __builtin_amdgcn_mfma_f32_16x16x32_bf16(Bt[n][k], At[m][k], acc[ai][bj][m][n], 0, 0, 0); __builtin_amdgcn_s_setprio(0); } while (0)
; #define PG8_WAIT_V(n) asm volatile("s_waitcnt vmcnt(" #n ")" ::: "memory")
; #define PG8_WAIT_L(n) asm volatile("s_waitcnt lgkmcnt(" #n ")" ::: "memory")
; #define PG8_BAR __builtin_amdgcn_s_barrier()
; #define PG8_SCHED __builtin_amdgcn_sched_barrier(0)
;     ...
;             PG8_LDB(B0, 1, 0); PG8_LDB(B1, 1, 1); PG8_SCHED; PG8_LDA(At, 1, 0); PG8_STAGEA(PG8_SA(0, 1), a2 + hstep, voffA);
;             PG8_WAIT_V(8); PG8_WAIT_L(0); PG8_BAR; PG8_MMA(0, 0, At, B0); PG8_MMA(0, 1, At, B1); PG8_BAR; PG8_SCHED;
	s_add_i32 s70, 0, 0x18000
	s_add_i32 s71, 0, 0x1c000
	v_add_u32_e32 v158, s70, v143
	v_add_u32_e32 v186, s71, v143
	ds_read_b128 v[146:149], v158
	ds_read_b128 v[150:153], v158 offset:1024
	ds_read_b128 v[154:157], v158 offset:2048
	ds_read_b128 v[158:161], v158 offset:3072
	ds_read_b128 v[174:177], v186
	ds_read_b128 v[178:181], v186 offset:1024
	ds_read_b128 v[182:185], v186 offset:2048
	ds_read_b128 v[186:189], v186 offset:3072
	s_add_u32 s54, s54, 0x40000
	s_addc_u32 s55, s55, 0
	s_mov_b32 m0, s60
	v_lshl_add_u64 v[240:241], s[54:55], 0, v[134:135]
	ds_read_b128 v[200:203], v145 offset:32768
	ds_read_b128 v[208:211], v145 offset:33792
	ds_read_b128 v[212:215], v145 offset:34816
	ds_read_b128 v[216:219], v145 offset:35840
	ds_read_b128 v[220:223], v145 offset:36864
	ds_read_b128 v[224:227], v145 offset:37888
	ds_read_b128 v[228:231], v145 offset:38912
	ds_read_b128 v[232:235], v145 offset:39936
	global_load_lds_dwordx4 v[240:241], off
	v_lshl_add_u64 v[240:241], s[54:55], 0, v[132:133]
	s_mov_b32 m0, s61
	s_nop 0
	global_load_lds_dwordx4 v[240:241], off
	s_waitcnt vmcnt(8)
	s_waitcnt lgkmcnt(0)
	s_barrier
	s_setprio 1
	s_waitcnt lgkmcnt(0)
	v_mfma_f32_16x16x32_bf16 v[126:129], v[146:149], v[200:203], v[126:129]
	v_mfma_f32_16x16x32_bf16 v[122:125], v[154:157], v[200:203], v[122:125]
	v_mfma_f32_16x16x32_bf16 v[110:113], v[146:149], v[212:215], v[110:113]
	v_mfma_f32_16x16x32_bf16 v[106:109], v[154:157], v[212:215], v[106:109]
	v_mfma_f32_16x16x32_bf16 v[94:97], v[146:149], v[220:223], v[94:97]
	v_mfma_f32_16x16x32_bf16 v[90:93], v[154:157], v[220:223], v[90:93]
	v_mfma_f32_16x16x32_bf16 v[78:81], v[146:149], v[228:231], v[78:81]
	v_mfma_f32_16x16x32_bf16 v[74:77], v[154:157], v[228:231], v[74:77]
	v_mfma_f32_16x16x32_bf16 v[126:129], v[150:153], v[208:211], v[126:129]
	v_mfma_f32_16x16x32_bf16 v[122:125], v[158:161], v[208:211], v[122:125]
	v_mfma_f32_16x16x32_bf16 v[110:113], v[150:153], v[216:219], v[110:113]
	v_mfma_f32_16x16x32_bf16 v[106:109], v[158:161], v[216:219], v[106:109]
	v_mfma_f32_16x16x32_bf16 v[94:97], v[150:153], v[224:227], v[94:97]
	v_mfma_f32_16x16x32_bf16 v[90:93], v[158:161], v[224:227], v[90:93]
	v_mfma_f32_16x16x32_bf16 v[78:81], v[150:153], v[232:235], v[78:81]
	v_mfma_f32_16x16x32_bf16 v[74:77], v[158:161], v[232:235], v[74:77]
	v_mfma_f32_16x16x32_bf16 v[118:121], v[174:177], v[200:203], v[118:121]
	v_mfma_f32_16x16x32_bf16 v[114:117], v[182:185], v[200:203], v[114:117]
	v_mfma_f32_16x16x32_bf16 v[102:105], v[174:177], v[212:215], v[102:105]
	v_mfma_f32_16x16x32_bf16 v[98:101], v[182:185], v[212:215], v[98:101]
	v_mfma_f32_16x16x32_bf16 v[86:89], v[174:177], v[220:223], v[86:89]
	v_mfma_f32_16x16x32_bf16 v[82:85], v[182:185], v[220:223], v[82:85]
	v_mfma_f32_16x16x32_bf16 v[70:73], v[174:177], v[228:231], v[70:73]
	v_mfma_f32_16x16x32_bf16 v[66:69], v[182:185], v[228:231], v[66:69]
	v_mfma_f32_16x16x32_bf16 v[118:121], v[178:181], v[208:211], v[118:121]
	v_mfma_f32_16x16x32_bf16 v[114:117], v[186:189], v[208:211], v[114:117]
	v_mfma_f32_16x16x32_bf16 v[102:105], v[178:181], v[216:219], v[102:105]
	v_mfma_f32_16x16x32_bf16 v[98:101], v[186:189], v[216:219], v[98:101]
	v_mfma_f32_16x16x32_bf16 v[86:89], v[178:181], v[224:227], v[86:89]
	v_mfma_f32_16x16x32_bf16 v[82:85], v[186:189], v[224:227], v[82:85]
	v_mfma_f32_16x16x32_bf16 v[70:73], v[178:181], v[232:235], v[70:73]
	v_mfma_f32_16x16x32_bf16 v[66:69], v[186:189], v[232:235], v[66:69]
	s_setprio 0
	s_barrier
; #define PG8_STAGE(bufoff, gbase, voff) do { _Pragma("unroll") for (int _i = 0; _i < 2; ++_i) \
;         __builtin_amdgcn_global_load_lds((const unsigned*)((const char*)(gbase) + (voff)[_i]), (PG8_LAS unsigned*)(lds + (bufoff) + ldsw + _i * 8192), 16, 0, 0); } while (0)
; #define PG8_STAGEA(bufoff, gbase, voff) do { _Pragma("unroll") for (int _i = 0; _i < 2; ++_i) \
;         __builtin_amdgcn_global_load_lds((const unsigned*)((const char*)(gbase) + (voff)[_i]), (PG8_LAS unsigned*)(lds + (bufoff) + ldsw + _i * 8192), 16, 0, A_AUX); } while (0)
; #define PG8_LDA(dst, b, h) do { _Pragma("unroll") for (int m = 0; m < 4; ++m) _Pragma("unroll") for (int k = 0; k < 2; ++k) dst[m][k] = *(const PG8_LAS bf16x8*)(lds + PG8_SA(b, h) + aoff + m * 2048 + k * 1024); } while (0)
; #define PG8_MMA(ai, bj, At, Bt) do { __builtin_amdgcn_s_setprio(1); _Pragma("unroll") for (int m = 0; m < 4; ++m) _Pragma("unroll") for (int n = 0; n < 2; ++n) _Pragma("unroll") for (int k = 0; k < 2; ++k) \
;         acc[ai][bj][m][n] = __builtin_amdgcn_mfma_f32_16x16x32_bf16(Bt[n][k], At[m][k], acc[ai][bj][m][n], 0, 0, 0); __builtin_amdgcn_s_setprio(0); } while (0)
; #define PG8_WAIT_V(n) asm volatile("s_waitcnt vmcnt(" #n ")" ::: "memory")
; #define PG8_WAIT_L(n) asm volatile("s_waitcnt lgkmcnt(" #n ")" ::: "memory")
; #define PG8_BAR __builtin_amdgcn_s_barrier()
; #define PG8_SCHED __builtin_amdgcn_sched_barrier(0)
;     ...
;         for (int t = 0; t < nt; t += 2) {
;             const bool last = (t == nt - 2);
;             const char* a1 = cA + (size_t)(t + 1) * kstep;
;             const char* a2 = last ? nA : cA + (size_t)(t + 2) * kstep; const char* b2 = last ? nB : cB + (size_t)(t + 2) * kstep;
;     ...
;             PG8_LDA(At, 1, 1); PG8_STAGE(PG8_SB(1, 0), b3, voffB); PG8_STAGE(PG8_SB(1, 1), b3 + hstep, voffB); PG8_STAGEA(PG8_SA(1, 0), a3, voffA);
;             PG8_WAIT_V(8); PG8_WAIT_L(0); PG8_BAR; PG8_MMA(1, 0, At, B0); PG8_MMA(1, 1, At, B1); PG8_BAR; PG8_SCHED;
	s_add_i32 s54, s70, s57
	v_lshl_add_u64 v[140:141], v[140:141], 0, s[8:9]
	s_mov_b32 m0, s54
	ds_read_b128 v[200:203], v145 offset:49152
	ds_read_b128 v[208:211], v145 offset:50176
	ds_read_b128 v[212:215], v145 offset:51200
	ds_read_b128 v[216:219], v145 offset:52224
	ds_read_b128 v[220:223], v145 offset:53248
	ds_read_b128 v[224:227], v145 offset:54272
	ds_read_b128 v[228:231], v145 offset:55296
	ds_read_b128 v[232:235], v145 offset:56320
	global_load_lds_dwordx4 v[140:141], off
	s_add_i32 m0, s54, 0x2000
	s_add_u32 s52, s52, 0x40080
	v_lshl_add_u64 v[140:141], v[190:191], 0, s[8:9]
	s_addc_u32 s53, s53, 0
	s_add_i32 s54, s71, s57
	global_load_lds_dwordx4 v[140:141], off
	v_lshl_add_u64 v[140:141], s[52:53], 0, v[0:1]
	s_mov_b32 m0, s54
	s_nop 0
	global_load_lds_dwordx4 v[140:141], off
	v_lshl_add_u64 v[140:141], s[52:53], 0, v[130:131]
	s_add_i32 m0, s54, 0x2000
	s_nop 0
	global_load_lds_dwordx4 v[140:141], off
	v_lshl_add_u64 v[140:141], v[236:237], 0, s[8:9]
	s_mov_b32 m0, s62
	s_nop 0
	global_load_lds_dwordx4 v[140:141], off
	v_lshl_add_u64 v[140:141], v[238:239], 0, s[8:9]
	s_mov_b32 m0, s63
	s_nop 0
	global_load_lds_dwordx4 v[140:141], off
	s_waitcnt vmcnt(8)
	s_waitcnt lgkmcnt(0)
	s_barrier
	s_setprio 1
	s_waitcnt lgkmcnt(0)
	v_mfma_f32_16x16x32_bf16 v[62:65], v[146:149], v[200:203], v[62:65]
	v_mfma_f32_16x16x32_bf16 v[58:61], v[154:157], v[200:203], v[58:61]
	v_mfma_f32_16x16x32_bf16 v[46:49], v[146:149], v[212:215], v[46:49]
	v_mfma_f32_16x16x32_bf16 v[42:45], v[154:157], v[212:215], v[42:45]
	v_mfma_f32_16x16x32_bf16 v[30:33], v[146:149], v[220:223], v[30:33]
	v_mfma_f32_16x16x32_bf16 v[26:29], v[154:157], v[220:223], v[26:29]
	v_mfma_f32_16x16x32_bf16 v[14:17], v[146:149], v[228:231], v[14:17]
	v_mfma_f32_16x16x32_bf16 v[10:13], v[154:157], v[228:231], v[10:13]
	v_mfma_f32_16x16x32_bf16 v[62:65], v[150:153], v[208:211], v[62:65]
	v_mfma_f32_16x16x32_bf16 v[58:61], v[158:161], v[208:211], v[58:61]
	v_mfma_f32_16x16x32_bf16 v[46:49], v[150:153], v[216:219], v[46:49]
	v_mfma_f32_16x16x32_bf16 v[42:45], v[158:161], v[216:219], v[42:45]
	v_mfma_f32_16x16x32_bf16 v[30:33], v[150:153], v[224:227], v[30:33]
	v_mfma_f32_16x16x32_bf16 v[26:29], v[158:161], v[224:227], v[26:29]
	v_mfma_f32_16x16x32_bf16 v[14:17], v[150:153], v[232:235], v[14:17]
	v_mfma_f32_16x16x32_bf16 v[10:13], v[158:161], v[232:235], v[10:13]
	v_mfma_f32_16x16x32_bf16 v[54:57], v[174:177], v[200:203], v[54:57]
	v_mfma_f32_16x16x32_bf16 v[50:53], v[182:185], v[200:203], v[50:53]
	v_mfma_f32_16x16x32_bf16 v[38:41], v[174:177], v[212:215], v[38:41]
	v_mfma_f32_16x16x32_bf16 v[34:37], v[182:185], v[212:215], v[34:37]
	v_mfma_f32_16x16x32_bf16 v[22:25], v[174:177], v[220:223], v[22:25]
	v_mfma_f32_16x16x32_bf16 v[18:21], v[182:185], v[220:223], v[18:21]
	v_mfma_f32_16x16x32_bf16 v[6:9], v[174:177], v[228:231], v[6:9]
	v_mfma_f32_16x16x32_bf16 v[2:5], v[182:185], v[228:231], v[2:5]
	v_mfma_f32_16x16x32_bf16 v[54:57], v[178:181], v[208:211], v[54:57]
	v_mfma_f32_16x16x32_bf16 v[50:53], v[186:189], v[208:211], v[50:53]
	v_mfma_f32_16x16x32_bf16 v[38:41], v[178:181], v[216:219], v[38:41]
	v_mfma_f32_16x16x32_bf16 v[34:37], v[186:189], v[216:219], v[34:37]
	v_mfma_f32_16x16x32_bf16 v[22:25], v[178:181], v[224:227], v[22:25]
	v_mfma_f32_16x16x32_bf16 v[18:21], v[186:189], v[224:227], v[18:21]
	v_mfma_f32_16x16x32_bf16 v[6:9], v[178:181], v[232:235], v[6:9]
	v_mfma_f32_16x16x32_bf16 v[2:5], v[186:189], v[232:235], v[2:5]
	s_setprio 0
	s_barrier
	s_add_i32 vcc_lo, vcc_lo, 2
	s_add_u32 s50, s50, 0x100
	s_addc_u32 s51, s51, 0
	s_add_u32 s73, s73, 0x100
	s_addc_u32 s76, s76, 0
	s_cmp_gt_u32 vcc_lo, 13
	s_cbranch_scc0 .LBB0_580
	s_and_b64 vcc, exec, s[36:37]
	s_cbranch_vccz .LBB0_583
	s_barrier

; #define PG8_STAGE(bufoff, gbase, voff) do { _Pragma("unroll") for (int _i = 0; _i < 2; ++_i) \
;         __builtin_amdgcn_global_load_lds((const unsigned*)((const char*)(gbase) + (voff)[_i]), (PG8_LAS unsigned*)(lds + (bufoff) + ldsw + _i * 8192), 16, 0, 0); } while (0)
; #define PG8_STAGEA(bufoff, gbase, voff) do { _Pragma("unroll") for (int _i = 0; _i < 2; ++_i) \
;         __builtin_amdgcn_global_load_lds((const unsigned*)((const char*)(gbase) + (voff)[_i]), (PG8_LAS unsigned*)(lds + (bufoff) + ldsw + _i * 8192), 16, 0, A_AUX); } while (0)
; #define PG8_LDA(dst, b, h) do { _Pragma("unroll") for (int m = 0; m < 4; ++m) _Pragma("unroll") for (int k = 0; k < 2; ++k) dst[m][k] = *(const PG8_LAS bf16x8*)(lds + PG8_SA(b, h) + aoff + m * 2048 + k * 1024); } while (0)
; #define PG8_LDB(dst, b, h) do { _Pragma("unroll") for (int n = 0; n < 2; ++n) _Pragma("unroll") for (int k = 0; k < 2; ++k) dst[n][k] = *(const PG8_LAS bf16x8*)(lds + PG8_SB(b, h) + boff + n * 2048 + k * 1024); } while (0)
; #define PG8_MMA(ai, bj, At, Bt) do { __builtin_amdgcn_s_setprio(1); _Pragma("unroll") for (int m = 0; m < 4; ++m) _Pragma("unroll") for (int n = 0; n < 2; ++n) _Pragma("unroll") for (int k = 0; k < 2; ++k) \
;         acc[ai][bj][m][n] = __builtin_amdgcn_mfma_f32_16x16x32_bf16(Bt[n][k], At[m][k], acc[ai][bj][m][n], 0, 0, 0); __builtin_amdgcn_s_setprio(0); } while (0)
; #define PG8_WAIT_V(n) asm volatile("s_waitcnt vmcnt(" #n ")" ::: "memory")
;     ...
;             const bool last = (t == nt - 2);
;             const char* a1 = cA + (size_t)(t + 1) * kstep;
;             const char* a2 = last ? nA : cA + (size_t)(t + 2) * kstep; const char* b2 = last ? nB : cB + (size_t)(t + 2) * kstep;
;             const char* a3 = a2 + kstep; const char* b3 = b2 + kstep;
;             if (last && has_next) S.a_ready(nxt);
;             if constexpr (SP2) {
;             PG8_LDB(B0, 0, 0); PG8_LDB(B1, 0, 1); PG8_SCHED; PG8_LDA(At, 0, 0); PG8_STAGEA(PG8_SA(1, 1), a1 + hstep, voffA);
;             PG8_WAIT_V(8); PG8_WAIT_L(0); PG8_BAR; PG8_MMA(0, 0, At, B0); PG8_MMA(0, 1, At, B1); PG8_BAR; PG8_SCHED;
;             PG8_LDA(At, 0, 1); PG8_STAGE(PG8_SB(0, 0), b2, voffB); PG8_STAGE(PG8_SB(0, 1), b2 + hstep, voffB); PG8_STAGEA(PG8_SA(0, 0), a2, voffA);
;             PG8_WAIT_V(8); PG8_WAIT_L(0); PG8_BAR; PG8_MMA(1, 0, At, B0); PG8_MMA(1, 1, At, B1); PG8_BAR; PG8_SCHED;
.LBB0_655:
	s_add_u32 s16, s48, 0x100
	s_addc_u32 s17, s49, 0
	s_mov_b32 s73, -2
	s_add_u32 s48, s46, 0x100
	s_addc_u32 s49, s47, 0
	s_add_i32 s70, 0, 0x10000
	s_cmp_eq_u32 s73, 40
	s_cselect_b32 s53, s1, s49
	s_cselect_b32 s52, s0, s48
	v_add_u32_e32 v140, s70, v143
	s_cselect_b32 s51, s45, s17
	s_cselect_b32 s50, s44, s16
	s_add_i32 s71, 0, 0x14000
	ds_read_b128 v[146:149], v140
	ds_read_b128 v[150:153], v140 offset:1024
	ds_read_b128 v[154:157], v140 offset:2048
	ds_read_b128 v[158:161], v140 offset:3072
	v_add_u32_e32 v140, s71, v143
	ds_read_b128 v[174:177], v140
	ds_read_b128 v[178:181], v140 offset:1024
	ds_read_b128 v[182:185], v140 offset:2048
	ds_read_b128 v[186:189], v140 offset:3072
	v_lshl_add_u64 v[140:141], s[46:47], 0, v[136:137]
	s_add_i32 m0, s56, 0xc000
	ds_read_b128 v[200:203], v145
	ds_read_b128 v[208:211], v145 offset:1024
	ds_read_b128 v[212:215], v145 offset:2048
	ds_read_b128 v[216:219], v145 offset:3072
	ds_read_b128 v[220:223], v145 offset:4096
	ds_read_b128 v[224:227], v145 offset:5120
	ds_read_b128 v[228:231], v145 offset:6144
	ds_read_b128 v[232:235], v145 offset:7168
	global_load_lds_dwordx4 v[140:141], off
	v_lshl_add_u64 v[140:141], s[46:47], 0, v[138:139]
	s_add_i32 m0, s56, 0xe000
	s_nop 0
	global_load_lds_dwordx4 v[140:141], off
	s_waitcnt vmcnt(8)
	s_waitcnt lgkmcnt(0)
	s_barrier
	s_setprio 1
	s_waitcnt lgkmcnt(0)
	v_mfma_f32_16x16x32_bf16 v[126:129], v[146:149], v[200:203], 0
	v_mfma_f32_16x16x32_bf16 v[122:125], v[154:157], v[200:203], 0
	v_mfma_f32_16x16x32_bf16 v[114:117], v[146:149], v[212:215], 0
	v_mfma_f32_16x16x32_bf16 v[106:109], v[154:157], v[212:215], 0
	v_mfma_f32_16x16x32_bf16 v[98:101], v[146:149], v[220:223], 0
	v_mfma_f32_16x16x32_bf16 v[90:93], v[154:157], v[220:223], 0
	v_mfma_f32_16x16x32_bf16 v[82:85], v[146:149], v[228:231], 0
	v_mfma_f32_16x16x32_bf16 v[74:77], v[154:157], v[228:231], 0
	v_mfma_f32_16x16x32_bf16 v[126:129], v[150:153], v[208:211], v[126:129]
	v_mfma_f32_16x16x32_bf16 v[122:125], v[158:161], v[208:211], v[122:125]
	v_mfma_f32_16x16x32_bf16 v[114:117], v[150:153], v[216:219], v[114:117]
	v_mfma_f32_16x16x32_bf16 v[106:109], v[158:161], v[216:219], v[106:109]
	v_mfma_f32_16x16x32_bf16 v[98:101], v[150:153], v[224:227], v[98:101]
	v_mfma_f32_16x16x32_bf16 v[90:93], v[158:161], v[224:227], v[90:93]
	v_mfma_f32_16x16x32_bf16 v[82:85], v[150:153], v[232:235], v[82:85]
	v_mfma_f32_16x16x32_bf16 v[74:77], v[158:161], v[232:235], v[74:77]
	v_mfma_f32_16x16x32_bf16 v[118:121], v[174:177], v[200:203], 0
	v_mfma_f32_16x16x32_bf16 v[110:113], v[182:185], v[200:203], 0
	v_mfma_f32_16x16x32_bf16 v[102:105], v[174:177], v[212:215], 0
	v_mfma_f32_16x16x32_bf16 v[94:97], v[182:185], v[212:215], 0
	v_mfma_f32_16x16x32_bf16 v[86:89], v[174:177], v[220:223], 0
	v_mfma_f32_16x16x32_bf16 v[78:81], v[182:185], v[220:223], 0
	v_mfma_f32_16x16x32_bf16 v[70:73], v[174:177], v[228:231], 0
	v_mfma_f32_16x16x32_bf16 v[66:69], v[182:185], v[228:231], 0
	v_mfma_f32_16x16x32_bf16 v[118:121], v[178:181], v[208:211], v[118:121]
	v_mfma_f32_16x16x32_bf16 v[110:113], v[186:189], v[208:211], v[110:113]
	v_mfma_f32_16x16x32_bf16 v[102:105], v[178:181], v[216:219], v[102:105]
	v_mfma_f32_16x16x32_bf16 v[94:97], v[186:189], v[216:219], v[94:97]
	v_mfma_f32_16x16x32_bf16 v[86:89], v[178:181], v[224:227], v[86:89]
	v_mfma_f32_16x16x32_bf16 v[78:81], v[186:189], v[224:227], v[78:81]
	v_mfma_f32_16x16x32_bf16 v[70:73], v[178:181], v[232:235], v[70:73]
	v_mfma_f32_16x16x32_bf16 v[66:69], v[186:189], v[232:235], v[66:69]
	s_setprio 0
	s_barrier
	s_add_i32 s46, s70, s55
	v_lshl_add_u64 v[140:141], s[50:51], 0, v[0:1]
	s_mov_b32 m0, s46
	ds_read_b128 v[200:203], v145 offset:16384
	ds_read_b128 v[208:211], v145 offset:17408
	ds_read_b128 v[212:215], v145 offset:18432
	ds_read_b128 v[216:219], v145 offset:19456
	ds_read_b128 v[220:223], v145 offset:20480
	ds_read_b128 v[224:227], v145 offset:21504
	ds_read_b128 v[228:231], v145 offset:22528
	ds_read_b128 v[232:235], v145 offset:23552
	global_load_lds_dwordx4 v[140:141], off
	s_add_i32 m0, s46, 0x2000
	s_add_u32 s46, s50, 0xb0000
	v_lshl_add_u64 v[190:191], s[50:51], 0, v[130:131]
	s_addc_u32 s47, s51, 0
	s_add_i32 s70, s71, s55
	global_load_lds_dwordx4 v[190:191], off
	v_lshl_add_u64 v[236:237], s[46:47], 0, v[0:1]
	s_mov_b32 m0, s70
	v_lshl_add_u64 v[238:239], s[52:53], 0, v[132:133]
	global_load_lds_dwordx4 v[236:237], off
	v_lshl_add_u64 v[236:237], s[46:47], 0, v[130:131]
	s_add_i32 m0, s70, 0x2000
	s_nop 0
	global_load_lds_dwordx4 v[236:237], off
	v_lshl_add_u64 v[236:237], s[52:53], 0, v[134:135]
	s_mov_b32 m0, s56
	s_nop 0
	global_load_lds_dwordx4 v[236:237], off
	s_mov_b32 m0, s57
	s_nop 0
	global_load_lds_dwordx4 v[238:239], off
	s_waitcnt vmcnt(8)
	s_waitcnt lgkmcnt(0)
	s_barrier
; #define PG8_STAGEA(bufoff, gbase, voff) do { _Pragma("unroll") for (int _i = 0; _i < 2; ++_i) \
;         __builtin_amdgcn_global_load_lds((const unsigned*)((const char*)(gbase) + (voff)[_i]), (PG8_LAS unsigned*)(lds + (bufoff) + ldsw + _i * 8192), 16, 0, A_AUX); } while (0)
; #define PG8_LDA(dst, b, h) do { _Pragma("unroll") for (int m = 0; m < 4; ++m) _Pragma("unroll") for (int k = 0; k < 2; ++k) dst[m][k] = *(const PG8_LAS bf16x8*)(lds + PG8_SA(b, h) + aoff + m * 2048 + k * 1024); } while (0)
; #define PG8_LDB(dst, b, h) do { _Pragma("unroll") for (int n = 0; n < 2; ++n) _Pragma("unroll") for (int k = 0; k < 2; ++k) dst[n][k] = *(const PG8_LAS bf16x8*)(lds + PG8_SB(b, h) + boff + n * 2048 + k * 1024); } while (0)
; #define PG8_MMA(ai, bj, At, Bt) do { __builtin_amdgcn_s_setprio(1); _Pragma("unroll") for (int m = 0; m < 4; ++m) _Pragma("unroll") for (int n = 0; n < 2; ++n) _Pragma("unroll") for (int k = 0; k < 2; ++k) \
;         acc[ai][bj][m][n] = __builtin_amdgcn_mfma_f32_16x16x32_bf16(Bt[n][k], At[m][k], acc[ai][bj][m][n], 0, 0, 0); __builtin_amdgcn_s_setprio(0); } while (0)
; #define PG8_WAIT_V(n) asm volatile("s_waitcnt vmcnt(" #n ")" ::: "memory")
; #define PG8_WAIT_L(n) asm volatile("s_waitcnt lgkmcnt(" #n ")" ::: "memory")
; #define PG8_BAR __builtin_amdgcn_s_barrier()
; #define PG8_SCHED __builtin_amdgcn_sched_barrier(0)
;     ...
;             PG8_WAIT_V(8); PG8_WAIT_L(0); PG8_BAR; PG8_MMA(1, 0, At, B0); PG8_MMA(1, 1, At, B1); PG8_BAR; PG8_SCHED;
;             PG8_LDB(B0, 1, 0); PG8_LDB(B1, 1, 1); PG8_SCHED; PG8_LDA(At, 1, 0); PG8_STAGEA(PG8_SA(0, 1), a2 + hstep, voffA);
;             PG8_WAIT_V(8); PG8_WAIT_L(0); PG8_BAR; PG8_MMA(0, 0, At, B0); PG8_MMA(0, 1, At, B1); PG8_BAR; PG8_SCHED;
	s_setprio 1
	s_waitcnt lgkmcnt(0)
	v_mfma_f32_16x16x32_bf16 v[62:65], v[146:149], v[200:203], 0
	v_mfma_f32_16x16x32_bf16 v[58:61], v[154:157], v[200:203], 0
	v_mfma_f32_16x16x32_bf16 v[50:53], v[146:149], v[212:215], 0
	v_mfma_f32_16x16x32_bf16 v[42:45], v[154:157], v[212:215], 0
	v_mfma_f32_16x16x32_bf16 v[34:37], v[146:149], v[220:223], 0
	v_mfma_f32_16x16x32_bf16 v[26:29], v[154:157], v[220:223], 0
	v_mfma_f32_16x16x32_bf16 v[18:21], v[146:149], v[228:231], 0
	v_mfma_f32_16x16x32_bf16 v[10:13], v[154:157], v[228:231], 0
	v_mfma_f32_16x16x32_bf16 v[62:65], v[150:153], v[208:211], v[62:65]
	v_mfma_f32_16x16x32_bf16 v[58:61], v[158:161], v[208:211], v[58:61]
	v_mfma_f32_16x16x32_bf16 v[50:53], v[150:153], v[216:219], v[50:53]
	v_mfma_f32_16x16x32_bf16 v[42:45], v[158:161], v[216:219], v[42:45]
	v_mfma_f32_16x16x32_bf16 v[34:37], v[150:153], v[224:227], v[34:37]
	v_mfma_f32_16x16x32_bf16 v[26:29], v[158:161], v[224:227], v[26:29]
	v_mfma_f32_16x16x32_bf16 v[18:21], v[150:153], v[232:235], v[18:21]
	v_mfma_f32_16x16x32_bf16 v[10:13], v[158:161], v[232:235], v[10:13]
	v_mfma_f32_16x16x32_bf16 v[54:57], v[174:177], v[200:203], 0
	v_mfma_f32_16x16x32_bf16 v[46:49], v[182:185], v[200:203], 0
	v_mfma_f32_16x16x32_bf16 v[38:41], v[174:177], v[212:215], 0
	v_mfma_f32_16x16x32_bf16 v[30:33], v[182:185], v[212:215], 0
	v_mfma_f32_16x16x32_bf16 v[22:25], v[174:177], v[220:223], 0
	v_mfma_f32_16x16x32_bf16 v[14:17], v[182:185], v[220:223], 0
	v_mfma_f32_16x16x32_bf16 v[6:9], v[174:177], v[228:231], 0
	v_mfma_f32_16x16x32_bf16 v[2:5], v[182:185], v[228:231], 0
	v_mfma_f32_16x16x32_bf16 v[54:57], v[178:181], v[208:211], v[54:57]
	v_mfma_f32_16x16x32_bf16 v[46:49], v[186:189], v[208:211], v[46:49]
	v_mfma_f32_16x16x32_bf16 v[38:41], v[178:181], v[216:219], v[38:41]
	v_mfma_f32_16x16x32_bf16 v[30:33], v[186:189], v[216:219], v[30:33]
	v_mfma_f32_16x16x32_bf16 v[22:25], v[178:181], v[224:227], v[22:25]
	v_mfma_f32_16x16x32_bf16 v[14:17], v[186:189], v[224:227], v[14:17]
	v_mfma_f32_16x16x32_bf16 v[6:9], v[178:181], v[232:235], v[6:9]
	v_mfma_f32_16x16x32_bf16 v[2:5], v[186:189], v[232:235], v[2:5]
	s_setprio 0
	s_barrier
	s_add_i32 s70, 0, 0x18000
	s_add_i32 s71, 0, 0x1c000
	v_add_u32_e32 v158, s70, v143
	v_add_u32_e32 v186, s71, v143
	ds_read_b128 v[146:149], v158
	ds_read_b128 v[150:153], v158 offset:1024
	ds_read_b128 v[154:157], v158 offset:2048
	ds_read_b128 v[158:161], v158 offset:3072
	ds_read_b128 v[174:177], v186
	ds_read_b128 v[178:181], v186 offset:1024
	ds_read_b128 v[182:185], v186 offset:2048
	ds_read_b128 v[186:189], v186 offset:3072
	s_add_u32 s46, s52, 0xb0000
	s_addc_u32 s47, s53, 0
	s_mov_b32 m0, s58
	v_lshl_add_u64 v[240:241], s[46:47], 0, v[134:135]
	ds_read_b128 v[200:203], v145 offset:32768
	ds_read_b128 v[208:211], v145 offset:33792
	ds_read_b128 v[212:215], v145 offset:34816
	ds_read_b128 v[216:219], v145 offset:35840
	ds_read_b128 v[220:223], v145 offset:36864
	ds_read_b128 v[224:227], v145 offset:37888
	ds_read_b128 v[228:231], v145 offset:38912
	ds_read_b128 v[232:235], v145 offset:39936
	global_load_lds_dwordx4 v[240:241], off
	v_lshl_add_u64 v[240:241], s[46:47], 0, v[132:133]
	s_mov_b32 m0, s59
	s_nop 0
	global_load_lds_dwordx4 v[240:241], off
	s_waitcnt vmcnt(8)
	s_waitcnt lgkmcnt(0)
	s_barrier
	s_setprio 1
	s_waitcnt lgkmcnt(0)
	v_mfma_f32_16x16x32_bf16 v[126:129], v[146:149], v[200:203], v[126:129]
	v_mfma_f32_16x16x32_bf16 v[122:125], v[154:157], v[200:203], v[122:125]
	v_mfma_f32_16x16x32_bf16 v[114:117], v[146:149], v[212:215], v[114:117]
	v_mfma_f32_16x16x32_bf16 v[106:109], v[154:157], v[212:215], v[106:109]
	v_mfma_f32_16x16x32_bf16 v[98:101], v[146:149], v[220:223], v[98:101]
	v_mfma_f32_16x16x32_bf16 v[90:93], v[154:157], v[220:223], v[90:93]
	v_mfma_f32_16x16x32_bf16 v[82:85], v[146:149], v[228:231], v[82:85]
	v_mfma_f32_16x16x32_bf16 v[74:77], v[154:157], v[228:231], v[74:77]
	v_mfma_f32_16x16x32_bf16 v[126:129], v[150:153], v[208:211], v[126:129]
	v_mfma_f32_16x16x32_bf16 v[122:125], v[158:161], v[208:211], v[122:125]
	v_mfma_f32_16x16x32_bf16 v[114:117], v[150:153], v[216:219], v[114:117]
	v_mfma_f32_16x16x32_bf16 v[106:109], v[158:161], v[216:219], v[106:109]
	v_mfma_f32_16x16x32_bf16 v[98:101], v[150:153], v[224:227], v[98:101]
	v_mfma_f32_16x16x32_bf16 v[90:93], v[158:161], v[224:227], v[90:93]
	v_mfma_f32_16x16x32_bf16 v[82:85], v[150:153], v[232:235], v[82:85]
	v_mfma_f32_16x16x32_bf16 v[74:77], v[158:161], v[232:235], v[74:77]
	v_mfma_f32_16x16x32_bf16 v[118:121], v[174:177], v[200:203], v[118:121]
	v_mfma_f32_16x16x32_bf16 v[110:113], v[182:185], v[200:203], v[110:113]
	v_mfma_f32_16x16x32_bf16 v[102:105], v[174:177], v[212:215], v[102:105]
	v_mfma_f32_16x16x32_bf16 v[94:97], v[182:185], v[212:215], v[94:97]
	v_mfma_f32_16x16x32_bf16 v[86:89], v[174:177], v[220:223], v[86:89]
	v_mfma_f32_16x16x32_bf16 v[78:81], v[182:185], v[220:223], v[78:81]
	v_mfma_f32_16x16x32_bf16 v[70:73], v[174:177], v[228:231], v[70:73]
	v_mfma_f32_16x16x32_bf16 v[66:69], v[182:185], v[228:231], v[66:69]
	v_mfma_f32_16x16x32_bf16 v[118:121], v[178:181], v[208:211], v[118:121]
	v_mfma_f32_16x16x32_bf16 v[110:113], v[186:189], v[208:211], v[110:113]
	v_mfma_f32_16x16x32_bf16 v[102:105], v[178:181], v[216:219], v[102:105]
	v_mfma_f32_16x16x32_bf16 v[94:97], v[186:189], v[216:219], v[94:97]
	v_mfma_f32_16x16x32_bf16 v[86:89], v[178:181], v[224:227], v[86:89]
	v_mfma_f32_16x16x32_bf16 v[78:81], v[186:189], v[224:227], v[78:81]
	v_mfma_f32_16x16x32_bf16 v[70:73], v[178:181], v[232:235], v[70:73]
	v_mfma_f32_16x16x32_bf16 v[66:69], v[186:189], v[232:235], v[66:69]
	s_setprio 0
	s_barrier
; #define PG8_STAGE(bufoff, gbase, voff) do { _Pragma("unroll") for (int _i = 0; _i < 2; ++_i) \
;         __builtin_amdgcn_global_load_lds((const unsigned*)((const char*)(gbase) + (voff)[_i]), (PG8_LAS unsigned*)(lds + (bufoff) + ldsw + _i * 8192), 16, 0, 0); } while (0)
; #define PG8_STAGEA(bufoff, gbase, voff) do { _Pragma("unroll") for (int _i = 0; _i < 2; ++_i) \
;         __builtin_amdgcn_global_load_lds((const unsigned*)((const char*)(gbase) + (voff)[_i]), (PG8_LAS unsigned*)(lds + (bufoff) + ldsw + _i * 8192), 16, 0, A_AUX); } while (0)
; #define PG8_LDA(dst, b, h) do { _Pragma("unroll") for (int m = 0; m < 4; ++m) _Pragma("unroll") for (int k = 0; k < 2; ++k) dst[m][k] = *(const PG8_LAS bf16x8*)(lds + PG8_SA(b, h) + aoff + m * 2048 + k * 1024); } while (0)
; #define PG8_LDB(dst, b, h) do { _Pragma("unroll") for (int n = 0; n < 2; ++n) _Pragma("unroll") for (int k = 0; k < 2; ++k) dst[n][k] = *(const PG8_LAS bf16x8*)(lds + PG8_SB(b, h) + boff + n * 2048 + k * 1024); } while (0)
; #define PG8_MMA(ai, bj, At, Bt) do { __builtin_amdgcn_s_setprio(1); _Pragma("unroll") for (int m = 0; m < 4; ++m) _Pragma("unroll") for (int n = 0; n < 2; ++n) _Pragma("unroll") for (int k = 0; k < 2; ++k) \
;         acc[ai][bj][m][n] = __builtin_amdgcn_mfma_f32_16x16x32_bf16(Bt[n][k], At[m][k], acc[ai][bj][m][n], 0, 0, 0); __builtin_amdgcn_s_setprio(0); } while (0)
; #define PG8_BAR __builtin_amdgcn_s_barrier()
;     ...
;         for (int t = 0; t < nt; t += 2) {
;             const bool last = (t == nt - 2);
;             const char* a1 = cA + (size_t)(t + 1) * kstep;
;             const char* a2 = last ? nA : cA + (size_t)(t + 2) * kstep; const char* b2 = last ? nB : cB + (size_t)(t + 2) * kstep;
;             const char* a3 = a2 + kstep; const char* b3 = b2 + kstep;
;             if (last && has_next) S.a_ready(nxt);
;             if constexpr (SP2) {
;             PG8_LDB(B0, 0, 0); PG8_LDB(B1, 0, 1); PG8_SCHED; PG8_LDA(At, 0, 0); PG8_STAGEA(PG8_SA(1, 1), a1 + hstep, voffA);
;             PG8_WAIT_V(8); PG8_WAIT_L(0); PG8_BAR; PG8_MMA(0, 0, At, B0); PG8_MMA(0, 1, At, B1); PG8_BAR; PG8_SCHED;
;     ...
;             PG8_LDA(At, 1, 1); PG8_STAGE(PG8_SB(1, 0), b3, voffB); PG8_STAGE(PG8_SB(1, 1), b3 + hstep, voffB); PG8_STAGEA(PG8_SA(1, 0), a3, voffA);
;             PG8_WAIT_V(8); PG8_WAIT_L(0); PG8_BAR; PG8_MMA(1, 0, At, B0); PG8_MMA(1, 1, At, B1); PG8_BAR; PG8_SCHED;
	s_add_i32 s46, s70, s55
	v_lshl_add_u64 v[140:141], v[140:141], 0, s[8:9]
	s_mov_b32 m0, s46
	ds_read_b128 v[200:203], v145 offset:49152
	ds_read_b128 v[208:211], v145 offset:50176
	ds_read_b128 v[212:215], v145 offset:51200
	ds_read_b128 v[216:219], v145 offset:52224
	ds_read_b128 v[220:223], v145 offset:53248
	ds_read_b128 v[224:227], v145 offset:54272
	ds_read_b128 v[228:231], v145 offset:55296
	ds_read_b128 v[232:235], v145 offset:56320
	global_load_lds_dwordx4 v[140:141], off
	s_add_i32 m0, s46, 0x2000
	s_add_u32 s46, s50, 0xb0080
	v_lshl_add_u64 v[140:141], v[190:191], 0, s[8:9]
	s_addc_u32 s47, s51, 0
	s_add_i32 s50, s71, s55
	global_load_lds_dwordx4 v[140:141], off
	v_lshl_add_u64 v[140:141], s[46:47], 0, v[0:1]
	s_mov_b32 m0, s50
	s_nop 0
	global_load_lds_dwordx4 v[140:141], off
	v_lshl_add_u64 v[140:141], s[46:47], 0, v[130:131]
	s_add_i32 m0, s50, 0x2000
	s_nop 0
	global_load_lds_dwordx4 v[140:141], off
	v_lshl_add_u64 v[140:141], v[236:237], 0, s[8:9]
	s_mov_b32 m0, s60
	s_nop 0
	global_load_lds_dwordx4 v[140:141], off
	v_lshl_add_u64 v[140:141], v[238:239], 0, s[8:9]
	s_mov_b32 m0, s61
	s_nop 0
	global_load_lds_dwordx4 v[140:141], off
	s_waitcnt vmcnt(8)
	s_waitcnt lgkmcnt(0)
	s_barrier
	s_setprio 1
	s_waitcnt lgkmcnt(0)
	v_mfma_f32_16x16x32_bf16 v[62:65], v[146:149], v[200:203], v[62:65]
	v_mfma_f32_16x16x32_bf16 v[58:61], v[154:157], v[200:203], v[58:61]
	v_mfma_f32_16x16x32_bf16 v[50:53], v[146:149], v[212:215], v[50:53]
	v_mfma_f32_16x16x32_bf16 v[42:45], v[154:157], v[212:215], v[42:45]
	v_mfma_f32_16x16x32_bf16 v[34:37], v[146:149], v[220:223], v[34:37]
	v_mfma_f32_16x16x32_bf16 v[26:29], v[154:157], v[220:223], v[26:29]
	v_mfma_f32_16x16x32_bf16 v[18:21], v[146:149], v[228:231], v[18:21]
	v_mfma_f32_16x16x32_bf16 v[10:13], v[154:157], v[228:231], v[10:13]
	v_mfma_f32_16x16x32_bf16 v[62:65], v[150:153], v[208:211], v[62:65]
	v_mfma_f32_16x16x32_bf16 v[58:61], v[158:161], v[208:211], v[58:61]
	v_mfma_f32_16x16x32_bf16 v[50:53], v[150:153], v[216:219], v[50:53]
	v_mfma_f32_16x16x32_bf16 v[42:45], v[158:161], v[216:219], v[42:45]
	v_mfma_f32_16x16x32_bf16 v[34:37], v[150:153], v[224:227], v[34:37]
	v_mfma_f32_16x16x32_bf16 v[26:29], v[158:161], v[224:227], v[26:29]
	v_mfma_f32_16x16x32_bf16 v[18:21], v[150:153], v[232:235], v[18:21]
	v_mfma_f32_16x16x32_bf16 v[10:13], v[158:161], v[232:235], v[10:13]
	v_mfma_f32_16x16x32_bf16 v[54:57], v[174:177], v[200:203], v[54:57]
	v_mfma_f32_16x16x32_bf16 v[46:49], v[182:185], v[200:203], v[46:49]
	v_mfma_f32_16x16x32_bf16 v[38:41], v[174:177], v[212:215], v[38:41]
	v_mfma_f32_16x16x32_bf16 v[30:33], v[182:185], v[212:215], v[30:33]
	v_mfma_f32_16x16x32_bf16 v[22:25], v[174:177], v[220:223], v[22:25]
	v_mfma_f32_16x16x32_bf16 v[14:17], v[182:185], v[220:223], v[14:17]
	v_mfma_f32_16x16x32_bf16 v[6:9], v[174:177], v[228:231], v[6:9]
	v_mfma_f32_16x16x32_bf16 v[2:5], v[182:185], v[228:231], v[2:5]
	v_mfma_f32_16x16x32_bf16 v[54:57], v[178:181], v[208:211], v[54:57]
	v_mfma_f32_16x16x32_bf16 v[46:49], v[186:189], v[208:211], v[46:49]
	v_mfma_f32_16x16x32_bf16 v[38:41], v[178:181], v[216:219], v[38:41]
	v_mfma_f32_16x16x32_bf16 v[30:33], v[186:189], v[216:219], v[30:33]
	v_mfma_f32_16x16x32_bf16 v[22:25], v[178:181], v[224:227], v[22:25]
	v_mfma_f32_16x16x32_bf16 v[14:17], v[186:189], v[224:227], v[14:17]
	v_mfma_f32_16x16x32_bf16 v[6:9], v[178:181], v[232:235], v[6:9]
	v_mfma_f32_16x16x32_bf16 v[2:5], v[186:189], v[232:235], v[2:5]
	s_setprio 0
	s_barrier
	s_add_i32 s73, s73, 2
	s_add_u32 s16, s16, 0x100
	s_addc_u32 s17, s17, 0
	s_cmp_gt_u32 s73, 41
	s_mov_b64 s[46:47], s[48:49]
.LBB0_656:
	s_add_u32 s48, s46, 0x100
	s_addc_u32 s49, s47, 0
	s_add_i32 s70, 0, 0x10000
	s_cmp_eq_u32 s73, 40
	s_cselect_b32 s53, s1, s49
	s_cselect_b32 s52, s0, s48
	v_add_u32_e32 v140, s70, v143
	s_cselect_b32 s51, s45, s17
	s_cselect_b32 s50, s44, s16
	s_add_i32 s71, 0, 0x14000
	ds_read_b128 v[146:149], v140
	ds_read_b128 v[150:153], v140 offset:1024
	ds_read_b128 v[154:157], v140 offset:2048
	ds_read_b128 v[158:161], v140 offset:3072
	v_add_u32_e32 v140, s71, v143
	ds_read_b128 v[174:177], v140
	ds_read_b128 v[178:181], v140 offset:1024
	ds_read_b128 v[182:185], v140 offset:2048
	ds_read_b128 v[186:189], v140 offset:3072
	v_lshl_add_u64 v[140:141], s[46:47], 0, v[136:137]
	s_add_i32 m0, s56, 0xc000
	ds_read_b128 v[200:203], v145
	ds_read_b128 v[208:211], v145 offset:1024
	ds_read_b128 v[212:215], v145 offset:2048
	ds_read_b128 v[216:219], v145 offset:3072
	ds_read_b128 v[220:223], v145 offset:4096
	ds_read_b128 v[224:227], v145 offset:5120
	ds_read_b128 v[228:231], v145 offset:6144
	ds_read_b128 v[232:235], v145 offset:7168
	global_load_lds_dwordx4 v[140:141], off
	v_lshl_add_u64 v[140:141], s[46:47], 0, v[138:139]
	s_add_i32 m0, s56, 0xe000
	s_nop 0
	global_load_lds_dwordx4 v[140:141], off
	s_waitcnt vmcnt(8)
	s_waitcnt lgkmcnt(0)
	s_barrier
; #define PG8_STAGE(bufoff, gbase, voff) do { _Pragma("unroll") for (int _i = 0; _i < 2; ++_i) \
;         __builtin_amdgcn_global_load_lds((const unsigned*)((const char*)(gbase) + (voff)[_i]), (PG8_LAS unsigned*)(lds + (bufoff) + ldsw + _i * 8192), 16, 0, 0); } while (0)
; #define PG8_STAGEA(bufoff, gbase, voff) do { _Pragma("unroll") for (int _i = 0; _i < 2; ++_i) \
;         __builtin_amdgcn_global_load_lds((const unsigned*)((const char*)(gbase) + (voff)[_i]), (PG8_LAS unsigned*)(lds + (bufoff) + ldsw + _i * 8192), 16, 0, A_AUX); } while (0)
; #define PG8_LDA(dst, b, h) do { _Pragma("unroll") for (int m = 0; m < 4; ++m) _Pragma("unroll") for (int k = 0; k < 2; ++k) dst[m][k] = *(const PG8_LAS bf16x8*)(lds + PG8_SA(b, h) + aoff + m * 2048 + k * 1024); } while (0)
; #define PG8_MMA(ai, bj, At, Bt) do { __builtin_amdgcn_s_setprio(1); _Pragma("unroll") for (int m = 0; m < 4; ++m) _Pragma("unroll") for (int n = 0; n < 2; ++n) _Pragma("unroll") for (int k = 0; k < 2; ++k) \
;         acc[ai][bj][m][n] = __builtin_amdgcn_mfma_f32_16x16x32_bf16(Bt[n][k], At[m][k], acc[ai][bj][m][n], 0, 0, 0); __builtin_amdgcn_s_setprio(0); } while (0)
; #define PG8_WAIT_V(n) asm volatile("s_waitcnt vmcnt(" #n ")" ::: "memory")
; #define PG8_WAIT_L(n) asm volatile("s_waitcnt lgkmcnt(" #n ")" ::: "memory")
; #define PG8_BAR __builtin_amdgcn_s_barrier()
; #define PG8_SCHED __builtin_amdgcn_sched_barrier(0)
;     ...
;             PG8_WAIT_V(8); PG8_WAIT_L(0); PG8_BAR; PG8_MMA(0, 0, At, B0); PG8_MMA(0, 1, At, B1); PG8_BAR; PG8_SCHED;
;             PG8_LDA(At, 0, 1); PG8_STAGE(PG8_SB(0, 0), b2, voffB); PG8_STAGE(PG8_SB(0, 1), b2 + hstep, voffB); PG8_STAGEA(PG8_SA(0, 0), a2, voffA);
;             PG8_WAIT_V(8); PG8_WAIT_L(0); PG8_BAR; PG8_MMA(1, 0, At, B0); PG8_MMA(1, 1, At, B1); PG8_BAR; PG8_SCHED;
	s_setprio 1
	s_waitcnt lgkmcnt(0)
	v_mfma_f32_16x16x32_bf16 v[126:129], v[146:149], v[200:203], v[126:129]
	v_mfma_f32_16x16x32_bf16 v[122:125], v[154:157], v[200:203], v[122:125]
	v_mfma_f32_16x16x32_bf16 v[114:117], v[146:149], v[212:215], v[114:117]
	v_mfma_f32_16x16x32_bf16 v[106:109], v[154:157], v[212:215], v[106:109]
	v_mfma_f32_16x16x32_bf16 v[98:101], v[146:149], v[220:223], v[98:101]
	v_mfma_f32_16x16x32_bf16 v[90:93], v[154:157], v[220:223], v[90:93]
	v_mfma_f32_16x16x32_bf16 v[82:85], v[146:149], v[228:231], v[82:85]
	v_mfma_f32_16x16x32_bf16 v[74:77], v[154:157], v[228:231], v[74:77]
	v_mfma_f32_16x16x32_bf16 v[126:129], v[150:153], v[208:211], v[126:129]
	v_mfma_f32_16x16x32_bf16 v[122:125], v[158:161], v[208:211], v[122:125]
	v_mfma_f32_16x16x32_bf16 v[114:117], v[150:153], v[216:219], v[114:117]
	v_mfma_f32_16x16x32_bf16 v[106:109], v[158:161], v[216:219], v[106:109]
	v_mfma_f32_16x16x32_bf16 v[98:101], v[150:153], v[224:227], v[98:101]
	v_mfma_f32_16x16x32_bf16 v[90:93], v[158:161], v[224:227], v[90:93]
	v_mfma_f32_16x16x32_bf16 v[82:85], v[150:153], v[232:235], v[82:85]
	v_mfma_f32_16x16x32_bf16 v[74:77], v[158:161], v[232:235], v[74:77]
	v_mfma_f32_16x16x32_bf16 v[118:121], v[174:177], v[200:203], v[118:121]
	v_mfma_f32_16x16x32_bf16 v[110:113], v[182:185], v[200:203], v[110:113]
	v_mfma_f32_16x16x32_bf16 v[102:105], v[174:177], v[212:215], v[102:105]
	v_mfma_f32_16x16x32_bf16 v[94:97], v[182:185], v[212:215], v[94:97]
	v_mfma_f32_16x16x32_bf16 v[86:89], v[174:177], v[220:223], v[86:89]
	v_mfma_f32_16x16x32_bf16 v[78:81], v[182:185], v[220:223], v[78:81]
	v_mfma_f32_16x16x32_bf16 v[70:73], v[174:177], v[228:231], v[70:73]
	v_mfma_f32_16x16x32_bf16 v[66:69], v[182:185], v[228:231], v[66:69]
	v_mfma_f32_16x16x32_bf16 v[118:121], v[178:181], v[208:211], v[118:121]
	v_mfma_f32_16x16x32_bf16 v[110:113], v[186:189], v[208:211], v[110:113]
	v_mfma_f32_16x16x32_bf16 v[102:105], v[178:181], v[216:219], v[102:105]
	v_mfma_f32_16x16x32_bf16 v[94:97], v[186:189], v[216:219], v[94:97]
	v_mfma_f32_16x16x32_bf16 v[86:89], v[178:181], v[224:227], v[86:89]
	v_mfma_f32_16x16x32_bf16 v[78:81], v[186:189], v[224:227], v[78:81]
	v_mfma_f32_16x16x32_bf16 v[70:73], v[178:181], v[232:235], v[70:73]
	v_mfma_f32_16x16x32_bf16 v[66:69], v[186:189], v[232:235], v[66:69]
	s_setprio 0
	s_barrier
	s_add_i32 s46, s70, s55
	v_lshl_add_u64 v[140:141], s[50:51], 0, v[0:1]
	s_mov_b32 m0, s46
	ds_read_b128 v[200:203], v145 offset:16384
	ds_read_b128 v[208:211], v145 offset:17408
	ds_read_b128 v[212:215], v145 offset:18432
	ds_read_b128 v[216:219], v145 offset:19456
	ds_read_b128 v[220:223], v145 offset:20480
	ds_read_b128 v[224:227], v145 offset:21504
	ds_read_b128 v[228:231], v145 offset:22528
	ds_read_b128 v[232:235], v145 offset:23552
	global_load_lds_dwordx4 v[140:141], off
	s_add_i32 m0, s46, 0x2000
	s_add_u32 s46, s50, 0xb0000
	v_lshl_add_u64 v[190:191], s[50:51], 0, v[130:131]
	s_addc_u32 s47, s51, 0
	s_add_i32 s70, s71, s55
	global_load_lds_dwordx4 v[190:191], off
	v_lshl_add_u64 v[236:237], s[46:47], 0, v[0:1]
	s_mov_b32 m0, s70
	v_lshl_add_u64 v[238:239], s[52:53], 0, v[132:133]
	global_load_lds_dwordx4 v[236:237], off
	v_lshl_add_u64 v[236:237], s[46:47], 0, v[130:131]
	s_add_i32 m0, s70, 0x2000
	s_nop 0
	global_load_lds_dwordx4 v[236:237], off
	v_lshl_add_u64 v[236:237], s[52:53], 0, v[134:135]
	s_mov_b32 m0, s56
	s_nop 0
	global_load_lds_dwordx4 v[236:237], off
	s_mov_b32 m0, s57
	s_nop 0
	global_load_lds_dwordx4 v[238:239], off
	s_waitcnt vmcnt(8)
	s_waitcnt lgkmcnt(0)
	s_barrier
	s_setprio 1
	s_waitcnt lgkmcnt(0)
	v_mfma_f32_16x16x32_bf16 v[62:65], v[146:149], v[200:203], v[62:65]
	v_mfma_f32_16x16x32_bf16 v[58:61], v[154:157], v[200:203], v[58:61]
	v_mfma_f32_16x16x32_bf16 v[50:53], v[146:149], v[212:215], v[50:53]
	v_mfma_f32_16x16x32_bf16 v[42:45], v[154:157], v[212:215], v[42:45]
	v_mfma_f32_16x16x32_bf16 v[34:37], v[146:149], v[220:223], v[34:37]
	v_mfma_f32_16x16x32_bf16 v[26:29], v[154:157], v[220:223], v[26:29]
	v_mfma_f32_16x16x32_bf16 v[18:21], v[146:149], v[228:231], v[18:21]
	v_mfma_f32_16x16x32_bf16 v[10:13], v[154:157], v[228:231], v[10:13]
	v_mfma_f32_16x16x32_bf16 v[62:65], v[150:153], v[208:211], v[62:65]
	v_mfma_f32_16x16x32_bf16 v[58:61], v[158:161], v[208:211], v[58:61]
	v_mfma_f32_16x16x32_bf16 v[50:53], v[150:153], v[216:219], v[50:53]
	v_mfma_f32_16x16x32_bf16 v[42:45], v[158:161], v[216:219], v[42:45]
	v_mfma_f32_16x16x32_bf16 v[34:37], v[150:153], v[224:227], v[34:37]
	v_mfma_f32_16x16x32_bf16 v[26:29], v[158:161], v[224:227], v[26:29]
	v_mfma_f32_16x16x32_bf16 v[18:21], v[150:153], v[232:235], v[18:21]
	v_mfma_f32_16x16x32_bf16 v[10:13], v[158:161], v[232:235], v[10:13]
	v_mfma_f32_16x16x32_bf16 v[54:57], v[174:177], v[200:203], v[54:57]
	v_mfma_f32_16x16x32_bf16 v[46:49], v[182:185], v[200:203], v[46:49]
	v_mfma_f32_16x16x32_bf16 v[38:41], v[174:177], v[212:215], v[38:41]
	v_mfma_f32_16x16x32_bf16 v[30:33], v[182:185], v[212:215], v[30:33]
	v_mfma_f32_16x16x32_bf16 v[22:25], v[174:177], v[220:223], v[22:25]
	v_mfma_f32_16x16x32_bf16 v[14:17], v[182:185], v[220:223], v[14:17]
	v_mfma_f32_16x16x32_bf16 v[6:9], v[174:177], v[228:231], v[6:9]
	v_mfma_f32_16x16x32_bf16 v[2:5], v[182:185], v[228:231], v[2:5]
	v_mfma_f32_16x16x32_bf16 v[54:57], v[178:181], v[208:211], v[54:57]
	v_mfma_f32_16x16x32_bf16 v[46:49], v[186:189], v[208:211], v[46:49]
	v_mfma_f32_16x16x32_bf16 v[38:41], v[178:181], v[216:219], v[38:41]
	v_mfma_f32_16x16x32_bf16 v[30:33], v[186:189], v[216:219], v[30:33]
	v_mfma_f32_16x16x32_bf16 v[22:25], v[178:181], v[224:227], v[22:25]
	v_mfma_f32_16x16x32_bf16 v[14:17], v[186:189], v[224:227], v[14:17]
	v_mfma_f32_16x16x32_bf16 v[6:9], v[178:181], v[232:235], v[6:9]
	v_mfma_f32_16x16x32_bf16 v[2:5], v[186:189], v[232:235], v[2:5]
	s_setprio 0
	s_barrier
; #define PG8_STAGEA(bufoff, gbase, voff) do { _Pragma("unroll") for (int _i = 0; _i < 2; ++_i) \
;         __builtin_amdgcn_global_load_lds((const unsigned*)((const char*)(gbase) + (voff)[_i]), (PG8_LAS unsigned*)(lds + (bufoff) + ldsw + _i * 8192), 16, 0, A_AUX); } while (0)
; #define PG8_LDA(dst, b, h) do { _Pragma("unroll") for (int m = 0; m < 4; ++m) _Pragma("unroll") for (int k = 0; k < 2; ++k) dst[m][k] = *(const PG8_LAS bf16x8*)(lds + PG8_SA(b, h) + aoff + m * 2048 + k * 1024); } while (0)
; #define PG8_LDB(dst, b, h) do { _Pragma("unroll") for (int n = 0; n < 2; ++n) _Pragma("unroll") for (int k = 0; k < 2; ++k) dst[n][k] = *(const PG8_LAS bf16x8*)(lds + PG8_SB(b, h) + boff + n * 2048 + k * 1024); } while (0)
; #define PG8_MMA(ai, bj, At, Bt) do { __builtin_amdgcn_s_setprio(1); _Pragma("unroll") for (int m = 0; m < 4; ++m) _Pragma("unroll") for (int n = 0; n < 2; ++n) _Pragma("unroll") for (int k = 0; k < 2; ++k) \
;         acc[ai][bj][m][n] = __builtin_amdgcn_mfma_f32_16x16x32_bf16(Bt[n][k], At[m][k], acc[ai][bj][m][n], 0, 0, 0); __builtin_amdgcn_s_setprio(0); } while (0)
; #define PG8_WAIT_V(n) asm volatile("s_waitcnt vmcnt(" #n ")" ::: "memory")
; #define PG8_WAIT_L(n) asm volatile("s_waitcnt lgkmcnt(" #n ")" ::: "memory")
; #define PG8_BAR __builtin_amdgcn_s_barrier()
; #define PG8_SCHED __builtin_amdgcn_sched_barrier(0)
;     ...
;             PG8_LDB(B0, 1, 0); PG8_LDB(B1, 1, 1); PG8_SCHED; PG8_LDA(At, 1, 0); PG8_STAGEA(PG8_SA(0, 1), a2 + hstep, voffA);
;             PG8_WAIT_V(8); PG8_WAIT_L(0); PG8_BAR; PG8_MMA(0, 0, At, B0); PG8_MMA(0, 1, At, B1); PG8_BAR; PG8_SCHED;
	s_add_i32 s70, 0, 0x18000
	s_add_i32 s71, 0, 0x1c000
	v_add_u32_e32 v158, s70, v143
	v_add_u32_e32 v186, s71, v143
	ds_read_b128 v[146:149], v158
	ds_read_b128 v[150:153], v158 offset:1024
	ds_read_b128 v[154:157], v158 offset:2048
	ds_read_b128 v[158:161], v158 offset:3072
	ds_read_b128 v[174:177], v186
	ds_read_b128 v[178:181], v186 offset:1024
	ds_read_b128 v[182:185], v186 offset:2048
	ds_read_b128 v[186:189], v186 offset:3072
	s_add_u32 s46, s52, 0xb0000
	s_addc_u32 s47, s53, 0
	s_mov_b32 m0, s58
	v_lshl_add_u64 v[240:241], s[46:47], 0, v[134:135]
	ds_read_b128 v[200:203], v145 offset:32768
	ds_read_b128 v[208:211], v145 offset:33792
	ds_read_b128 v[212:215], v145 offset:34816
	ds_read_b128 v[216:219], v145 offset:35840
	ds_read_b128 v[220:223], v145 offset:36864
	ds_read_b128 v[224:227], v145 offset:37888
	ds_read_b128 v[228:231], v145 offset:38912
	ds_read_b128 v[232:235], v145 offset:39936
	global_load_lds_dwordx4 v[240:241], off
	v_lshl_add_u64 v[240:241], s[46:47], 0, v[132:133]
	s_mov_b32 m0, s59
	s_nop 0
	global_load_lds_dwordx4 v[240:241], off
	s_waitcnt vmcnt(8)
	s_waitcnt lgkmcnt(0)
	s_barrier
	s_setprio 1
	s_waitcnt lgkmcnt(0)
	v_mfma_f32_16x16x32_bf16 v[126:129], v[146:149], v[200:203], v[126:129]
	v_mfma_f32_16x16x32_bf16 v[122:125], v[154:157], v[200:203], v[122:125]
	v_mfma_f32_16x16x32_bf16 v[114:117], v[146:149], v[212:215], v[114:117]
	v_mfma_f32_16x16x32_bf16 v[106:109], v[154:157], v[212:215], v[106:109]
	v_mfma_f32_16x16x32_bf16 v[98:101], v[146:149], v[220:223], v[98:101]
	v_mfma_f32_16x16x32_bf16 v[90:93], v[154:157], v[220:223], v[90:93]
	v_mfma_f32_16x16x32_bf16 v[82:85], v[146:149], v[228:231], v[82:85]
	v_mfma_f32_16x16x32_bf16 v[74:77], v[154:157], v[228:231], v[74:77]
	v_mfma_f32_16x16x32_bf16 v[126:129], v[150:153], v[208:211], v[126:129]
	v_mfma_f32_16x16x32_bf16 v[122:125], v[158:161], v[208:211], v[122:125]
	v_mfma_f32_16x16x32_bf16 v[114:117], v[150:153], v[216:219], v[114:117]
	v_mfma_f32_16x16x32_bf16 v[106:109], v[158:161], v[216:219], v[106:109]
	v_mfma_f32_16x16x32_bf16 v[98:101], v[150:153], v[224:227], v[98:101]
	v_mfma_f32_16x16x32_bf16 v[90:93], v[158:161], v[224:227], v[90:93]
	v_mfma_f32_16x16x32_bf16 v[82:85], v[150:153], v[232:235], v[82:85]
	v_mfma_f32_16x16x32_bf16 v[74:77], v[158:161], v[232:235], v[74:77]
	v_mfma_f32_16x16x32_bf16 v[118:121], v[174:177], v[200:203], v[118:121]
	v_mfma_f32_16x16x32_bf16 v[110:113], v[182:185], v[200:203], v[110:113]
	v_mfma_f32_16x16x32_bf16 v[102:105], v[174:177], v[212:215], v[102:105]
	v_mfma_f32_16x16x32_bf16 v[94:97], v[182:185], v[212:215], v[94:97]
	v_mfma_f32_16x16x32_bf16 v[86:89], v[174:177], v[220:223], v[86:89]
	v_mfma_f32_16x16x32_bf16 v[78:81], v[182:185], v[220:223], v[78:81]
	v_mfma_f32_16x16x32_bf16 v[70:73], v[174:177], v[228:231], v[70:73]
	v_mfma_f32_16x16x32_bf16 v[66:69], v[182:185], v[228:231], v[66:69]
	v_mfma_f32_16x16x32_bf16 v[118:121], v[178:181], v[208:211], v[118:121]
	v_mfma_f32_16x16x32_bf16 v[110:113], v[186:189], v[208:211], v[110:113]
	v_mfma_f32_16x16x32_bf16 v[102:105], v[178:181], v[216:219], v[102:105]
	v_mfma_f32_16x16x32_bf16 v[94:97], v[186:189], v[216:219], v[94:97]
	v_mfma_f32_16x16x32_bf16 v[86:89], v[178:181], v[224:227], v[86:89]
	v_mfma_f32_16x16x32_bf16 v[78:81], v[186:189], v[224:227], v[78:81]
	v_mfma_f32_16x16x32_bf16 v[70:73], v[178:181], v[232:235], v[70:73]
	v_mfma_f32_16x16x32_bf16 v[66:69], v[186:189], v[232:235], v[66:69]
	s_setprio 0
	s_barrier
; #define PG8_STAGE(bufoff, gbase, voff) do { _Pragma("unroll") for (int _i = 0; _i < 2; ++_i) \
;         __builtin_amdgcn_global_load_lds((const unsigned*)((const char*)(gbase) + (voff)[_i]), (PG8_LAS unsigned*)(lds + (bufoff) + ldsw + _i * 8192), 16, 0, 0); } while (0)
; #define PG8_STAGEA(bufoff, gbase, voff) do { _Pragma("unroll") for (int _i = 0; _i < 2; ++_i) \
;         __builtin_amdgcn_global_load_lds((const unsigned*)((const char*)(gbase) + (voff)[_i]), (PG8_LAS unsigned*)(lds + (bufoff) + ldsw + _i * 8192), 16, 0, A_AUX); } while (0)
; #define PG8_LDA(dst, b, h) do { _Pragma("unroll") for (int m = 0; m < 4; ++m) _Pragma("unroll") for (int k = 0; k < 2; ++k) dst[m][k] = *(const PG8_LAS bf16x8*)(lds + PG8_SA(b, h) + aoff + m * 2048 + k * 1024); } while (0)
; #define PG8_MMA(ai, bj, At, Bt) do { __builtin_amdgcn_s_setprio(1); _Pragma("unroll") for (int m = 0; m < 4; ++m) _Pragma("unroll") for (int n = 0; n < 2; ++n) _Pragma("unroll") for (int k = 0; k < 2; ++k) \
;         acc[ai][bj][m][n] = __builtin_amdgcn_mfma_f32_16x16x32_bf16(Bt[n][k], At[m][k], acc[ai][bj][m][n], 0, 0, 0); __builtin_amdgcn_s_setprio(0); } while (0)
; #define PG8_WAIT_V(n) asm volatile("s_waitcnt vmcnt(" #n ")" ::: "memory")
; #define PG8_WAIT_L(n) asm volatile("s_waitcnt lgkmcnt(" #n ")" ::: "memory")
; #define PG8_BAR __builtin_amdgcn_s_barrier()
; #define PG8_SCHED __builtin_amdgcn_sched_barrier(0)
;     ...
;         for (int t = 0; t < nt; t += 2) {
;             const bool last = (t == nt - 2);
;             const char* a1 = cA + (size_t)(t + 1) * kstep;
;             const char* a2 = last ? nA : cA + (size_t)(t + 2) * kstep; const char* b2 = last ? nB : cB + (size_t)(t + 2) * kstep;
;     ...
;             PG8_LDA(At, 1, 1); PG8_STAGE(PG8_SB(1, 0), b3, voffB); PG8_STAGE(PG8_SB(1, 1), b3 + hstep, voffB); PG8_STAGEA(PG8_SA(1, 0), a3, voffA);
;             PG8_WAIT_V(8); PG8_WAIT_L(0); PG8_BAR; PG8_MMA(1, 0, At, B0); PG8_MMA(1, 1, At, B1); PG8_BAR; PG8_SCHED;
	s_add_i32 s46, s70, s55
	v_lshl_add_u64 v[140:141], v[140:141], 0, s[8:9]
	s_mov_b32 m0, s46
	ds_read_b128 v[200:203], v145 offset:49152
	ds_read_b128 v[208:211], v145 offset:50176
	ds_read_b128 v[212:215], v145 offset:51200
	ds_read_b128 v[216:219], v145 offset:52224
	ds_read_b128 v[220:223], v145 offset:53248
	ds_read_b128 v[224:227], v145 offset:54272
	ds_read_b128 v[228:231], v145 offset:55296
	ds_read_b128 v[232:235], v145 offset:56320
	global_load_lds_dwordx4 v[140:141], off
	s_add_i32 m0, s46, 0x2000
	s_add_u32 s46, s50, 0xb0080
	v_lshl_add_u64 v[140:141], v[190:191], 0, s[8:9]
	s_addc_u32 s47, s51, 0
	s_add_i32 s50, s71, s55
	global_load_lds_dwordx4 v[140:141], off
	v_lshl_add_u64 v[140:141], s[46:47], 0, v[0:1]
	s_mov_b32 m0, s50
	s_nop 0
	global_load_lds_dwordx4 v[140:141], off
	v_lshl_add_u64 v[140:141], s[46:47], 0, v[130:131]
	s_add_i32 m0, s50, 0x2000
	s_nop 0
	global_load_lds_dwordx4 v[140:141], off
	v_lshl_add_u64 v[140:141], v[236:237], 0, s[8:9]
	s_mov_b32 m0, s60
	s_nop 0
	global_load_lds_dwordx4 v[140:141], off
	v_lshl_add_u64 v[140:141], v[238:239], 0, s[8:9]
	s_mov_b32 m0, s61
	s_nop 0
	global_load_lds_dwordx4 v[140:141], off
	s_waitcnt vmcnt(8)
	s_waitcnt lgkmcnt(0)
	s_barrier
	s_setprio 1
	s_waitcnt lgkmcnt(0)
	v_mfma_f32_16x16x32_bf16 v[62:65], v[146:149], v[200:203], v[62:65]
	v_mfma_f32_16x16x32_bf16 v[58:61], v[154:157], v[200:203], v[58:61]
	v_mfma_f32_16x16x32_bf16 v[50:53], v[146:149], v[212:215], v[50:53]
	v_mfma_f32_16x16x32_bf16 v[42:45], v[154:157], v[212:215], v[42:45]
	v_mfma_f32_16x16x32_bf16 v[34:37], v[146:149], v[220:223], v[34:37]
	v_mfma_f32_16x16x32_bf16 v[26:29], v[154:157], v[220:223], v[26:29]
	v_mfma_f32_16x16x32_bf16 v[18:21], v[146:149], v[228:231], v[18:21]
	v_mfma_f32_16x16x32_bf16 v[10:13], v[154:157], v[228:231], v[10:13]
	v_mfma_f32_16x16x32_bf16 v[62:65], v[150:153], v[208:211], v[62:65]
	v_mfma_f32_16x16x32_bf16 v[58:61], v[158:161], v[208:211], v[58:61]
	v_mfma_f32_16x16x32_bf16 v[50:53], v[150:153], v[216:219], v[50:53]
	v_mfma_f32_16x16x32_bf16 v[42:45], v[158:161], v[216:219], v[42:45]
	v_mfma_f32_16x16x32_bf16 v[34:37], v[150:153], v[224:227], v[34:37]
	v_mfma_f32_16x16x32_bf16 v[26:29], v[158:161], v[224:227], v[26:29]
	v_mfma_f32_16x16x32_bf16 v[18:21], v[150:153], v[232:235], v[18:21]
	v_mfma_f32_16x16x32_bf16 v[10:13], v[158:161], v[232:235], v[10:13]
	v_mfma_f32_16x16x32_bf16 v[54:57], v[174:177], v[200:203], v[54:57]
	v_mfma_f32_16x16x32_bf16 v[46:49], v[182:185], v[200:203], v[46:49]
	v_mfma_f32_16x16x32_bf16 v[38:41], v[174:177], v[212:215], v[38:41]
	v_mfma_f32_16x16x32_bf16 v[30:33], v[182:185], v[212:215], v[30:33]
	v_mfma_f32_16x16x32_bf16 v[22:25], v[174:177], v[220:223], v[22:25]
	v_mfma_f32_16x16x32_bf16 v[14:17], v[182:185], v[220:223], v[14:17]
	v_mfma_f32_16x16x32_bf16 v[6:9], v[174:177], v[228:231], v[6:9]
	v_mfma_f32_16x16x32_bf16 v[2:5], v[182:185], v[228:231], v[2:5]
	v_mfma_f32_16x16x32_bf16 v[54:57], v[178:181], v[208:211], v[54:57]
	v_mfma_f32_16x16x32_bf16 v[46:49], v[186:189], v[208:211], v[46:49]
	v_mfma_f32_16x16x32_bf16 v[38:41], v[178:181], v[216:219], v[38:41]
	v_mfma_f32_16x16x32_bf16 v[30:33], v[186:189], v[216:219], v[30:33]
	v_mfma_f32_16x16x32_bf16 v[22:25], v[178:181], v[224:227], v[22:25]
	v_mfma_f32_16x16x32_bf16 v[14:17], v[186:189], v[224:227], v[14:17]
	v_mfma_f32_16x16x32_bf16 v[6:9], v[178:181], v[232:235], v[6:9]
	v_mfma_f32_16x16x32_bf16 v[2:5], v[186:189], v[232:235], v[2:5]
	s_setprio 0
	s_barrier
	s_add_i32 s73, s73, 2
	s_add_u32 s16, s16, 0x100
	s_addc_u32 s17, s17, 0
	s_cmp_gt_u32 s73, 41
	s_mov_b64 s[46:47], s[48:49]
	s_cbranch_scc0 .LBB0_656
	s_and_b64 vcc, exec, s[42:43]
	s_cbranch_vccz .LBB0_659
	s_barrier
